# on top of v11: every 16-MFMA block of the K-loops and peeled iterations starts 8-byte aligned (one s_nop 0 in the preceding load segment where needed, 14 pads)
# baseline (speedup 1.0000x reference)
; #define PG8_STAGE(bufoff, gbase, voff) do { _Pragma("unroll") for (int _i = 0; _i < 2; ++_i) \
;         __builtin_amdgcn_global_load_lds((const unsigned*)((const char*)(gbase) + (voff)[_i]), (PG8_LAS unsigned*)(lds + (bufoff) + ldsw + _i * 8192), 16, 0, 0); } while (0)
; #define PG8_LDA(dst, b, h) do { _Pragma("unroll") for (int m = 0; m < 4; ++m) _Pragma("unroll") for (int k = 0; k < 2; ++k) dst[m][k] = *(const PG8_LAS bf16x8*)(lds + PG8_SA(b, h) + aoff + m * 2048 + k * 1024); } while (0)
; template <class Epi, class Sched, bool ALIGN_EPI = false, bool SP2 = false>
; __device__ __forceinline__ void gemm_phase(PG8_LAS unsigned char* lds, const Gemm g, const Sched& S, const Epi& E, const int wave_id) {
;     ...
;         const char* nA = has_next ? (const char*)g.A + (size_t)nxt.lm * tstep : cA; const char* nB = has_next ? (const char*)g.Bt + (size_t)nxt.ln * tstep : cB;
; #pragma unroll 1
;         for (int t = 0; t < nt; t += 2) {
;             const bool last = (t == nt - 2);
;             const char* a1 = cA + (size_t)(t + 1) * kstep;
;             const char* a2 = last ? nA : cA + (size_t)(t + 2) * kstep; const char* b2 = last ? nB : cB + (size_t)(t + 2) * kstep;
;             const char* a3 = a2 + kstep; const char* b3 = b2 + kstep;
;             if (last && has_next) S.a_ready(nxt);
;             if constexpr (SP2) {
;             PG8_LDB(B0, 0, 0); PG8_LDB(B1, 0, 1); PG8_SCHED; PG8_LDA(At, 0, 0); PG8_STAGE(PG8_SA(1, 1), a1 + hstep, voffA);
;             PG8_WAIT_V(8); PG8_WAIT_L(0); PG8_BAR; PG8_MMA(0, 0, At, B0); PG8_MMA(0, 1, At, B1); PG8_BAR; PG8_SCHED;
;             PG8_LDA(At, 0, 1); PG8_STAGE(PG8_SB(0, 0), b2, voffB); PG8_STAGE(PG8_SB(0, 1), b2 + hstep, voffB); PG8_STAGE(PG8_SA(0, 0), a2, voffA);
;             PG8_WAIT_V(8); PG8_WAIT_L(0); PG8_BAR; PG8_MMA(1, 0, At, B0); PG8_MMA(1, 1, At, B1); PG8_BAR; PG8_SCHED;
;             PG8_LDB(B0, 1, 0); PG8_LDB(B1, 1, 1); PG8_SCHED; PG8_LDA(At, 1, 0); PG8_STAGE(PG8_SA(0, 1), a2 + hstep, voffA);
;             PG8_WAIT_V(8); PG8_WAIT_L(0); PG8_BAR; PG8_MMA(0, 0, At, B0); PG8_MMA(0, 1, At, B1); PG8_BAR; PG8_SCHED;
;             PG8_LDA(At, 1, 1); PG8_STAGE(PG8_SB(1, 0), b3, voffB); PG8_STAGE(PG8_SB(1, 1), b3 + hstep, voffB); PG8_STAGE(PG8_SA(1, 0), a3, voffA);
;             PG8_WAIT_V(8); PG8_WAIT_L(0); PG8_BAR; PG8_MMA(1, 0, At, B0); PG8_MMA(1, 1, At, B1); PG8_BAR; PG8_SCHED;
.LBB0_173:
	s_ashr_i32 s15, s14, 31
	s_lshl_b64 s[16:17], s[14:15], 20
	s_add_u32 s16, s49, s16
	s_addc_u32 s17, s52, s17
	s_and_b64 s[18:19], s[38:39], exec
	s_cselect_b32 s15, s17, s21
	s_cselect_b32 s41, s16, s20
	s_ashr_i32 s13, s12, 31
	s_lshl_b64 s[18:19], s[12:13], 20
	s_add_u32 s18, s47, s18
	s_addc_u32 s19, s48, s19
	s_and_b64 s[44:45], s[38:39], exec
	s_cselect_b32 s13, s19, s43
	s_cselect_b32 s72, s18, s42
	s_add_u32 s20, s20, 0x80080
	s_addc_u32 s21, s21, 0
	s_add_u32 s73, s42, 0x100
	s_addc_u32 s74, s43, 0
	s_mov_b32 s75, -2
	v_add_u32_e32 v230, 0x10000, v171
	s_add_u32 s42, s20, 0xfff80080
	s_addc_u32 s43, s21, -1
	s_add_i32 s76, 0, 0x10000
	s_cmp_eq_u32 s75, 28
	s_cselect_b32 s45, s15, s43
	s_cselect_b32 s44, s41, s42
	s_cselect_b32 s43, s13, s74
	s_cselect_b32 s42, s72, s73
	s_add_i32 s79, 0, 0x14000
	s_add_i32 m0, s56, 0xc000
	s_nop 0
	global_load_lds_dwordx4 v138, s[20:21]
	ds_read_b128 v[142:145], v230
	ds_read_b128 v[146:149], v230 offset:1024
	ds_read_b128 v[150:153], v230 offset:2048
	ds_read_b128 v[154:157], v230 offset:3072
	ds_read_b128 v[158:161], v230 offset:16384
	ds_read_b128 v[162:165], v230 offset:17408
	ds_read_b128 v[166:169], v230 offset:18432
	ds_read_b128 v[178:181], v230 offset:19456
	s_add_i32 m0, s56, 0xe000
	s_nop 0
	global_load_lds_dwordx4 v140, s[20:21]
	ds_read_b128 v[182:185], v175
	ds_read_b128 v[186:189], v175 offset:1024
	ds_read_b128 v[190:193], v175 offset:2048
	ds_read_b128 v[206:209], v175 offset:3072
	ds_read_b128 v[210:213], v175 offset:4096
	ds_read_b128 v[214:217], v175 offset:5120
	ds_read_b128 v[226:229], v175 offset:6144
	ds_read_b128 v[234:237], v175 offset:7168
	s_waitcnt vmcnt(8)
	s_waitcnt lgkmcnt(0)
	s_barrier
	s_setprio 1
	s_waitcnt lgkmcnt(0)
	v_mfma_f32_16x16x32_bf16 v[126:129], v[142:145], v[182:185], 0
	v_mfma_f32_16x16x32_bf16 v[118:121], v[150:153], v[182:185], 0
	v_mfma_f32_16x16x32_bf16 v[110:113], v[142:145], v[190:193], 0
	v_mfma_f32_16x16x32_bf16 v[102:105], v[150:153], v[190:193], 0
	v_mfma_f32_16x16x32_bf16 v[94:97], v[142:145], v[210:213], 0
	v_mfma_f32_16x16x32_bf16 v[86:89], v[150:153], v[210:213], 0
	v_mfma_f32_16x16x32_bf16 v[78:81], v[142:145], v[226:229], 0
	v_mfma_f32_16x16x32_bf16 v[70:73], v[150:153], v[226:229], 0
	v_mfma_f32_16x16x32_bf16 v[126:129], v[146:149], v[186:189], v[126:129]
	v_mfma_f32_16x16x32_bf16 v[118:121], v[154:157], v[186:189], v[118:121]
	v_mfma_f32_16x16x32_bf16 v[110:113], v[146:149], v[206:209], v[110:113]
	v_mfma_f32_16x16x32_bf16 v[102:105], v[154:157], v[206:209], v[102:105]
	v_mfma_f32_16x16x32_bf16 v[94:97], v[146:149], v[214:217], v[94:97]
	v_mfma_f32_16x16x32_bf16 v[86:89], v[154:157], v[214:217], v[86:89]
	v_mfma_f32_16x16x32_bf16 v[78:81], v[146:149], v[234:237], v[78:81]
	v_mfma_f32_16x16x32_bf16 v[70:73], v[154:157], v[234:237], v[70:73]
	s_setprio 0
	s_setprio 1
	v_mfma_f32_16x16x32_bf16 v[122:125], v[158:161], v[182:185], 0
	v_mfma_f32_16x16x32_bf16 v[114:117], v[166:169], v[182:185], 0
	v_mfma_f32_16x16x32_bf16 v[106:109], v[158:161], v[190:193], 0
	v_mfma_f32_16x16x32_bf16 v[98:101], v[166:169], v[190:193], 0
	v_mfma_f32_16x16x32_bf16 v[90:93], v[158:161], v[210:213], 0
	v_mfma_f32_16x16x32_bf16 v[82:85], v[166:169], v[210:213], 0
	v_mfma_f32_16x16x32_bf16 v[74:77], v[158:161], v[226:229], 0
	v_mfma_f32_16x16x32_bf16 v[66:69], v[166:169], v[226:229], 0
	v_mfma_f32_16x16x32_bf16 v[122:125], v[162:165], v[186:189], v[122:125]
	v_mfma_f32_16x16x32_bf16 v[114:117], v[178:181], v[186:189], v[114:117]
	v_mfma_f32_16x16x32_bf16 v[106:109], v[162:165], v[206:209], v[106:109]
	v_mfma_f32_16x16x32_bf16 v[98:101], v[178:181], v[206:209], v[98:101]
	v_mfma_f32_16x16x32_bf16 v[90:93], v[162:165], v[214:217], v[90:93]
	v_mfma_f32_16x16x32_bf16 v[82:85], v[178:181], v[214:217], v[82:85]
	v_mfma_f32_16x16x32_bf16 v[74:77], v[162:165], v[234:237], v[74:77]
	v_mfma_f32_16x16x32_bf16 v[66:69], v[178:181], v[234:237], v[66:69]
	s_setprio 0
	s_barrier
	s_add_i32 s76, s76, s53
	s_mov_b32 m0, s76
	s_nop 0
	global_load_lds_dwordx4 v132, s[42:43]
	ds_read_b128 v[182:185], v175 offset:16384
	ds_read_b128 v[186:189], v175 offset:17408
	s_add_i32 m0, s76, 0x2000
	s_add_u32 s76, s42, 0x80000
	s_addc_u32 s77, s43, 0
	s_add_i32 s79, s79, s53
	global_load_lds_dwordx4 v136, s[42:43]
	ds_read_b128 v[190:193], v175 offset:18432
	ds_read_b128 v[206:209], v175 offset:19456
	s_mov_b32 m0, s79
	s_nop 0
	global_load_lds_dwordx4 v132, s[76:77]
	ds_read_b128 v[210:213], v175 offset:20480
	ds_read_b128 v[214:217], v175 offset:21504
	s_add_i32 m0, s79, 0x2000
	s_nop 0
	global_load_lds_dwordx4 v136, s[76:77]
	ds_read_b128 v[226:229], v175 offset:22528
	ds_read_b128 v[234:237], v175 offset:23552
	s_mov_b32 m0, s56
	s_nop 0
	global_load_lds_dwordx4 v130, s[44:45]
	s_mov_b32 m0, s57
	s_nop 0
	global_load_lds_dwordx4 v134, s[44:45]
	s_waitcnt vmcnt(8)
	s_waitcnt lgkmcnt(0)
	s_nop 0
	s_barrier
; #define PG8_STAGE(bufoff, gbase, voff) do { _Pragma("unroll") for (int _i = 0; _i < 2; ++_i) \
;         __builtin_amdgcn_global_load_lds((const unsigned*)((const char*)(gbase) + (voff)[_i]), (PG8_LAS unsigned*)(lds + (bufoff) + ldsw + _i * 8192), 16, 0, 0); } while (0)
; #define PG8_LDA(dst, b, h) do { _Pragma("unroll") for (int m = 0; m < 4; ++m) _Pragma("unroll") for (int k = 0; k < 2; ++k) dst[m][k] = *(const PG8_LAS bf16x8*)(lds + PG8_SA(b, h) + aoff + m * 2048 + k * 1024); } while (0)
; #define PG8_LDB(dst, b, h) do { _Pragma("unroll") for (int n = 0; n < 2; ++n) _Pragma("unroll") for (int k = 0; k < 2; ++k) dst[n][k] = *(const PG8_LAS bf16x8*)(lds + PG8_SB(b, h) + boff + n * 2048 + k * 1024); } while (0)
; #define PG8_MMA(ai, bj, At, Bt) do { __builtin_amdgcn_s_setprio(1); _Pragma("unroll") for (int m = 0; m < 4; ++m) _Pragma("unroll") for (int n = 0; n < 2; ++n) _Pragma("unroll") for (int k = 0; k < 2; ++k) \
;         acc[ai][bj][m][n] = __builtin_amdgcn_mfma_f32_16x16x32_bf16(Bt[n][k], At[m][k], acc[ai][bj][m][n], 0, 0, 0); __builtin_amdgcn_s_setprio(0); } while (0)
; #define PG8_WAIT_V(n) asm volatile("s_waitcnt vmcnt(" #n ")" ::: "memory")
; #define PG8_WAIT_L(n) asm volatile("s_waitcnt lgkmcnt(" #n ")" ::: "memory")
; #define PG8_BAR __builtin_amdgcn_s_barrier()
; #define PG8_SCHED __builtin_amdgcn_sched_barrier(0)
; template <class Epi, class Sched, bool ALIGN_EPI = false, bool SP2 = false>
; __device__ __forceinline__ void gemm_phase(PG8_LAS unsigned char* lds, const Gemm g, const Sched& S, const Epi& E, const int wave_id) {
;     ...
;             PG8_WAIT_V(8); PG8_WAIT_L(0); PG8_BAR; PG8_MMA(0, 0, At, B0); PG8_MMA(0, 1, At, B1); PG8_BAR; PG8_SCHED;
;             PG8_LDA(At, 0, 1); PG8_STAGE(PG8_SB(0, 0), b2, voffB); PG8_STAGE(PG8_SB(0, 1), b2 + hstep, voffB); PG8_STAGE(PG8_SA(0, 0), a2, voffA);
;             PG8_WAIT_V(8); PG8_WAIT_L(0); PG8_BAR; PG8_MMA(1, 0, At, B0); PG8_MMA(1, 1, At, B1); PG8_BAR; PG8_SCHED;
;             PG8_LDB(B0, 1, 0); PG8_LDB(B1, 1, 1); PG8_SCHED; PG8_LDA(At, 1, 0); PG8_STAGE(PG8_SA(0, 1), a2 + hstep, voffA);
;             PG8_WAIT_V(8); PG8_WAIT_L(0); PG8_BAR; PG8_MMA(0, 0, At, B0); PG8_MMA(0, 1, At, B1); PG8_BAR; PG8_SCHED;
	s_setprio 1
	s_waitcnt lgkmcnt(0)
	v_mfma_f32_16x16x32_bf16 v[62:65], v[142:145], v[182:185], 0
	v_mfma_f32_16x16x32_bf16 v[54:57], v[150:153], v[182:185], 0
	v_mfma_f32_16x16x32_bf16 v[46:49], v[142:145], v[190:193], 0
	v_mfma_f32_16x16x32_bf16 v[38:41], v[150:153], v[190:193], 0
	v_mfma_f32_16x16x32_bf16 v[30:33], v[142:145], v[210:213], 0
	v_mfma_f32_16x16x32_bf16 v[22:25], v[150:153], v[210:213], 0
	v_mfma_f32_16x16x32_bf16 v[14:17], v[142:145], v[226:229], 0
	v_mfma_f32_16x16x32_bf16 v[6:9], v[150:153], v[226:229], 0
	v_mfma_f32_16x16x32_bf16 v[62:65], v[146:149], v[186:189], v[62:65]
	v_mfma_f32_16x16x32_bf16 v[54:57], v[154:157], v[186:189], v[54:57]
	v_mfma_f32_16x16x32_bf16 v[46:49], v[146:149], v[206:209], v[46:49]
	v_mfma_f32_16x16x32_bf16 v[38:41], v[154:157], v[206:209], v[38:41]
	v_mfma_f32_16x16x32_bf16 v[30:33], v[146:149], v[214:217], v[30:33]
	v_mfma_f32_16x16x32_bf16 v[22:25], v[154:157], v[214:217], v[22:25]
	v_mfma_f32_16x16x32_bf16 v[14:17], v[146:149], v[234:237], v[14:17]
	v_mfma_f32_16x16x32_bf16 v[6:9], v[154:157], v[234:237], v[6:9]
	s_setprio 0
	s_setprio 1
	v_mfma_f32_16x16x32_bf16 v[58:61], v[158:161], v[182:185], 0
	v_mfma_f32_16x16x32_bf16 v[50:53], v[166:169], v[182:185], 0
	v_mfma_f32_16x16x32_bf16 v[42:45], v[158:161], v[190:193], 0
	v_mfma_f32_16x16x32_bf16 v[34:37], v[166:169], v[190:193], 0
	v_mfma_f32_16x16x32_bf16 v[26:29], v[158:161], v[210:213], 0
	v_mfma_f32_16x16x32_bf16 v[18:21], v[166:169], v[210:213], 0
	v_mfma_f32_16x16x32_bf16 v[10:13], v[158:161], v[226:229], 0
	v_mfma_f32_16x16x32_bf16 v[2:5], v[166:169], v[226:229], 0
	v_mfma_f32_16x16x32_bf16 v[58:61], v[162:165], v[186:189], v[58:61]
	v_mfma_f32_16x16x32_bf16 v[50:53], v[178:181], v[186:189], v[50:53]
	v_mfma_f32_16x16x32_bf16 v[42:45], v[162:165], v[206:209], v[42:45]
	v_mfma_f32_16x16x32_bf16 v[34:37], v[178:181], v[206:209], v[34:37]
	v_mfma_f32_16x16x32_bf16 v[26:29], v[162:165], v[214:217], v[26:29]
	v_mfma_f32_16x16x32_bf16 v[18:21], v[178:181], v[214:217], v[18:21]
	v_mfma_f32_16x16x32_bf16 v[10:13], v[162:165], v[234:237], v[10:13]
	v_mfma_f32_16x16x32_bf16 v[2:5], v[178:181], v[234:237], v[2:5]
	s_setprio 0
	s_barrier
	s_add_i32 s76, 0, 0x18000
	s_add_i32 s77, 0, 0x1c000
	s_add_u32 s44, s44, 0x80000
	s_addc_u32 s45, s45, 0
	s_mov_b32 m0, s64
	s_nop 0
	global_load_lds_dwordx4 v130, s[44:45]
	ds_read_b128 v[142:145], v230 offset:32768
	ds_read_b128 v[146:149], v230 offset:33792
	ds_read_b128 v[150:153], v230 offset:34816
	ds_read_b128 v[154:157], v230 offset:35840
	ds_read_b128 v[158:161], v230 offset:49152
	ds_read_b128 v[162:165], v230 offset:50176
	ds_read_b128 v[166:169], v230 offset:51200
	ds_read_b128 v[178:181], v230 offset:52224
	s_mov_b32 m0, s65
	s_nop 0
	global_load_lds_dwordx4 v134, s[44:45]
	ds_read_b128 v[182:185], v175 offset:32768
	ds_read_b128 v[186:189], v175 offset:33792
	ds_read_b128 v[190:193], v175 offset:34816
	ds_read_b128 v[206:209], v175 offset:35840
	ds_read_b128 v[210:213], v175 offset:36864
	ds_read_b128 v[214:217], v175 offset:37888
	ds_read_b128 v[226:229], v175 offset:38912
	ds_read_b128 v[234:237], v175 offset:39936
	s_waitcnt vmcnt(8)
	s_waitcnt lgkmcnt(0)
	s_barrier
	s_setprio 1
	s_waitcnt lgkmcnt(0)
	v_mfma_f32_16x16x32_bf16 v[126:129], v[142:145], v[182:185], v[126:129]
	v_mfma_f32_16x16x32_bf16 v[118:121], v[150:153], v[182:185], v[118:121]
	v_mfma_f32_16x16x32_bf16 v[110:113], v[142:145], v[190:193], v[110:113]
	v_mfma_f32_16x16x32_bf16 v[102:105], v[150:153], v[190:193], v[102:105]
	v_mfma_f32_16x16x32_bf16 v[94:97], v[142:145], v[210:213], v[94:97]
	v_mfma_f32_16x16x32_bf16 v[86:89], v[150:153], v[210:213], v[86:89]
	v_mfma_f32_16x16x32_bf16 v[78:81], v[142:145], v[226:229], v[78:81]
	v_mfma_f32_16x16x32_bf16 v[70:73], v[150:153], v[226:229], v[70:73]
	v_mfma_f32_16x16x32_bf16 v[126:129], v[146:149], v[186:189], v[126:129]
	v_mfma_f32_16x16x32_bf16 v[118:121], v[154:157], v[186:189], v[118:121]
	v_mfma_f32_16x16x32_bf16 v[110:113], v[146:149], v[206:209], v[110:113]
	v_mfma_f32_16x16x32_bf16 v[102:105], v[154:157], v[206:209], v[102:105]
	v_mfma_f32_16x16x32_bf16 v[94:97], v[146:149], v[214:217], v[94:97]
	v_mfma_f32_16x16x32_bf16 v[86:89], v[154:157], v[214:217], v[86:89]
	v_mfma_f32_16x16x32_bf16 v[78:81], v[146:149], v[234:237], v[78:81]
	v_mfma_f32_16x16x32_bf16 v[70:73], v[154:157], v[234:237], v[70:73]
	s_setprio 0
	s_setprio 1
	v_mfma_f32_16x16x32_bf16 v[122:125], v[158:161], v[182:185], v[122:125]
	v_mfma_f32_16x16x32_bf16 v[114:117], v[166:169], v[182:185], v[114:117]
	v_mfma_f32_16x16x32_bf16 v[106:109], v[158:161], v[190:193], v[106:109]
	v_mfma_f32_16x16x32_bf16 v[98:101], v[166:169], v[190:193], v[98:101]
	v_mfma_f32_16x16x32_bf16 v[90:93], v[158:161], v[210:213], v[90:93]
	v_mfma_f32_16x16x32_bf16 v[82:85], v[166:169], v[210:213], v[82:85]
	v_mfma_f32_16x16x32_bf16 v[74:77], v[158:161], v[226:229], v[74:77]
	v_mfma_f32_16x16x32_bf16 v[66:69], v[166:169], v[226:229], v[66:69]
	v_mfma_f32_16x16x32_bf16 v[122:125], v[162:165], v[186:189], v[122:125]
	v_mfma_f32_16x16x32_bf16 v[114:117], v[178:181], v[186:189], v[114:117]
	v_mfma_f32_16x16x32_bf16 v[106:109], v[162:165], v[206:209], v[106:109]
	v_mfma_f32_16x16x32_bf16 v[98:101], v[178:181], v[206:209], v[98:101]
	v_mfma_f32_16x16x32_bf16 v[90:93], v[162:165], v[214:217], v[90:93]
	v_mfma_f32_16x16x32_bf16 v[82:85], v[178:181], v[214:217], v[82:85]
	v_mfma_f32_16x16x32_bf16 v[74:77], v[162:165], v[234:237], v[74:77]
	v_mfma_f32_16x16x32_bf16 v[66:69], v[178:181], v[234:237], v[66:69]
	s_setprio 0
	s_barrier
; #define PG8_STAGE(bufoff, gbase, voff) do { _Pragma("unroll") for (int _i = 0; _i < 2; ++_i) \
;         __builtin_amdgcn_global_load_lds((const unsigned*)((const char*)(gbase) + (voff)[_i]), (PG8_LAS unsigned*)(lds + (bufoff) + ldsw + _i * 8192), 16, 0, 0); } while (0)
; #define PG8_LDA(dst, b, h) do { _Pragma("unroll") for (int m = 0; m < 4; ++m) _Pragma("unroll") for (int k = 0; k < 2; ++k) dst[m][k] = *(const PG8_LAS bf16x8*)(lds + PG8_SA(b, h) + aoff + m * 2048 + k * 1024); } while (0)
; #define PG8_LDB(dst, b, h) do { _Pragma("unroll") for (int n = 0; n < 2; ++n) _Pragma("unroll") for (int k = 0; k < 2; ++k) dst[n][k] = *(const PG8_LAS bf16x8*)(lds + PG8_SB(b, h) + boff + n * 2048 + k * 1024); } while (0)
; #define PG8_MMA(ai, bj, At, Bt) do { __builtin_amdgcn_s_setprio(1); _Pragma("unroll") for (int m = 0; m < 4; ++m) _Pragma("unroll") for (int n = 0; n < 2; ++n) _Pragma("unroll") for (int k = 0; k < 2; ++k) \
;         acc[ai][bj][m][n] = __builtin_amdgcn_mfma_f32_16x16x32_bf16(Bt[n][k], At[m][k], acc[ai][bj][m][n], 0, 0, 0); __builtin_amdgcn_s_setprio(0); } while (0)
; #define PG8_WAIT_V(n) asm volatile("s_waitcnt vmcnt(" #n ")" ::: "memory")
; #define PG8_WAIT_L(n) asm volatile("s_waitcnt lgkmcnt(" #n ")" ::: "memory")
; #define PG8_BAR __builtin_amdgcn_s_barrier()
; template <class Epi, class Sched, bool ALIGN_EPI = false, bool SP2 = false>
; __device__ __forceinline__ void gemm_phase(PG8_LAS unsigned char* lds, const Gemm g, const Sched& S, const Epi& E, const int wave_id) {
;     ...
;         for (int t = 0; t < nt; t += 2) {
;             const bool last = (t == nt - 2);
;             const char* a1 = cA + (size_t)(t + 1) * kstep;
;             const char* a2 = last ? nA : cA + (size_t)(t + 2) * kstep; const char* b2 = last ? nB : cB + (size_t)(t + 2) * kstep;
;             const char* a3 = a2 + kstep; const char* b3 = b2 + kstep;
;     ...
;             PG8_LDB(B0, 1, 0); PG8_LDB(B1, 1, 1); PG8_SCHED; PG8_LDA(At, 1, 0); PG8_STAGE(PG8_SA(0, 1), a2 + hstep, voffA);
;             PG8_WAIT_V(8); PG8_WAIT_L(0); PG8_BAR; PG8_MMA(0, 0, At, B0); PG8_MMA(0, 1, At, B1); PG8_BAR; PG8_SCHED;
;             PG8_LDA(At, 1, 1); PG8_STAGE(PG8_SB(1, 0), b3, voffB); PG8_STAGE(PG8_SB(1, 1), b3 + hstep, voffB); PG8_STAGE(PG8_SA(1, 0), a3, voffA);
;             PG8_WAIT_V(8); PG8_WAIT_L(0); PG8_BAR; PG8_MMA(1, 0, At, B0); PG8_MMA(1, 1, At, B1); PG8_BAR; PG8_SCHED;
	s_add_u32 vcc_lo, s44, 0xfff80080
	s_addc_u32 vcc_hi, s45, -1
	s_mov_b32 m0, s68
	s_nop 0
	global_load_lds_dwordx4 v130, vcc
	ds_read_b128 v[182:185], v175 offset:49152
	ds_read_b128 v[186:189], v175 offset:50176
	s_mov_b32 m0, s69
	s_add_i32 s44, s76, s53
	global_load_lds_dwordx4 v134, vcc
	ds_read_b128 v[190:193], v175 offset:51200
	ds_read_b128 v[206:209], v175 offset:52224
	s_add_u32 vcc_lo, s42, 0x80
	s_addc_u32 vcc_hi, s43, 0
	s_mov_b32 m0, s44
	s_nop 0
	global_load_lds_dwordx4 v132, vcc
	ds_read_b128 v[210:213], v175 offset:53248
	ds_read_b128 v[214:217], v175 offset:54272
	s_add_i32 m0, s44, 0x2000
	s_add_u32 s42, s42, 0x80080
	s_addc_u32 s43, s43, 0
	global_load_lds_dwordx4 v136, vcc
	ds_read_b128 v[226:229], v175 offset:55296
	ds_read_b128 v[234:237], v175 offset:56320
	s_add_i32 s44, s77, s53
	s_mov_b32 m0, s44
	s_nop 0
	global_load_lds_dwordx4 v132, s[42:43]
	s_add_i32 m0, s44, 0x2000
	s_nop 0
	global_load_lds_dwordx4 v136, s[42:43]
	s_waitcnt vmcnt(8)
	s_waitcnt lgkmcnt(0)
	s_barrier
	s_setprio 1
	s_waitcnt lgkmcnt(0)
	v_mfma_f32_16x16x32_bf16 v[62:65], v[142:145], v[182:185], v[62:65]
	v_mfma_f32_16x16x32_bf16 v[54:57], v[150:153], v[182:185], v[54:57]
	v_mfma_f32_16x16x32_bf16 v[46:49], v[142:145], v[190:193], v[46:49]
	v_mfma_f32_16x16x32_bf16 v[38:41], v[150:153], v[190:193], v[38:41]
	v_mfma_f32_16x16x32_bf16 v[30:33], v[142:145], v[210:213], v[30:33]
	v_mfma_f32_16x16x32_bf16 v[22:25], v[150:153], v[210:213], v[22:25]
	v_mfma_f32_16x16x32_bf16 v[14:17], v[142:145], v[226:229], v[14:17]
	v_mfma_f32_16x16x32_bf16 v[6:9], v[150:153], v[226:229], v[6:9]
	v_mfma_f32_16x16x32_bf16 v[62:65], v[146:149], v[186:189], v[62:65]
	v_mfma_f32_16x16x32_bf16 v[54:57], v[154:157], v[186:189], v[54:57]
	v_mfma_f32_16x16x32_bf16 v[46:49], v[146:149], v[206:209], v[46:49]
	v_mfma_f32_16x16x32_bf16 v[38:41], v[154:157], v[206:209], v[38:41]
	v_mfma_f32_16x16x32_bf16 v[30:33], v[146:149], v[214:217], v[30:33]
	v_mfma_f32_16x16x32_bf16 v[22:25], v[154:157], v[214:217], v[22:25]
	v_mfma_f32_16x16x32_bf16 v[14:17], v[146:149], v[234:237], v[14:17]
	v_mfma_f32_16x16x32_bf16 v[6:9], v[154:157], v[234:237], v[6:9]
	s_setprio 0
	s_setprio 1
	v_mfma_f32_16x16x32_bf16 v[58:61], v[158:161], v[182:185], v[58:61]
	v_mfma_f32_16x16x32_bf16 v[50:53], v[166:169], v[182:185], v[50:53]
	v_mfma_f32_16x16x32_bf16 v[42:45], v[158:161], v[190:193], v[42:45]
	v_mfma_f32_16x16x32_bf16 v[34:37], v[166:169], v[190:193], v[34:37]
	v_mfma_f32_16x16x32_bf16 v[26:29], v[158:161], v[210:213], v[26:29]
	v_mfma_f32_16x16x32_bf16 v[18:21], v[166:169], v[210:213], v[18:21]
	v_mfma_f32_16x16x32_bf16 v[10:13], v[158:161], v[226:229], v[10:13]
	v_mfma_f32_16x16x32_bf16 v[2:5], v[166:169], v[226:229], v[2:5]
	v_mfma_f32_16x16x32_bf16 v[58:61], v[162:165], v[186:189], v[58:61]
	v_mfma_f32_16x16x32_bf16 v[50:53], v[178:181], v[186:189], v[50:53]
	v_mfma_f32_16x16x32_bf16 v[42:45], v[162:165], v[206:209], v[42:45]
	v_mfma_f32_16x16x32_bf16 v[34:37], v[178:181], v[206:209], v[34:37]
	v_mfma_f32_16x16x32_bf16 v[26:29], v[162:165], v[214:217], v[26:29]
	v_mfma_f32_16x16x32_bf16 v[18:21], v[178:181], v[214:217], v[18:21]
	v_mfma_f32_16x16x32_bf16 v[10:13], v[162:165], v[234:237], v[10:13]
	v_mfma_f32_16x16x32_bf16 v[2:5], v[178:181], v[234:237], v[2:5]
	s_setprio 0
	s_barrier
	s_add_i32 s75, s75, 2
	s_add_u32 s20, s20, 0x100
	s_addc_u32 s21, s21, 0
	s_add_u32 s73, s73, 0x100
	s_addc_u32 s74, s74, 0
	s_cmp_gt_u32 s75, 29
	s_cbranch_scc1 .Lpeel_exit_g1
.LBB0_174:
	s_add_u32 s42, s20, 0xfff80080
	s_addc_u32 s43, s21, -1
	s_add_i32 s76, 0, 0x10000
	s_cmp_eq_u32 s75, 28
	s_cselect_b32 s45, s15, s43
	s_cselect_b32 s44, s41, s42
	s_cselect_b32 s43, s13, s74
	s_cselect_b32 s42, s72, s73
	s_add_i32 s79, 0, 0x14000
	s_add_i32 m0, s56, 0xc000
	s_nop 0
	global_load_lds_dwordx4 v138, s[20:21]
	ds_read_b128 v[142:145], v230
	ds_read_b128 v[146:149], v230 offset:1024
	ds_read_b128 v[150:153], v230 offset:2048
	ds_read_b128 v[154:157], v230 offset:3072
	ds_read_b128 v[158:161], v230 offset:16384
	ds_read_b128 v[162:165], v230 offset:17408
	ds_read_b128 v[166:169], v230 offset:18432
	ds_read_b128 v[178:181], v230 offset:19456
	s_add_i32 m0, s56, 0xe000
	s_nop 0
	global_load_lds_dwordx4 v140, s[20:21]
	ds_read_b128 v[182:185], v175
	ds_read_b128 v[186:189], v175 offset:1024
	ds_read_b128 v[190:193], v175 offset:2048
	ds_read_b128 v[206:209], v175 offset:3072
	ds_read_b128 v[210:213], v175 offset:4096
	ds_read_b128 v[214:217], v175 offset:5120
	ds_read_b128 v[226:229], v175 offset:6144
	ds_read_b128 v[234:237], v175 offset:7168
	s_waitcnt vmcnt(8)
	s_waitcnt lgkmcnt(0)
	s_barrier
; #define PG8_STAGE(bufoff, gbase, voff) do { _Pragma("unroll") for (int _i = 0; _i < 2; ++_i) \
;         __builtin_amdgcn_global_load_lds((const unsigned*)((const char*)(gbase) + (voff)[_i]), (PG8_LAS unsigned*)(lds + (bufoff) + ldsw + _i * 8192), 16, 0, 0); } while (0)
; #define PG8_LDA(dst, b, h) do { _Pragma("unroll") for (int m = 0; m < 4; ++m) _Pragma("unroll") for (int k = 0; k < 2; ++k) dst[m][k] = *(const PG8_LAS bf16x8*)(lds + PG8_SA(b, h) + aoff + m * 2048 + k * 1024); } while (0)
; #define PG8_LDB(dst, b, h) do { _Pragma("unroll") for (int n = 0; n < 2; ++n) _Pragma("unroll") for (int k = 0; k < 2; ++k) dst[n][k] = *(const PG8_LAS bf16x8*)(lds + PG8_SB(b, h) + boff + n * 2048 + k * 1024); } while (0)
; #define PG8_MMA(ai, bj, At, Bt) do { __builtin_amdgcn_s_setprio(1); _Pragma("unroll") for (int m = 0; m < 4; ++m) _Pragma("unroll") for (int n = 0; n < 2; ++n) _Pragma("unroll") for (int k = 0; k < 2; ++k) \
;         acc[ai][bj][m][n] = __builtin_amdgcn_mfma_f32_16x16x32_bf16(Bt[n][k], At[m][k], acc[ai][bj][m][n], 0, 0, 0); __builtin_amdgcn_s_setprio(0); } while (0)
; #define PG8_WAIT_V(n) asm volatile("s_waitcnt vmcnt(" #n ")" ::: "memory")
; #define PG8_WAIT_L(n) asm volatile("s_waitcnt lgkmcnt(" #n ")" ::: "memory")
; #define PG8_BAR __builtin_amdgcn_s_barrier()
; #define PG8_SCHED __builtin_amdgcn_sched_barrier(0)
; template <class Epi, class Sched, bool ALIGN_EPI = false, bool SP2 = false>
; __device__ __forceinline__ void gemm_phase(PG8_LAS unsigned char* lds, const Gemm g, const Sched& S, const Epi& E, const int wave_id) {
;     ...
;             PG8_LDB(B0, 0, 0); PG8_LDB(B1, 0, 1); PG8_SCHED; PG8_LDA(At, 0, 0); PG8_STAGE(PG8_SA(1, 1), a1 + hstep, voffA);
;             PG8_WAIT_V(8); PG8_WAIT_L(0); PG8_BAR; PG8_MMA(0, 0, At, B0); PG8_MMA(0, 1, At, B1); PG8_BAR; PG8_SCHED;
;             PG8_LDA(At, 0, 1); PG8_STAGE(PG8_SB(0, 0), b2, voffB); PG8_STAGE(PG8_SB(0, 1), b2 + hstep, voffB); PG8_STAGE(PG8_SA(0, 0), a2, voffA);
;             PG8_WAIT_V(8); PG8_WAIT_L(0); PG8_BAR; PG8_MMA(1, 0, At, B0); PG8_MMA(1, 1, At, B1); PG8_BAR; PG8_SCHED;
	s_setprio 1
	s_waitcnt lgkmcnt(0)
	v_mfma_f32_16x16x32_bf16 v[126:129], v[142:145], v[182:185], v[126:129]
	v_mfma_f32_16x16x32_bf16 v[118:121], v[150:153], v[182:185], v[118:121]
	v_mfma_f32_16x16x32_bf16 v[110:113], v[142:145], v[190:193], v[110:113]
	v_mfma_f32_16x16x32_bf16 v[102:105], v[150:153], v[190:193], v[102:105]
	v_mfma_f32_16x16x32_bf16 v[94:97], v[142:145], v[210:213], v[94:97]
	v_mfma_f32_16x16x32_bf16 v[86:89], v[150:153], v[210:213], v[86:89]
	v_mfma_f32_16x16x32_bf16 v[78:81], v[142:145], v[226:229], v[78:81]
	v_mfma_f32_16x16x32_bf16 v[70:73], v[150:153], v[226:229], v[70:73]
	v_mfma_f32_16x16x32_bf16 v[126:129], v[146:149], v[186:189], v[126:129]
	v_mfma_f32_16x16x32_bf16 v[118:121], v[154:157], v[186:189], v[118:121]
	v_mfma_f32_16x16x32_bf16 v[110:113], v[146:149], v[206:209], v[110:113]
	v_mfma_f32_16x16x32_bf16 v[102:105], v[154:157], v[206:209], v[102:105]
	v_mfma_f32_16x16x32_bf16 v[94:97], v[146:149], v[214:217], v[94:97]
	v_mfma_f32_16x16x32_bf16 v[86:89], v[154:157], v[214:217], v[86:89]
	v_mfma_f32_16x16x32_bf16 v[78:81], v[146:149], v[234:237], v[78:81]
	v_mfma_f32_16x16x32_bf16 v[70:73], v[154:157], v[234:237], v[70:73]
	s_setprio 0
	s_setprio 1
	v_mfma_f32_16x16x32_bf16 v[122:125], v[158:161], v[182:185], v[122:125]
	v_mfma_f32_16x16x32_bf16 v[114:117], v[166:169], v[182:185], v[114:117]
	v_mfma_f32_16x16x32_bf16 v[106:109], v[158:161], v[190:193], v[106:109]
	v_mfma_f32_16x16x32_bf16 v[98:101], v[166:169], v[190:193], v[98:101]
	v_mfma_f32_16x16x32_bf16 v[90:93], v[158:161], v[210:213], v[90:93]
	v_mfma_f32_16x16x32_bf16 v[82:85], v[166:169], v[210:213], v[82:85]
	v_mfma_f32_16x16x32_bf16 v[74:77], v[158:161], v[226:229], v[74:77]
	v_mfma_f32_16x16x32_bf16 v[66:69], v[166:169], v[226:229], v[66:69]
	v_mfma_f32_16x16x32_bf16 v[122:125], v[162:165], v[186:189], v[122:125]
	v_mfma_f32_16x16x32_bf16 v[114:117], v[178:181], v[186:189], v[114:117]
	v_mfma_f32_16x16x32_bf16 v[106:109], v[162:165], v[206:209], v[106:109]
	v_mfma_f32_16x16x32_bf16 v[98:101], v[178:181], v[206:209], v[98:101]
	v_mfma_f32_16x16x32_bf16 v[90:93], v[162:165], v[214:217], v[90:93]
	v_mfma_f32_16x16x32_bf16 v[82:85], v[178:181], v[214:217], v[82:85]
	v_mfma_f32_16x16x32_bf16 v[74:77], v[162:165], v[234:237], v[74:77]
	v_mfma_f32_16x16x32_bf16 v[66:69], v[178:181], v[234:237], v[66:69]
	s_setprio 0
	s_barrier
	s_add_i32 s76, s76, s53
	s_mov_b32 m0, s76
	s_nop 0
	global_load_lds_dwordx4 v132, s[42:43]
	ds_read_b128 v[182:185], v175 offset:16384
	ds_read_b128 v[186:189], v175 offset:17408
	s_add_i32 m0, s76, 0x2000
	s_add_u32 s76, s42, 0x80000
	s_addc_u32 s77, s43, 0
	s_add_i32 s79, s79, s53
	global_load_lds_dwordx4 v136, s[42:43]
	ds_read_b128 v[190:193], v175 offset:18432
	ds_read_b128 v[206:209], v175 offset:19456
	s_mov_b32 m0, s79
	s_nop 0
	global_load_lds_dwordx4 v132, s[76:77]
	ds_read_b128 v[210:213], v175 offset:20480
	ds_read_b128 v[214:217], v175 offset:21504
	s_add_i32 m0, s79, 0x2000
	s_nop 0
	global_load_lds_dwordx4 v136, s[76:77]
	ds_read_b128 v[226:229], v175 offset:22528
	ds_read_b128 v[234:237], v175 offset:23552
	s_mov_b32 m0, s56
	s_nop 0
	global_load_lds_dwordx4 v130, s[44:45]
	s_mov_b32 m0, s57
	s_nop 0
	global_load_lds_dwordx4 v134, s[44:45]
	s_waitcnt vmcnt(8)
	s_waitcnt lgkmcnt(0)
	s_nop 0
	s_barrier
	s_setprio 1
	s_waitcnt lgkmcnt(0)
	v_mfma_f32_16x16x32_bf16 v[62:65], v[142:145], v[182:185], v[62:65]
	v_mfma_f32_16x16x32_bf16 v[54:57], v[150:153], v[182:185], v[54:57]
	v_mfma_f32_16x16x32_bf16 v[46:49], v[142:145], v[190:193], v[46:49]
	v_mfma_f32_16x16x32_bf16 v[38:41], v[150:153], v[190:193], v[38:41]
	v_mfma_f32_16x16x32_bf16 v[30:33], v[142:145], v[210:213], v[30:33]
	v_mfma_f32_16x16x32_bf16 v[22:25], v[150:153], v[210:213], v[22:25]
	v_mfma_f32_16x16x32_bf16 v[14:17], v[142:145], v[226:229], v[14:17]
	v_mfma_f32_16x16x32_bf16 v[6:9], v[150:153], v[226:229], v[6:9]
	v_mfma_f32_16x16x32_bf16 v[62:65], v[146:149], v[186:189], v[62:65]
	v_mfma_f32_16x16x32_bf16 v[54:57], v[154:157], v[186:189], v[54:57]
	v_mfma_f32_16x16x32_bf16 v[46:49], v[146:149], v[206:209], v[46:49]
	v_mfma_f32_16x16x32_bf16 v[38:41], v[154:157], v[206:209], v[38:41]
	v_mfma_f32_16x16x32_bf16 v[30:33], v[146:149], v[214:217], v[30:33]
	v_mfma_f32_16x16x32_bf16 v[22:25], v[154:157], v[214:217], v[22:25]
	v_mfma_f32_16x16x32_bf16 v[14:17], v[146:149], v[234:237], v[14:17]
	v_mfma_f32_16x16x32_bf16 v[6:9], v[154:157], v[234:237], v[6:9]
	s_setprio 0
	s_setprio 1
	v_mfma_f32_16x16x32_bf16 v[58:61], v[158:161], v[182:185], v[58:61]
	v_mfma_f32_16x16x32_bf16 v[50:53], v[166:169], v[182:185], v[50:53]
	v_mfma_f32_16x16x32_bf16 v[42:45], v[158:161], v[190:193], v[42:45]
	v_mfma_f32_16x16x32_bf16 v[34:37], v[166:169], v[190:193], v[34:37]
	v_mfma_f32_16x16x32_bf16 v[26:29], v[158:161], v[210:213], v[26:29]
	v_mfma_f32_16x16x32_bf16 v[18:21], v[166:169], v[210:213], v[18:21]
	v_mfma_f32_16x16x32_bf16 v[10:13], v[158:161], v[226:229], v[10:13]
	v_mfma_f32_16x16x32_bf16 v[2:5], v[166:169], v[226:229], v[2:5]
	v_mfma_f32_16x16x32_bf16 v[58:61], v[162:165], v[186:189], v[58:61]
	v_mfma_f32_16x16x32_bf16 v[50:53], v[178:181], v[186:189], v[50:53]
	v_mfma_f32_16x16x32_bf16 v[42:45], v[162:165], v[206:209], v[42:45]
	v_mfma_f32_16x16x32_bf16 v[34:37], v[178:181], v[206:209], v[34:37]
	v_mfma_f32_16x16x32_bf16 v[26:29], v[162:165], v[214:217], v[26:29]
	v_mfma_f32_16x16x32_bf16 v[18:21], v[178:181], v[214:217], v[18:21]
	v_mfma_f32_16x16x32_bf16 v[10:13], v[162:165], v[234:237], v[10:13]
	v_mfma_f32_16x16x32_bf16 v[2:5], v[178:181], v[234:237], v[2:5]
	s_setprio 0
	s_barrier
; #define PG8_STAGE(bufoff, gbase, voff) do { _Pragma("unroll") for (int _i = 0; _i < 2; ++_i) \
;         __builtin_amdgcn_global_load_lds((const unsigned*)((const char*)(gbase) + (voff)[_i]), (PG8_LAS unsigned*)(lds + (bufoff) + ldsw + _i * 8192), 16, 0, 0); } while (0)
; #define PG8_LDA(dst, b, h) do { _Pragma("unroll") for (int m = 0; m < 4; ++m) _Pragma("unroll") for (int k = 0; k < 2; ++k) dst[m][k] = *(const PG8_LAS bf16x8*)(lds + PG8_SA(b, h) + aoff + m * 2048 + k * 1024); } while (0)
; #define PG8_LDB(dst, b, h) do { _Pragma("unroll") for (int n = 0; n < 2; ++n) _Pragma("unroll") for (int k = 0; k < 2; ++k) dst[n][k] = *(const PG8_LAS bf16x8*)(lds + PG8_SB(b, h) + boff + n * 2048 + k * 1024); } while (0)
; #define PG8_MMA(ai, bj, At, Bt) do { __builtin_amdgcn_s_setprio(1); _Pragma("unroll") for (int m = 0; m < 4; ++m) _Pragma("unroll") for (int n = 0; n < 2; ++n) _Pragma("unroll") for (int k = 0; k < 2; ++k) \
;         acc[ai][bj][m][n] = __builtin_amdgcn_mfma_f32_16x16x32_bf16(Bt[n][k], At[m][k], acc[ai][bj][m][n], 0, 0, 0); __builtin_amdgcn_s_setprio(0); } while (0)
; #define PG8_WAIT_V(n) asm volatile("s_waitcnt vmcnt(" #n ")" ::: "memory")
; #define PG8_WAIT_L(n) asm volatile("s_waitcnt lgkmcnt(" #n ")" ::: "memory")
; #define PG8_BAR __builtin_amdgcn_s_barrier()
; #define PG8_SCHED __builtin_amdgcn_sched_barrier(0)
; template <class Epi, class Sched, bool ALIGN_EPI = false, bool SP2 = false>
; __device__ __forceinline__ void gemm_phase(PG8_LAS unsigned char* lds, const Gemm g, const Sched& S, const Epi& E, const int wave_id) {
;     ...
;             PG8_LDB(B0, 1, 0); PG8_LDB(B1, 1, 1); PG8_SCHED; PG8_LDA(At, 1, 0); PG8_STAGE(PG8_SA(0, 1), a2 + hstep, voffA);
;             PG8_WAIT_V(8); PG8_WAIT_L(0); PG8_BAR; PG8_MMA(0, 0, At, B0); PG8_MMA(0, 1, At, B1); PG8_BAR; PG8_SCHED;
;             PG8_LDA(At, 1, 1); PG8_STAGE(PG8_SB(1, 0), b3, voffB); PG8_STAGE(PG8_SB(1, 1), b3 + hstep, voffB); PG8_STAGE(PG8_SA(1, 0), a3, voffA);
;             PG8_WAIT_V(8); PG8_WAIT_L(0); PG8_BAR; PG8_MMA(1, 0, At, B0); PG8_MMA(1, 1, At, B1); PG8_BAR; PG8_SCHED;
	s_add_i32 s76, 0, 0x18000
	s_add_i32 s77, 0, 0x1c000
	s_add_u32 s44, s44, 0x80000
	s_addc_u32 s45, s45, 0
	s_mov_b32 m0, s64
	s_nop 0
	global_load_lds_dwordx4 v130, s[44:45]
	ds_read_b128 v[142:145], v230 offset:32768
	ds_read_b128 v[146:149], v230 offset:33792
	ds_read_b128 v[150:153], v230 offset:34816
	ds_read_b128 v[154:157], v230 offset:35840
	ds_read_b128 v[158:161], v230 offset:49152
	ds_read_b128 v[162:165], v230 offset:50176
	ds_read_b128 v[166:169], v230 offset:51200
	ds_read_b128 v[178:181], v230 offset:52224
	s_mov_b32 m0, s65
	s_nop 0
	global_load_lds_dwordx4 v134, s[44:45]
	ds_read_b128 v[182:185], v175 offset:32768
	ds_read_b128 v[186:189], v175 offset:33792
	ds_read_b128 v[190:193], v175 offset:34816
	ds_read_b128 v[206:209], v175 offset:35840
	ds_read_b128 v[210:213], v175 offset:36864
	ds_read_b128 v[214:217], v175 offset:37888
	ds_read_b128 v[226:229], v175 offset:38912
	ds_read_b128 v[234:237], v175 offset:39936
	s_waitcnt vmcnt(8)
	s_waitcnt lgkmcnt(0)
	s_barrier
	s_setprio 1
	s_waitcnt lgkmcnt(0)
	v_mfma_f32_16x16x32_bf16 v[126:129], v[142:145], v[182:185], v[126:129]
	v_mfma_f32_16x16x32_bf16 v[118:121], v[150:153], v[182:185], v[118:121]
	v_mfma_f32_16x16x32_bf16 v[110:113], v[142:145], v[190:193], v[110:113]
	v_mfma_f32_16x16x32_bf16 v[102:105], v[150:153], v[190:193], v[102:105]
	v_mfma_f32_16x16x32_bf16 v[94:97], v[142:145], v[210:213], v[94:97]
	v_mfma_f32_16x16x32_bf16 v[86:89], v[150:153], v[210:213], v[86:89]
	v_mfma_f32_16x16x32_bf16 v[78:81], v[142:145], v[226:229], v[78:81]
	v_mfma_f32_16x16x32_bf16 v[70:73], v[150:153], v[226:229], v[70:73]
	v_mfma_f32_16x16x32_bf16 v[126:129], v[146:149], v[186:189], v[126:129]
	v_mfma_f32_16x16x32_bf16 v[118:121], v[154:157], v[186:189], v[118:121]
	v_mfma_f32_16x16x32_bf16 v[110:113], v[146:149], v[206:209], v[110:113]
	v_mfma_f32_16x16x32_bf16 v[102:105], v[154:157], v[206:209], v[102:105]
	v_mfma_f32_16x16x32_bf16 v[94:97], v[146:149], v[214:217], v[94:97]
	v_mfma_f32_16x16x32_bf16 v[86:89], v[154:157], v[214:217], v[86:89]
	v_mfma_f32_16x16x32_bf16 v[78:81], v[146:149], v[234:237], v[78:81]
	v_mfma_f32_16x16x32_bf16 v[70:73], v[154:157], v[234:237], v[70:73]
	s_setprio 0
	s_setprio 1
	v_mfma_f32_16x16x32_bf16 v[122:125], v[158:161], v[182:185], v[122:125]
	v_mfma_f32_16x16x32_bf16 v[114:117], v[166:169], v[182:185], v[114:117]
	v_mfma_f32_16x16x32_bf16 v[106:109], v[158:161], v[190:193], v[106:109]
	v_mfma_f32_16x16x32_bf16 v[98:101], v[166:169], v[190:193], v[98:101]
	v_mfma_f32_16x16x32_bf16 v[90:93], v[158:161], v[210:213], v[90:93]
	v_mfma_f32_16x16x32_bf16 v[82:85], v[166:169], v[210:213], v[82:85]
	v_mfma_f32_16x16x32_bf16 v[74:77], v[158:161], v[226:229], v[74:77]
	v_mfma_f32_16x16x32_bf16 v[66:69], v[166:169], v[226:229], v[66:69]
	v_mfma_f32_16x16x32_bf16 v[122:125], v[162:165], v[186:189], v[122:125]
	v_mfma_f32_16x16x32_bf16 v[114:117], v[178:181], v[186:189], v[114:117]
	v_mfma_f32_16x16x32_bf16 v[106:109], v[162:165], v[206:209], v[106:109]
	v_mfma_f32_16x16x32_bf16 v[98:101], v[178:181], v[206:209], v[98:101]
	v_mfma_f32_16x16x32_bf16 v[90:93], v[162:165], v[214:217], v[90:93]
	v_mfma_f32_16x16x32_bf16 v[82:85], v[178:181], v[214:217], v[82:85]
	v_mfma_f32_16x16x32_bf16 v[74:77], v[162:165], v[234:237], v[74:77]
	v_mfma_f32_16x16x32_bf16 v[66:69], v[178:181], v[234:237], v[66:69]
	s_setprio 0
	s_barrier
	s_add_u32 vcc_lo, s44, 0xfff80080
	s_addc_u32 vcc_hi, s45, -1
	s_mov_b32 m0, s68
	s_nop 0
	global_load_lds_dwordx4 v130, vcc
	ds_read_b128 v[182:185], v175 offset:49152
	ds_read_b128 v[186:189], v175 offset:50176
	s_mov_b32 m0, s69
	s_add_i32 s44, s76, s53
	global_load_lds_dwordx4 v134, vcc
	ds_read_b128 v[190:193], v175 offset:51200
	ds_read_b128 v[206:209], v175 offset:52224
	s_add_u32 vcc_lo, s42, 0x80
	s_addc_u32 vcc_hi, s43, 0
	s_mov_b32 m0, s44
	s_nop 0
	global_load_lds_dwordx4 v132, vcc
	ds_read_b128 v[210:213], v175 offset:53248
	ds_read_b128 v[214:217], v175 offset:54272
	s_add_i32 m0, s44, 0x2000
	s_add_u32 s42, s42, 0x80080
	s_addc_u32 s43, s43, 0
	global_load_lds_dwordx4 v136, vcc
	ds_read_b128 v[226:229], v175 offset:55296
	ds_read_b128 v[234:237], v175 offset:56320
	s_add_i32 s44, s77, s53
	s_mov_b32 m0, s44
	s_nop 0
	global_load_lds_dwordx4 v132, s[42:43]
	s_add_i32 m0, s44, 0x2000
	s_nop 0
	global_load_lds_dwordx4 v136, s[42:43]
	s_waitcnt vmcnt(8)
	s_waitcnt lgkmcnt(0)
	s_barrier
	s_setprio 1
	s_waitcnt lgkmcnt(0)
	v_mfma_f32_16x16x32_bf16 v[62:65], v[142:145], v[182:185], v[62:65]
	v_mfma_f32_16x16x32_bf16 v[54:57], v[150:153], v[182:185], v[54:57]
	v_mfma_f32_16x16x32_bf16 v[46:49], v[142:145], v[190:193], v[46:49]
	v_mfma_f32_16x16x32_bf16 v[38:41], v[150:153], v[190:193], v[38:41]
	v_mfma_f32_16x16x32_bf16 v[30:33], v[142:145], v[210:213], v[30:33]
	v_mfma_f32_16x16x32_bf16 v[22:25], v[150:153], v[210:213], v[22:25]
	v_mfma_f32_16x16x32_bf16 v[14:17], v[142:145], v[226:229], v[14:17]
	v_mfma_f32_16x16x32_bf16 v[6:9], v[150:153], v[226:229], v[6:9]
	v_mfma_f32_16x16x32_bf16 v[62:65], v[146:149], v[186:189], v[62:65]
	v_mfma_f32_16x16x32_bf16 v[54:57], v[154:157], v[186:189], v[54:57]
	v_mfma_f32_16x16x32_bf16 v[46:49], v[146:149], v[206:209], v[46:49]
	v_mfma_f32_16x16x32_bf16 v[38:41], v[154:157], v[206:209], v[38:41]
	v_mfma_f32_16x16x32_bf16 v[30:33], v[146:149], v[214:217], v[30:33]
	v_mfma_f32_16x16x32_bf16 v[22:25], v[154:157], v[214:217], v[22:25]
	v_mfma_f32_16x16x32_bf16 v[14:17], v[146:149], v[234:237], v[14:17]
	v_mfma_f32_16x16x32_bf16 v[6:9], v[154:157], v[234:237], v[6:9]
	s_setprio 0
	s_setprio 1
	v_mfma_f32_16x16x32_bf16 v[58:61], v[158:161], v[182:185], v[58:61]
	v_mfma_f32_16x16x32_bf16 v[50:53], v[166:169], v[182:185], v[50:53]
	v_mfma_f32_16x16x32_bf16 v[42:45], v[158:161], v[190:193], v[42:45]
	v_mfma_f32_16x16x32_bf16 v[34:37], v[166:169], v[190:193], v[34:37]
	v_mfma_f32_16x16x32_bf16 v[26:29], v[158:161], v[210:213], v[26:29]
	v_mfma_f32_16x16x32_bf16 v[18:21], v[166:169], v[210:213], v[18:21]
	v_mfma_f32_16x16x32_bf16 v[10:13], v[158:161], v[226:229], v[10:13]
	v_mfma_f32_16x16x32_bf16 v[2:5], v[166:169], v[226:229], v[2:5]
	v_mfma_f32_16x16x32_bf16 v[58:61], v[162:165], v[186:189], v[58:61]
	v_mfma_f32_16x16x32_bf16 v[50:53], v[178:181], v[186:189], v[50:53]
	v_mfma_f32_16x16x32_bf16 v[42:45], v[162:165], v[206:209], v[42:45]
	v_mfma_f32_16x16x32_bf16 v[34:37], v[178:181], v[206:209], v[34:37]
	v_mfma_f32_16x16x32_bf16 v[26:29], v[162:165], v[214:217], v[26:29]
	v_mfma_f32_16x16x32_bf16 v[18:21], v[178:181], v[214:217], v[18:21]
	v_mfma_f32_16x16x32_bf16 v[10:13], v[162:165], v[234:237], v[10:13]
	v_mfma_f32_16x16x32_bf16 v[2:5], v[178:181], v[234:237], v[2:5]
	s_setprio 0
	s_barrier
	s_add_i32 s75, s75, 2
	s_add_u32 s20, s20, 0x100
	s_addc_u32 s21, s21, 0
	s_add_u32 s73, s73, 0x100
	s_addc_u32 s74, s74, 0
	s_cmp_gt_u32 s75, 29
	s_cbranch_scc0 .LBB0_174

; #define PG8_STAGE(bufoff, gbase, voff) do { _Pragma("unroll") for (int _i = 0; _i < 2; ++_i) \
;         __builtin_amdgcn_global_load_lds((const unsigned*)((const char*)(gbase) + (voff)[_i]), (PG8_LAS unsigned*)(lds + (bufoff) + ldsw + _i * 8192), 16, 0, 0); } while (0)
; #define PG8_LDA(dst, b, h) do { _Pragma("unroll") for (int m = 0; m < 4; ++m) _Pragma("unroll") for (int k = 0; k < 2; ++k) dst[m][k] = *(const PG8_LAS bf16x8*)(lds + PG8_SA(b, h) + aoff + m * 2048 + k * 1024); } while (0)
; template <class Epi, class Sched, bool ALIGN_EPI = false, bool SP2 = false>
; __device__ __forceinline__ void gemm_phase(PG8_LAS unsigned char* lds, const Gemm g, const Sched& S, const Epi& E, const int wave_id) {
;     ...
;         const char* nA = has_next ? (const char*)g.A + (size_t)nxt.lm * tstep : cA; const char* nB = has_next ? (const char*)g.Bt + (size_t)nxt.ln * tstep : cB;
; #pragma unroll 1
;         for (int t = 0; t < nt; t += 2) {
;             const bool last = (t == nt - 2);
;             const char* a1 = cA + (size_t)(t + 1) * kstep;
;             const char* a2 = last ? nA : cA + (size_t)(t + 2) * kstep; const char* b2 = last ? nB : cB + (size_t)(t + 2) * kstep;
;             const char* a3 = a2 + kstep; const char* b3 = b2 + kstep;
;             if (last && has_next) S.a_ready(nxt);
;             if constexpr (SP2) {
;             PG8_LDB(B0, 0, 0); PG8_LDB(B1, 0, 1); PG8_SCHED; PG8_LDA(At, 0, 0); PG8_STAGE(PG8_SA(1, 1), a1 + hstep, voffA);
;             PG8_WAIT_V(8); PG8_WAIT_L(0); PG8_BAR; PG8_MMA(0, 0, At, B0); PG8_MMA(0, 1, At, B1); PG8_BAR; PG8_SCHED;
;             PG8_LDA(At, 0, 1); PG8_STAGE(PG8_SB(0, 0), b2, voffB); PG8_STAGE(PG8_SB(0, 1), b2 + hstep, voffB); PG8_STAGE(PG8_SA(0, 0), a2, voffA);
;             PG8_WAIT_V(8); PG8_WAIT_L(0); PG8_BAR; PG8_MMA(1, 0, At, B0); PG8_MMA(1, 1, At, B1); PG8_BAR; PG8_SCHED;
;             PG8_LDB(B0, 1, 0); PG8_LDB(B1, 1, 1); PG8_SCHED; PG8_LDA(At, 1, 0); PG8_STAGE(PG8_SA(0, 1), a2 + hstep, voffA);
;             PG8_WAIT_V(8); PG8_WAIT_L(0); PG8_BAR; PG8_MMA(0, 0, At, B0); PG8_MMA(0, 1, At, B1); PG8_BAR; PG8_SCHED;
;             PG8_LDA(At, 1, 1); PG8_STAGE(PG8_SB(1, 0), b3, voffB); PG8_STAGE(PG8_SB(1, 1), b3 + hstep, voffB); PG8_STAGE(PG8_SA(1, 0), a3, voffA);
;             PG8_WAIT_V(8); PG8_WAIT_L(0); PG8_BAR; PG8_MMA(1, 0, At, B0); PG8_MMA(1, 1, At, B1); PG8_BAR; PG8_SCHED;
.LBB0_523:
	s_ashr_i32 s15, s14, 31
	s_lshl_b64 s[16:17], s[14:15], 20
	s_add_u32 s16, s47, s16
	s_addc_u32 s17, s48, s17
	s_and_b64 s[18:19], s[38:39], exec
	s_cselect_b32 s15, s17, s41
	s_cselect_b32 s21, s16, s40
	s_ashr_i32 s13, s12, 31
	s_lshl_b64 s[18:19], s[12:13], 20
	s_add_u32 s18, s49, s18
	s_addc_u32 s19, s52, s19
	s_and_b64 s[44:45], s[38:39], exec
	s_cselect_b32 s13, s19, s43
	s_cselect_b32 s73, s18, s42
	s_add_u32 s40, s40, 0x80080
	s_addc_u32 s41, s41, 0
	s_add_u32 s74, s42, 0x100
	s_addc_u32 s75, s43, 0
	s_mov_b32 s76, -2
	v_add_u32_e32 v226, 0x10000, v218
	s_add_u32 s42, s40, 0xfff80080
	s_addc_u32 s43, s41, -1
	s_add_i32 s77, 0, 0x10000
	s_cmp_eq_u32 s76, 28
	s_cselect_b32 s45, s15, s43
	s_cselect_b32 s44, s21, s42
	s_cselect_b32 s43, s13, s75
	s_cselect_b32 s42, s73, s74
	s_add_i32 s79, 0, 0x14000
	s_add_i32 m0, s56, 0xc000
	s_nop 0
	global_load_lds_dwordx4 v210, s[40:41]
	ds_read_b128 v[118:121], v226
	ds_read_b128 v[122:125], v226 offset:1024
	ds_read_b128 v[130:133], v226 offset:2048
	ds_read_b128 v[134:137], v226 offset:3072
	ds_read_b128 v[146:149], v226 offset:16384
	ds_read_b128 v[150:153], v226 offset:17408
	ds_read_b128 v[154:157], v226 offset:18432
	ds_read_b128 v[158:161], v226 offset:19456
	s_add_i32 m0, s56, 0xe000
	s_nop 0
	global_load_lds_dwordx4 v212, s[40:41]
	ds_read_b128 v[162:165], v222
	ds_read_b128 v[166:169], v222 offset:1024
	ds_read_b128 v[170:173], v222 offset:2048
	ds_read_b128 v[174:177], v222 offset:3072
	ds_read_b128 v[178:181], v222 offset:4096
	ds_read_b128 v[182:185], v222 offset:5120
	ds_read_b128 v[186:189], v222 offset:6144
	ds_read_b128 v[214:217], v222 offset:7168
	s_waitcnt vmcnt(8)
	s_waitcnt lgkmcnt(0)
	s_barrier
	s_setprio 1
	s_waitcnt lgkmcnt(0)
	v_mfma_f32_16x16x32_bf16 v[142:145], v[118:121], v[162:165], 0
	v_mfma_f32_16x16x32_bf16 v[138:141], v[130:133], v[162:165], 0
	v_mfma_f32_16x16x32_bf16 v[110:113], v[118:121], v[170:173], 0
	v_mfma_f32_16x16x32_bf16 v[106:109], v[130:133], v[170:173], 0
	v_mfma_f32_16x16x32_bf16 v[94:97], v[118:121], v[178:181], 0
	v_mfma_f32_16x16x32_bf16 v[90:93], v[130:133], v[178:181], 0
	v_mfma_f32_16x16x32_bf16 v[78:81], v[118:121], v[186:189], 0
	v_mfma_f32_16x16x32_bf16 v[74:77], v[130:133], v[186:189], 0
	v_mfma_f32_16x16x32_bf16 v[142:145], v[122:125], v[166:169], v[142:145]
	v_mfma_f32_16x16x32_bf16 v[138:141], v[134:137], v[166:169], v[138:141]
	v_mfma_f32_16x16x32_bf16 v[110:113], v[122:125], v[174:177], v[110:113]
	v_mfma_f32_16x16x32_bf16 v[106:109], v[134:137], v[174:177], v[106:109]
	v_mfma_f32_16x16x32_bf16 v[94:97], v[122:125], v[182:185], v[94:97]
	v_mfma_f32_16x16x32_bf16 v[90:93], v[134:137], v[182:185], v[90:93]
	v_mfma_f32_16x16x32_bf16 v[78:81], v[122:125], v[214:217], v[78:81]
	v_mfma_f32_16x16x32_bf16 v[74:77], v[134:137], v[214:217], v[74:77]
	s_setprio 0
	s_setprio 1
	v_mfma_f32_16x16x32_bf16 v[126:129], v[146:149], v[162:165], 0
	v_mfma_f32_16x16x32_bf16 v[114:117], v[154:157], v[162:165], 0
	v_mfma_f32_16x16x32_bf16 v[102:105], v[146:149], v[170:173], 0
	v_mfma_f32_16x16x32_bf16 v[98:101], v[154:157], v[170:173], 0
	v_mfma_f32_16x16x32_bf16 v[86:89], v[146:149], v[178:181], 0
	v_mfma_f32_16x16x32_bf16 v[82:85], v[154:157], v[178:181], 0
	v_mfma_f32_16x16x32_bf16 v[70:73], v[146:149], v[186:189], 0
	v_mfma_f32_16x16x32_bf16 v[66:69], v[154:157], v[186:189], 0
	v_mfma_f32_16x16x32_bf16 v[126:129], v[150:153], v[166:169], v[126:129]
	v_mfma_f32_16x16x32_bf16 v[114:117], v[158:161], v[166:169], v[114:117]
	v_mfma_f32_16x16x32_bf16 v[102:105], v[150:153], v[174:177], v[102:105]
	v_mfma_f32_16x16x32_bf16 v[98:101], v[158:161], v[174:177], v[98:101]
	v_mfma_f32_16x16x32_bf16 v[86:89], v[150:153], v[182:185], v[86:89]
	v_mfma_f32_16x16x32_bf16 v[82:85], v[158:161], v[182:185], v[82:85]
	v_mfma_f32_16x16x32_bf16 v[70:73], v[150:153], v[214:217], v[70:73]
	v_mfma_f32_16x16x32_bf16 v[66:69], v[158:161], v[214:217], v[66:69]
	s_setprio 0
	s_barrier
	s_add_i32 s77, s77, s53
	s_mov_b32 m0, s77
	s_nop 0
	global_load_lds_dwordx4 v192, s[42:43]
	ds_read_b128 v[162:165], v222 offset:16384
	ds_read_b128 v[166:169], v222 offset:17408
	s_add_i32 m0, s77, 0x2000
	s_add_u32 s80, s42, 0x80000
	s_addc_u32 s81, s43, 0
	s_add_i32 s77, s79, s53
	global_load_lds_dwordx4 v208, s[42:43]
	ds_read_b128 v[170:173], v222 offset:18432
	ds_read_b128 v[174:177], v222 offset:19456
	s_mov_b32 m0, s77
	s_nop 0
	global_load_lds_dwordx4 v192, s[80:81]
	ds_read_b128 v[178:181], v222 offset:20480
	ds_read_b128 v[182:185], v222 offset:21504
	s_add_i32 m0, s77, 0x2000
	s_nop 0
	global_load_lds_dwordx4 v208, s[80:81]
	ds_read_b128 v[186:189], v222 offset:22528
	ds_read_b128 v[214:217], v222 offset:23552
	s_mov_b32 m0, s56
	s_nop 0
	global_load_lds_dwordx4 v190, s[44:45]
	s_mov_b32 m0, s57
	s_nop 0
	global_load_lds_dwordx4 v206, s[44:45]
	s_waitcnt vmcnt(8)
	s_waitcnt lgkmcnt(0)
	s_nop 0
	s_barrier
; #define PG8_STAGE(bufoff, gbase, voff) do { _Pragma("unroll") for (int _i = 0; _i < 2; ++_i) \
;         __builtin_amdgcn_global_load_lds((const unsigned*)((const char*)(gbase) + (voff)[_i]), (PG8_LAS unsigned*)(lds + (bufoff) + ldsw + _i * 8192), 16, 0, 0); } while (0)
; #define PG8_LDA(dst, b, h) do { _Pragma("unroll") for (int m = 0; m < 4; ++m) _Pragma("unroll") for (int k = 0; k < 2; ++k) dst[m][k] = *(const PG8_LAS bf16x8*)(lds + PG8_SA(b, h) + aoff + m * 2048 + k * 1024); } while (0)
; #define PG8_LDB(dst, b, h) do { _Pragma("unroll") for (int n = 0; n < 2; ++n) _Pragma("unroll") for (int k = 0; k < 2; ++k) dst[n][k] = *(const PG8_LAS bf16x8*)(lds + PG8_SB(b, h) + boff + n * 2048 + k * 1024); } while (0)
; #define PG8_MMA(ai, bj, At, Bt) do { __builtin_amdgcn_s_setprio(1); _Pragma("unroll") for (int m = 0; m < 4; ++m) _Pragma("unroll") for (int n = 0; n < 2; ++n) _Pragma("unroll") for (int k = 0; k < 2; ++k) \
;         acc[ai][bj][m][n] = __builtin_amdgcn_mfma_f32_16x16x32_bf16(Bt[n][k], At[m][k], acc[ai][bj][m][n], 0, 0, 0); __builtin_amdgcn_s_setprio(0); } while (0)
; #define PG8_WAIT_V(n) asm volatile("s_waitcnt vmcnt(" #n ")" ::: "memory")
; #define PG8_WAIT_L(n) asm volatile("s_waitcnt lgkmcnt(" #n ")" ::: "memory")
; #define PG8_BAR __builtin_amdgcn_s_barrier()
; #define PG8_SCHED __builtin_amdgcn_sched_barrier(0)
; template <class Epi, class Sched, bool ALIGN_EPI = false, bool SP2 = false>
; __device__ __forceinline__ void gemm_phase(PG8_LAS unsigned char* lds, const Gemm g, const Sched& S, const Epi& E, const int wave_id) {
;     ...
;             PG8_WAIT_V(8); PG8_WAIT_L(0); PG8_BAR; PG8_MMA(0, 0, At, B0); PG8_MMA(0, 1, At, B1); PG8_BAR; PG8_SCHED;
;             PG8_LDA(At, 0, 1); PG8_STAGE(PG8_SB(0, 0), b2, voffB); PG8_STAGE(PG8_SB(0, 1), b2 + hstep, voffB); PG8_STAGE(PG8_SA(0, 0), a2, voffA);
;             PG8_WAIT_V(8); PG8_WAIT_L(0); PG8_BAR; PG8_MMA(1, 0, At, B0); PG8_MMA(1, 1, At, B1); PG8_BAR; PG8_SCHED;
;             PG8_LDB(B0, 1, 0); PG8_LDB(B1, 1, 1); PG8_SCHED; PG8_LDA(At, 1, 0); PG8_STAGE(PG8_SA(0, 1), a2 + hstep, voffA);
;             PG8_WAIT_V(8); PG8_WAIT_L(0); PG8_BAR; PG8_MMA(0, 0, At, B0); PG8_MMA(0, 1, At, B1); PG8_BAR; PG8_SCHED;
	s_setprio 1
	s_waitcnt lgkmcnt(0)
	v_mfma_f32_16x16x32_bf16 v[62:65], v[118:121], v[162:165], 0
	v_mfma_f32_16x16x32_bf16 v[58:61], v[130:133], v[162:165], 0
	v_mfma_f32_16x16x32_bf16 v[46:49], v[118:121], v[170:173], 0
	v_mfma_f32_16x16x32_bf16 v[42:45], v[130:133], v[170:173], 0
	v_mfma_f32_16x16x32_bf16 v[30:33], v[118:121], v[178:181], 0
	v_mfma_f32_16x16x32_bf16 v[26:29], v[130:133], v[178:181], 0
	v_mfma_f32_16x16x32_bf16 v[14:17], v[118:121], v[186:189], 0
	v_mfma_f32_16x16x32_bf16 v[10:13], v[130:133], v[186:189], 0
	v_mfma_f32_16x16x32_bf16 v[62:65], v[122:125], v[166:169], v[62:65]
	v_mfma_f32_16x16x32_bf16 v[58:61], v[134:137], v[166:169], v[58:61]
	v_mfma_f32_16x16x32_bf16 v[46:49], v[122:125], v[174:177], v[46:49]
	v_mfma_f32_16x16x32_bf16 v[42:45], v[134:137], v[174:177], v[42:45]
	v_mfma_f32_16x16x32_bf16 v[30:33], v[122:125], v[182:185], v[30:33]
	v_mfma_f32_16x16x32_bf16 v[26:29], v[134:137], v[182:185], v[26:29]
	v_mfma_f32_16x16x32_bf16 v[14:17], v[122:125], v[214:217], v[14:17]
	v_mfma_f32_16x16x32_bf16 v[10:13], v[134:137], v[214:217], v[10:13]
	s_setprio 0
	s_setprio 1
	v_mfma_f32_16x16x32_bf16 v[54:57], v[146:149], v[162:165], 0
	v_mfma_f32_16x16x32_bf16 v[50:53], v[154:157], v[162:165], 0
	v_mfma_f32_16x16x32_bf16 v[38:41], v[146:149], v[170:173], 0
	v_mfma_f32_16x16x32_bf16 v[34:37], v[154:157], v[170:173], 0
	v_mfma_f32_16x16x32_bf16 v[22:25], v[146:149], v[178:181], 0
	v_mfma_f32_16x16x32_bf16 v[18:21], v[154:157], v[178:181], 0
	v_mfma_f32_16x16x32_bf16 v[6:9], v[146:149], v[186:189], 0
	v_mfma_f32_16x16x32_bf16 v[2:5], v[154:157], v[186:189], 0
	v_mfma_f32_16x16x32_bf16 v[54:57], v[150:153], v[166:169], v[54:57]
	v_mfma_f32_16x16x32_bf16 v[50:53], v[158:161], v[166:169], v[50:53]
	v_mfma_f32_16x16x32_bf16 v[38:41], v[150:153], v[174:177], v[38:41]
	v_mfma_f32_16x16x32_bf16 v[34:37], v[158:161], v[174:177], v[34:37]
	v_mfma_f32_16x16x32_bf16 v[22:25], v[150:153], v[182:185], v[22:25]
	v_mfma_f32_16x16x32_bf16 v[18:21], v[158:161], v[182:185], v[18:21]
	v_mfma_f32_16x16x32_bf16 v[6:9], v[150:153], v[214:217], v[6:9]
	v_mfma_f32_16x16x32_bf16 v[2:5], v[158:161], v[214:217], v[2:5]
	s_setprio 0
	s_barrier
	s_add_i32 s77, 0, 0x18000
	s_add_i32 s79, 0, 0x1c000
	s_add_u32 s44, s44, 0x80000
	s_addc_u32 s45, s45, 0
	s_mov_b32 m0, s64
	s_nop 0
	global_load_lds_dwordx4 v190, s[44:45]
	ds_read_b128 v[118:121], v226 offset:32768
	ds_read_b128 v[122:125], v226 offset:33792
	ds_read_b128 v[130:133], v226 offset:34816
	ds_read_b128 v[134:137], v226 offset:35840
	ds_read_b128 v[146:149], v226 offset:49152
	ds_read_b128 v[150:153], v226 offset:50176
	ds_read_b128 v[154:157], v226 offset:51200
	ds_read_b128 v[158:161], v226 offset:52224
	s_mov_b32 m0, s65
	s_nop 0
	global_load_lds_dwordx4 v206, s[44:45]
	ds_read_b128 v[162:165], v222 offset:32768
	ds_read_b128 v[166:169], v222 offset:33792
	ds_read_b128 v[170:173], v222 offset:34816
	ds_read_b128 v[174:177], v222 offset:35840
	ds_read_b128 v[178:181], v222 offset:36864
	ds_read_b128 v[182:185], v222 offset:37888
	ds_read_b128 v[186:189], v222 offset:38912
	ds_read_b128 v[214:217], v222 offset:39936
	s_waitcnt vmcnt(8)
	s_waitcnt lgkmcnt(0)
	s_barrier
	s_setprio 1
	s_waitcnt lgkmcnt(0)
	v_mfma_f32_16x16x32_bf16 v[142:145], v[118:121], v[162:165], v[142:145]
	v_mfma_f32_16x16x32_bf16 v[138:141], v[130:133], v[162:165], v[138:141]
	v_mfma_f32_16x16x32_bf16 v[110:113], v[118:121], v[170:173], v[110:113]
	v_mfma_f32_16x16x32_bf16 v[106:109], v[130:133], v[170:173], v[106:109]
	v_mfma_f32_16x16x32_bf16 v[94:97], v[118:121], v[178:181], v[94:97]
	v_mfma_f32_16x16x32_bf16 v[90:93], v[130:133], v[178:181], v[90:93]
	v_mfma_f32_16x16x32_bf16 v[78:81], v[118:121], v[186:189], v[78:81]
	v_mfma_f32_16x16x32_bf16 v[74:77], v[130:133], v[186:189], v[74:77]
	v_mfma_f32_16x16x32_bf16 v[142:145], v[122:125], v[166:169], v[142:145]
	v_mfma_f32_16x16x32_bf16 v[138:141], v[134:137], v[166:169], v[138:141]
	v_mfma_f32_16x16x32_bf16 v[110:113], v[122:125], v[174:177], v[110:113]
	v_mfma_f32_16x16x32_bf16 v[106:109], v[134:137], v[174:177], v[106:109]
	v_mfma_f32_16x16x32_bf16 v[94:97], v[122:125], v[182:185], v[94:97]
	v_mfma_f32_16x16x32_bf16 v[90:93], v[134:137], v[182:185], v[90:93]
	v_mfma_f32_16x16x32_bf16 v[78:81], v[122:125], v[214:217], v[78:81]
	v_mfma_f32_16x16x32_bf16 v[74:77], v[134:137], v[214:217], v[74:77]
	s_setprio 0
	s_setprio 1
	v_mfma_f32_16x16x32_bf16 v[126:129], v[146:149], v[162:165], v[126:129]
	v_mfma_f32_16x16x32_bf16 v[114:117], v[154:157], v[162:165], v[114:117]
	v_mfma_f32_16x16x32_bf16 v[102:105], v[146:149], v[170:173], v[102:105]
	v_mfma_f32_16x16x32_bf16 v[98:101], v[154:157], v[170:173], v[98:101]
	v_mfma_f32_16x16x32_bf16 v[86:89], v[146:149], v[178:181], v[86:89]
	v_mfma_f32_16x16x32_bf16 v[82:85], v[154:157], v[178:181], v[82:85]
	v_mfma_f32_16x16x32_bf16 v[70:73], v[146:149], v[186:189], v[70:73]
	v_mfma_f32_16x16x32_bf16 v[66:69], v[154:157], v[186:189], v[66:69]
	v_mfma_f32_16x16x32_bf16 v[126:129], v[150:153], v[166:169], v[126:129]
	v_mfma_f32_16x16x32_bf16 v[114:117], v[158:161], v[166:169], v[114:117]
	v_mfma_f32_16x16x32_bf16 v[102:105], v[150:153], v[174:177], v[102:105]
	v_mfma_f32_16x16x32_bf16 v[98:101], v[158:161], v[174:177], v[98:101]
	v_mfma_f32_16x16x32_bf16 v[86:89], v[150:153], v[182:185], v[86:89]
	v_mfma_f32_16x16x32_bf16 v[82:85], v[158:161], v[182:185], v[82:85]
	v_mfma_f32_16x16x32_bf16 v[70:73], v[150:153], v[214:217], v[70:73]
	v_mfma_f32_16x16x32_bf16 v[66:69], v[158:161], v[214:217], v[66:69]
	s_setprio 0
	s_barrier
; #define PG8_STAGE(bufoff, gbase, voff) do { _Pragma("unroll") for (int _i = 0; _i < 2; ++_i) \
;         __builtin_amdgcn_global_load_lds((const unsigned*)((const char*)(gbase) + (voff)[_i]), (PG8_LAS unsigned*)(lds + (bufoff) + ldsw + _i * 8192), 16, 0, 0); } while (0)
; #define PG8_LDA(dst, b, h) do { _Pragma("unroll") for (int m = 0; m < 4; ++m) _Pragma("unroll") for (int k = 0; k < 2; ++k) dst[m][k] = *(const PG8_LAS bf16x8*)(lds + PG8_SA(b, h) + aoff + m * 2048 + k * 1024); } while (0)
; #define PG8_LDB(dst, b, h) do { _Pragma("unroll") for (int n = 0; n < 2; ++n) _Pragma("unroll") for (int k = 0; k < 2; ++k) dst[n][k] = *(const PG8_LAS bf16x8*)(lds + PG8_SB(b, h) + boff + n * 2048 + k * 1024); } while (0)
; #define PG8_MMA(ai, bj, At, Bt) do { __builtin_amdgcn_s_setprio(1); _Pragma("unroll") for (int m = 0; m < 4; ++m) _Pragma("unroll") for (int n = 0; n < 2; ++n) _Pragma("unroll") for (int k = 0; k < 2; ++k) \
;         acc[ai][bj][m][n] = __builtin_amdgcn_mfma_f32_16x16x32_bf16(Bt[n][k], At[m][k], acc[ai][bj][m][n], 0, 0, 0); __builtin_amdgcn_s_setprio(0); } while (0)
; #define PG8_WAIT_V(n) asm volatile("s_waitcnt vmcnt(" #n ")" ::: "memory")
; #define PG8_WAIT_L(n) asm volatile("s_waitcnt lgkmcnt(" #n ")" ::: "memory")
; #define PG8_BAR __builtin_amdgcn_s_barrier()
; template <class Epi, class Sched, bool ALIGN_EPI = false, bool SP2 = false>
; __device__ __forceinline__ void gemm_phase(PG8_LAS unsigned char* lds, const Gemm g, const Sched& S, const Epi& E, const int wave_id) {
;     ...
;         for (int t = 0; t < nt; t += 2) {
;             const bool last = (t == nt - 2);
;             const char* a1 = cA + (size_t)(t + 1) * kstep;
;             const char* a2 = last ? nA : cA + (size_t)(t + 2) * kstep; const char* b2 = last ? nB : cB + (size_t)(t + 2) * kstep;
;             const char* a3 = a2 + kstep; const char* b3 = b2 + kstep;
;     ...
;             PG8_LDB(B0, 1, 0); PG8_LDB(B1, 1, 1); PG8_SCHED; PG8_LDA(At, 1, 0); PG8_STAGE(PG8_SA(0, 1), a2 + hstep, voffA);
;             PG8_WAIT_V(8); PG8_WAIT_L(0); PG8_BAR; PG8_MMA(0, 0, At, B0); PG8_MMA(0, 1, At, B1); PG8_BAR; PG8_SCHED;
;             PG8_LDA(At, 1, 1); PG8_STAGE(PG8_SB(1, 0), b3, voffB); PG8_STAGE(PG8_SB(1, 1), b3 + hstep, voffB); PG8_STAGE(PG8_SA(1, 0), a3, voffA);
;             PG8_WAIT_V(8); PG8_WAIT_L(0); PG8_BAR; PG8_MMA(1, 0, At, B0); PG8_MMA(1, 1, At, B1); PG8_BAR; PG8_SCHED;
	s_add_u32 vcc_lo, s44, 0xfff80080
	s_addc_u32 vcc_hi, s45, -1
	s_mov_b32 m0, s70
	s_nop 0
	global_load_lds_dwordx4 v190, vcc
	ds_read_b128 v[162:165], v222 offset:49152
	ds_read_b128 v[166:169], v222 offset:50176
	s_mov_b32 m0, s71
	s_add_i32 s44, s77, s53
	global_load_lds_dwordx4 v206, vcc
	ds_read_b128 v[170:173], v222 offset:51200
	ds_read_b128 v[174:177], v222 offset:52224
	s_add_u32 vcc_lo, s42, 0x80
	s_addc_u32 vcc_hi, s43, 0
	s_mov_b32 m0, s44
	s_nop 0
	global_load_lds_dwordx4 v192, vcc
	ds_read_b128 v[178:181], v222 offset:53248
	ds_read_b128 v[182:185], v222 offset:54272
	s_add_i32 m0, s44, 0x2000
	s_add_u32 s42, s42, 0x80080
	s_addc_u32 s43, s43, 0
	global_load_lds_dwordx4 v208, vcc
	ds_read_b128 v[186:189], v222 offset:55296
	ds_read_b128 v[214:217], v222 offset:56320
	s_add_i32 s44, s79, s53
	s_mov_b32 m0, s44
	s_nop 0
	global_load_lds_dwordx4 v192, s[42:43]
	s_add_i32 m0, s44, 0x2000
	s_nop 0
	global_load_lds_dwordx4 v208, s[42:43]
	s_waitcnt vmcnt(8)
	s_waitcnt lgkmcnt(0)
	s_barrier
	s_setprio 1
	s_waitcnt lgkmcnt(0)
	v_mfma_f32_16x16x32_bf16 v[62:65], v[118:121], v[162:165], v[62:65]
	v_mfma_f32_16x16x32_bf16 v[58:61], v[130:133], v[162:165], v[58:61]
	v_mfma_f32_16x16x32_bf16 v[46:49], v[118:121], v[170:173], v[46:49]
	v_mfma_f32_16x16x32_bf16 v[42:45], v[130:133], v[170:173], v[42:45]
	v_mfma_f32_16x16x32_bf16 v[30:33], v[118:121], v[178:181], v[30:33]
	v_mfma_f32_16x16x32_bf16 v[26:29], v[130:133], v[178:181], v[26:29]
	v_mfma_f32_16x16x32_bf16 v[14:17], v[118:121], v[186:189], v[14:17]
	v_mfma_f32_16x16x32_bf16 v[10:13], v[130:133], v[186:189], v[10:13]
	v_mfma_f32_16x16x32_bf16 v[62:65], v[122:125], v[166:169], v[62:65]
	v_mfma_f32_16x16x32_bf16 v[58:61], v[134:137], v[166:169], v[58:61]
	v_mfma_f32_16x16x32_bf16 v[46:49], v[122:125], v[174:177], v[46:49]
	v_mfma_f32_16x16x32_bf16 v[42:45], v[134:137], v[174:177], v[42:45]
	v_mfma_f32_16x16x32_bf16 v[30:33], v[122:125], v[182:185], v[30:33]
	v_mfma_f32_16x16x32_bf16 v[26:29], v[134:137], v[182:185], v[26:29]
	v_mfma_f32_16x16x32_bf16 v[14:17], v[122:125], v[214:217], v[14:17]
	v_mfma_f32_16x16x32_bf16 v[10:13], v[134:137], v[214:217], v[10:13]
	s_setprio 0
	s_setprio 1
	v_mfma_f32_16x16x32_bf16 v[54:57], v[146:149], v[162:165], v[54:57]
	v_mfma_f32_16x16x32_bf16 v[50:53], v[154:157], v[162:165], v[50:53]
	v_mfma_f32_16x16x32_bf16 v[38:41], v[146:149], v[170:173], v[38:41]
	v_mfma_f32_16x16x32_bf16 v[34:37], v[154:157], v[170:173], v[34:37]
	v_mfma_f32_16x16x32_bf16 v[22:25], v[146:149], v[178:181], v[22:25]
	v_mfma_f32_16x16x32_bf16 v[18:21], v[154:157], v[178:181], v[18:21]
	v_mfma_f32_16x16x32_bf16 v[6:9], v[146:149], v[186:189], v[6:9]
	v_mfma_f32_16x16x32_bf16 v[2:5], v[154:157], v[186:189], v[2:5]
	v_mfma_f32_16x16x32_bf16 v[54:57], v[150:153], v[166:169], v[54:57]
	v_mfma_f32_16x16x32_bf16 v[50:53], v[158:161], v[166:169], v[50:53]
	v_mfma_f32_16x16x32_bf16 v[38:41], v[150:153], v[174:177], v[38:41]
	v_mfma_f32_16x16x32_bf16 v[34:37], v[158:161], v[174:177], v[34:37]
	v_mfma_f32_16x16x32_bf16 v[22:25], v[150:153], v[182:185], v[22:25]
	v_mfma_f32_16x16x32_bf16 v[18:21], v[158:161], v[182:185], v[18:21]
	v_mfma_f32_16x16x32_bf16 v[6:9], v[150:153], v[214:217], v[6:9]
	v_mfma_f32_16x16x32_bf16 v[2:5], v[158:161], v[214:217], v[2:5]
	s_setprio 0
	s_barrier
	s_add_i32 s76, s76, 2
	s_add_u32 s40, s40, 0x100
	s_addc_u32 s41, s41, 0
	s_add_u32 s74, s74, 0x100
	s_addc_u32 s75, s75, 0
	s_cmp_gt_u32 s76, 29
	s_cbranch_scc1 .Lpeel_exit_g2
.LBB0_524:
	s_add_u32 s42, s40, 0xfff80080
	s_addc_u32 s43, s41, -1
	s_add_i32 s77, 0, 0x10000
	s_cmp_eq_u32 s76, 28
	s_cselect_b32 s45, s15, s43
	s_cselect_b32 s44, s21, s42
	s_cselect_b32 s43, s13, s75
	s_cselect_b32 s42, s73, s74
	s_add_i32 s79, 0, 0x14000
	s_add_i32 m0, s56, 0xc000
	s_nop 0
	global_load_lds_dwordx4 v210, s[40:41]
	ds_read_b128 v[118:121], v226
	ds_read_b128 v[122:125], v226 offset:1024
	ds_read_b128 v[130:133], v226 offset:2048
	ds_read_b128 v[134:137], v226 offset:3072
	ds_read_b128 v[146:149], v226 offset:16384
	ds_read_b128 v[150:153], v226 offset:17408
	ds_read_b128 v[154:157], v226 offset:18432
	ds_read_b128 v[158:161], v226 offset:19456
	s_add_i32 m0, s56, 0xe000
	s_nop 0
	global_load_lds_dwordx4 v212, s[40:41]
	ds_read_b128 v[162:165], v222
	ds_read_b128 v[166:169], v222 offset:1024
	ds_read_b128 v[170:173], v222 offset:2048
	ds_read_b128 v[174:177], v222 offset:3072
	ds_read_b128 v[178:181], v222 offset:4096
	ds_read_b128 v[182:185], v222 offset:5120
	ds_read_b128 v[186:189], v222 offset:6144
	ds_read_b128 v[214:217], v222 offset:7168
	s_waitcnt vmcnt(8)
	s_waitcnt lgkmcnt(0)
	s_barrier
; #define PG8_STAGE(bufoff, gbase, voff) do { _Pragma("unroll") for (int _i = 0; _i < 2; ++_i) \
;         __builtin_amdgcn_global_load_lds((const unsigned*)((const char*)(gbase) + (voff)[_i]), (PG8_LAS unsigned*)(lds + (bufoff) + ldsw + _i * 8192), 16, 0, 0); } while (0)
; #define PG8_LDA(dst, b, h) do { _Pragma("unroll") for (int m = 0; m < 4; ++m) _Pragma("unroll") for (int k = 0; k < 2; ++k) dst[m][k] = *(const PG8_LAS bf16x8*)(lds + PG8_SA(b, h) + aoff + m * 2048 + k * 1024); } while (0)
; #define PG8_LDB(dst, b, h) do { _Pragma("unroll") for (int n = 0; n < 2; ++n) _Pragma("unroll") for (int k = 0; k < 2; ++k) dst[n][k] = *(const PG8_LAS bf16x8*)(lds + PG8_SB(b, h) + boff + n * 2048 + k * 1024); } while (0)
; #define PG8_MMA(ai, bj, At, Bt) do { __builtin_amdgcn_s_setprio(1); _Pragma("unroll") for (int m = 0; m < 4; ++m) _Pragma("unroll") for (int n = 0; n < 2; ++n) _Pragma("unroll") for (int k = 0; k < 2; ++k) \
;         acc[ai][bj][m][n] = __builtin_amdgcn_mfma_f32_16x16x32_bf16(Bt[n][k], At[m][k], acc[ai][bj][m][n], 0, 0, 0); __builtin_amdgcn_s_setprio(0); } while (0)
; #define PG8_WAIT_V(n) asm volatile("s_waitcnt vmcnt(" #n ")" ::: "memory")
; #define PG8_WAIT_L(n) asm volatile("s_waitcnt lgkmcnt(" #n ")" ::: "memory")
; #define PG8_BAR __builtin_amdgcn_s_barrier()
; #define PG8_SCHED __builtin_amdgcn_sched_barrier(0)
; template <class Epi, class Sched, bool ALIGN_EPI = false, bool SP2 = false>
; __device__ __forceinline__ void gemm_phase(PG8_LAS unsigned char* lds, const Gemm g, const Sched& S, const Epi& E, const int wave_id) {
;     ...
;             PG8_LDB(B0, 0, 0); PG8_LDB(B1, 0, 1); PG8_SCHED; PG8_LDA(At, 0, 0); PG8_STAGE(PG8_SA(1, 1), a1 + hstep, voffA);
;             PG8_WAIT_V(8); PG8_WAIT_L(0); PG8_BAR; PG8_MMA(0, 0, At, B0); PG8_MMA(0, 1, At, B1); PG8_BAR; PG8_SCHED;
;             PG8_LDA(At, 0, 1); PG8_STAGE(PG8_SB(0, 0), b2, voffB); PG8_STAGE(PG8_SB(0, 1), b2 + hstep, voffB); PG8_STAGE(PG8_SA(0, 0), a2, voffA);
;             PG8_WAIT_V(8); PG8_WAIT_L(0); PG8_BAR; PG8_MMA(1, 0, At, B0); PG8_MMA(1, 1, At, B1); PG8_BAR; PG8_SCHED;
	s_setprio 1
	s_waitcnt lgkmcnt(0)
	v_mfma_f32_16x16x32_bf16 v[142:145], v[118:121], v[162:165], v[142:145]
	v_mfma_f32_16x16x32_bf16 v[138:141], v[130:133], v[162:165], v[138:141]
	v_mfma_f32_16x16x32_bf16 v[110:113], v[118:121], v[170:173], v[110:113]
	v_mfma_f32_16x16x32_bf16 v[106:109], v[130:133], v[170:173], v[106:109]
	v_mfma_f32_16x16x32_bf16 v[94:97], v[118:121], v[178:181], v[94:97]
	v_mfma_f32_16x16x32_bf16 v[90:93], v[130:133], v[178:181], v[90:93]
	v_mfma_f32_16x16x32_bf16 v[78:81], v[118:121], v[186:189], v[78:81]
	v_mfma_f32_16x16x32_bf16 v[74:77], v[130:133], v[186:189], v[74:77]
	v_mfma_f32_16x16x32_bf16 v[142:145], v[122:125], v[166:169], v[142:145]
	v_mfma_f32_16x16x32_bf16 v[138:141], v[134:137], v[166:169], v[138:141]
	v_mfma_f32_16x16x32_bf16 v[110:113], v[122:125], v[174:177], v[110:113]
	v_mfma_f32_16x16x32_bf16 v[106:109], v[134:137], v[174:177], v[106:109]
	v_mfma_f32_16x16x32_bf16 v[94:97], v[122:125], v[182:185], v[94:97]
	v_mfma_f32_16x16x32_bf16 v[90:93], v[134:137], v[182:185], v[90:93]
	v_mfma_f32_16x16x32_bf16 v[78:81], v[122:125], v[214:217], v[78:81]
	v_mfma_f32_16x16x32_bf16 v[74:77], v[134:137], v[214:217], v[74:77]
	s_setprio 0
	s_setprio 1
	v_mfma_f32_16x16x32_bf16 v[126:129], v[146:149], v[162:165], v[126:129]
	v_mfma_f32_16x16x32_bf16 v[114:117], v[154:157], v[162:165], v[114:117]
	v_mfma_f32_16x16x32_bf16 v[102:105], v[146:149], v[170:173], v[102:105]
	v_mfma_f32_16x16x32_bf16 v[98:101], v[154:157], v[170:173], v[98:101]
	v_mfma_f32_16x16x32_bf16 v[86:89], v[146:149], v[178:181], v[86:89]
	v_mfma_f32_16x16x32_bf16 v[82:85], v[154:157], v[178:181], v[82:85]
	v_mfma_f32_16x16x32_bf16 v[70:73], v[146:149], v[186:189], v[70:73]
	v_mfma_f32_16x16x32_bf16 v[66:69], v[154:157], v[186:189], v[66:69]
	v_mfma_f32_16x16x32_bf16 v[126:129], v[150:153], v[166:169], v[126:129]
	v_mfma_f32_16x16x32_bf16 v[114:117], v[158:161], v[166:169], v[114:117]
	v_mfma_f32_16x16x32_bf16 v[102:105], v[150:153], v[174:177], v[102:105]
	v_mfma_f32_16x16x32_bf16 v[98:101], v[158:161], v[174:177], v[98:101]
	v_mfma_f32_16x16x32_bf16 v[86:89], v[150:153], v[182:185], v[86:89]
	v_mfma_f32_16x16x32_bf16 v[82:85], v[158:161], v[182:185], v[82:85]
	v_mfma_f32_16x16x32_bf16 v[70:73], v[150:153], v[214:217], v[70:73]
	v_mfma_f32_16x16x32_bf16 v[66:69], v[158:161], v[214:217], v[66:69]
	s_setprio 0
	s_barrier
	s_add_i32 s77, s77, s53
	s_mov_b32 m0, s77
	s_nop 0
	global_load_lds_dwordx4 v192, s[42:43]
	ds_read_b128 v[162:165], v222 offset:16384
	ds_read_b128 v[166:169], v222 offset:17408
	s_add_i32 m0, s77, 0x2000
	s_add_u32 s80, s42, 0x80000
	s_addc_u32 s81, s43, 0
	s_add_i32 s77, s79, s53
	global_load_lds_dwordx4 v208, s[42:43]
	ds_read_b128 v[170:173], v222 offset:18432
	ds_read_b128 v[174:177], v222 offset:19456
	s_mov_b32 m0, s77
	s_nop 0
	global_load_lds_dwordx4 v192, s[80:81]
	ds_read_b128 v[178:181], v222 offset:20480
	ds_read_b128 v[182:185], v222 offset:21504
	s_add_i32 m0, s77, 0x2000
	s_nop 0
	global_load_lds_dwordx4 v208, s[80:81]
	ds_read_b128 v[186:189], v222 offset:22528
	ds_read_b128 v[214:217], v222 offset:23552
	s_mov_b32 m0, s56
	s_nop 0
	global_load_lds_dwordx4 v190, s[44:45]
	s_mov_b32 m0, s57
	s_nop 0
	global_load_lds_dwordx4 v206, s[44:45]
	s_waitcnt vmcnt(8)
	s_waitcnt lgkmcnt(0)
	s_nop 0
	s_barrier
	s_setprio 1
	s_waitcnt lgkmcnt(0)
	v_mfma_f32_16x16x32_bf16 v[62:65], v[118:121], v[162:165], v[62:65]
	v_mfma_f32_16x16x32_bf16 v[58:61], v[130:133], v[162:165], v[58:61]
	v_mfma_f32_16x16x32_bf16 v[46:49], v[118:121], v[170:173], v[46:49]
	v_mfma_f32_16x16x32_bf16 v[42:45], v[130:133], v[170:173], v[42:45]
	v_mfma_f32_16x16x32_bf16 v[30:33], v[118:121], v[178:181], v[30:33]
	v_mfma_f32_16x16x32_bf16 v[26:29], v[130:133], v[178:181], v[26:29]
	v_mfma_f32_16x16x32_bf16 v[14:17], v[118:121], v[186:189], v[14:17]
	v_mfma_f32_16x16x32_bf16 v[10:13], v[130:133], v[186:189], v[10:13]
	v_mfma_f32_16x16x32_bf16 v[62:65], v[122:125], v[166:169], v[62:65]
	v_mfma_f32_16x16x32_bf16 v[58:61], v[134:137], v[166:169], v[58:61]
	v_mfma_f32_16x16x32_bf16 v[46:49], v[122:125], v[174:177], v[46:49]
	v_mfma_f32_16x16x32_bf16 v[42:45], v[134:137], v[174:177], v[42:45]
	v_mfma_f32_16x16x32_bf16 v[30:33], v[122:125], v[182:185], v[30:33]
	v_mfma_f32_16x16x32_bf16 v[26:29], v[134:137], v[182:185], v[26:29]
	v_mfma_f32_16x16x32_bf16 v[14:17], v[122:125], v[214:217], v[14:17]
	v_mfma_f32_16x16x32_bf16 v[10:13], v[134:137], v[214:217], v[10:13]
	s_setprio 0
	s_setprio 1
	v_mfma_f32_16x16x32_bf16 v[54:57], v[146:149], v[162:165], v[54:57]
	v_mfma_f32_16x16x32_bf16 v[50:53], v[154:157], v[162:165], v[50:53]
	v_mfma_f32_16x16x32_bf16 v[38:41], v[146:149], v[170:173], v[38:41]
	v_mfma_f32_16x16x32_bf16 v[34:37], v[154:157], v[170:173], v[34:37]
	v_mfma_f32_16x16x32_bf16 v[22:25], v[146:149], v[178:181], v[22:25]
	v_mfma_f32_16x16x32_bf16 v[18:21], v[154:157], v[178:181], v[18:21]
	v_mfma_f32_16x16x32_bf16 v[6:9], v[146:149], v[186:189], v[6:9]
	v_mfma_f32_16x16x32_bf16 v[2:5], v[154:157], v[186:189], v[2:5]
	v_mfma_f32_16x16x32_bf16 v[54:57], v[150:153], v[166:169], v[54:57]
	v_mfma_f32_16x16x32_bf16 v[50:53], v[158:161], v[166:169], v[50:53]
	v_mfma_f32_16x16x32_bf16 v[38:41], v[150:153], v[174:177], v[38:41]
	v_mfma_f32_16x16x32_bf16 v[34:37], v[158:161], v[174:177], v[34:37]
	v_mfma_f32_16x16x32_bf16 v[22:25], v[150:153], v[182:185], v[22:25]
	v_mfma_f32_16x16x32_bf16 v[18:21], v[158:161], v[182:185], v[18:21]
	v_mfma_f32_16x16x32_bf16 v[6:9], v[150:153], v[214:217], v[6:9]
	v_mfma_f32_16x16x32_bf16 v[2:5], v[158:161], v[214:217], v[2:5]
	s_setprio 0
	s_barrier
; #define PG8_STAGE(bufoff, gbase, voff) do { _Pragma("unroll") for (int _i = 0; _i < 2; ++_i) \
;         __builtin_amdgcn_global_load_lds((const unsigned*)((const char*)(gbase) + (voff)[_i]), (PG8_LAS unsigned*)(lds + (bufoff) + ldsw + _i * 8192), 16, 0, 0); } while (0)
; #define PG8_LDA(dst, b, h) do { _Pragma("unroll") for (int m = 0; m < 4; ++m) _Pragma("unroll") for (int k = 0; k < 2; ++k) dst[m][k] = *(const PG8_LAS bf16x8*)(lds + PG8_SA(b, h) + aoff + m * 2048 + k * 1024); } while (0)
; #define PG8_LDB(dst, b, h) do { _Pragma("unroll") for (int n = 0; n < 2; ++n) _Pragma("unroll") for (int k = 0; k < 2; ++k) dst[n][k] = *(const PG8_LAS bf16x8*)(lds + PG8_SB(b, h) + boff + n * 2048 + k * 1024); } while (0)
; #define PG8_MMA(ai, bj, At, Bt) do { __builtin_amdgcn_s_setprio(1); _Pragma("unroll") for (int m = 0; m < 4; ++m) _Pragma("unroll") for (int n = 0; n < 2; ++n) _Pragma("unroll") for (int k = 0; k < 2; ++k) \
;         acc[ai][bj][m][n] = __builtin_amdgcn_mfma_f32_16x16x32_bf16(Bt[n][k], At[m][k], acc[ai][bj][m][n], 0, 0, 0); __builtin_amdgcn_s_setprio(0); } while (0)
; #define PG8_WAIT_V(n) asm volatile("s_waitcnt vmcnt(" #n ")" ::: "memory")
; #define PG8_WAIT_L(n) asm volatile("s_waitcnt lgkmcnt(" #n ")" ::: "memory")
; #define PG8_BAR __builtin_amdgcn_s_barrier()
; #define PG8_SCHED __builtin_amdgcn_sched_barrier(0)
; template <class Epi, class Sched, bool ALIGN_EPI = false, bool SP2 = false>
; __device__ __forceinline__ void gemm_phase(PG8_LAS unsigned char* lds, const Gemm g, const Sched& S, const Epi& E, const int wave_id) {
;     ...
;             PG8_LDB(B0, 1, 0); PG8_LDB(B1, 1, 1); PG8_SCHED; PG8_LDA(At, 1, 0); PG8_STAGE(PG8_SA(0, 1), a2 + hstep, voffA);
;             PG8_WAIT_V(8); PG8_WAIT_L(0); PG8_BAR; PG8_MMA(0, 0, At, B0); PG8_MMA(0, 1, At, B1); PG8_BAR; PG8_SCHED;
;             PG8_LDA(At, 1, 1); PG8_STAGE(PG8_SB(1, 0), b3, voffB); PG8_STAGE(PG8_SB(1, 1), b3 + hstep, voffB); PG8_STAGE(PG8_SA(1, 0), a3, voffA);
;             PG8_WAIT_V(8); PG8_WAIT_L(0); PG8_BAR; PG8_MMA(1, 0, At, B0); PG8_MMA(1, 1, At, B1); PG8_BAR; PG8_SCHED;
	s_add_i32 s77, 0, 0x18000
	s_add_i32 s79, 0, 0x1c000
	s_add_u32 s44, s44, 0x80000
	s_addc_u32 s45, s45, 0
	s_mov_b32 m0, s64
	s_nop 0
	global_load_lds_dwordx4 v190, s[44:45]
	ds_read_b128 v[118:121], v226 offset:32768
	ds_read_b128 v[122:125], v226 offset:33792
	ds_read_b128 v[130:133], v226 offset:34816
	ds_read_b128 v[134:137], v226 offset:35840
	ds_read_b128 v[146:149], v226 offset:49152
	ds_read_b128 v[150:153], v226 offset:50176
	ds_read_b128 v[154:157], v226 offset:51200
	ds_read_b128 v[158:161], v226 offset:52224
	s_mov_b32 m0, s65
	s_nop 0
	global_load_lds_dwordx4 v206, s[44:45]
	ds_read_b128 v[162:165], v222 offset:32768
	ds_read_b128 v[166:169], v222 offset:33792
	ds_read_b128 v[170:173], v222 offset:34816
	ds_read_b128 v[174:177], v222 offset:35840
	ds_read_b128 v[178:181], v222 offset:36864
	ds_read_b128 v[182:185], v222 offset:37888
	ds_read_b128 v[186:189], v222 offset:38912
	ds_read_b128 v[214:217], v222 offset:39936
	s_waitcnt vmcnt(8)
	s_waitcnt lgkmcnt(0)
	s_barrier
	s_setprio 1
	s_waitcnt lgkmcnt(0)
	v_mfma_f32_16x16x32_bf16 v[142:145], v[118:121], v[162:165], v[142:145]
	v_mfma_f32_16x16x32_bf16 v[138:141], v[130:133], v[162:165], v[138:141]
	v_mfma_f32_16x16x32_bf16 v[110:113], v[118:121], v[170:173], v[110:113]
	v_mfma_f32_16x16x32_bf16 v[106:109], v[130:133], v[170:173], v[106:109]
	v_mfma_f32_16x16x32_bf16 v[94:97], v[118:121], v[178:181], v[94:97]
	v_mfma_f32_16x16x32_bf16 v[90:93], v[130:133], v[178:181], v[90:93]
	v_mfma_f32_16x16x32_bf16 v[78:81], v[118:121], v[186:189], v[78:81]
	v_mfma_f32_16x16x32_bf16 v[74:77], v[130:133], v[186:189], v[74:77]
	v_mfma_f32_16x16x32_bf16 v[142:145], v[122:125], v[166:169], v[142:145]
	v_mfma_f32_16x16x32_bf16 v[138:141], v[134:137], v[166:169], v[138:141]
	v_mfma_f32_16x16x32_bf16 v[110:113], v[122:125], v[174:177], v[110:113]
	v_mfma_f32_16x16x32_bf16 v[106:109], v[134:137], v[174:177], v[106:109]
	v_mfma_f32_16x16x32_bf16 v[94:97], v[122:125], v[182:185], v[94:97]
	v_mfma_f32_16x16x32_bf16 v[90:93], v[134:137], v[182:185], v[90:93]
	v_mfma_f32_16x16x32_bf16 v[78:81], v[122:125], v[214:217], v[78:81]
	v_mfma_f32_16x16x32_bf16 v[74:77], v[134:137], v[214:217], v[74:77]
	s_setprio 0
	s_setprio 1
	v_mfma_f32_16x16x32_bf16 v[126:129], v[146:149], v[162:165], v[126:129]
	v_mfma_f32_16x16x32_bf16 v[114:117], v[154:157], v[162:165], v[114:117]
	v_mfma_f32_16x16x32_bf16 v[102:105], v[146:149], v[170:173], v[102:105]
	v_mfma_f32_16x16x32_bf16 v[98:101], v[154:157], v[170:173], v[98:101]
	v_mfma_f32_16x16x32_bf16 v[86:89], v[146:149], v[178:181], v[86:89]
	v_mfma_f32_16x16x32_bf16 v[82:85], v[154:157], v[178:181], v[82:85]
	v_mfma_f32_16x16x32_bf16 v[70:73], v[146:149], v[186:189], v[70:73]
	v_mfma_f32_16x16x32_bf16 v[66:69], v[154:157], v[186:189], v[66:69]
	v_mfma_f32_16x16x32_bf16 v[126:129], v[150:153], v[166:169], v[126:129]
	v_mfma_f32_16x16x32_bf16 v[114:117], v[158:161], v[166:169], v[114:117]
	v_mfma_f32_16x16x32_bf16 v[102:105], v[150:153], v[174:177], v[102:105]
	v_mfma_f32_16x16x32_bf16 v[98:101], v[158:161], v[174:177], v[98:101]
	v_mfma_f32_16x16x32_bf16 v[86:89], v[150:153], v[182:185], v[86:89]
	v_mfma_f32_16x16x32_bf16 v[82:85], v[158:161], v[182:185], v[82:85]
	v_mfma_f32_16x16x32_bf16 v[70:73], v[150:153], v[214:217], v[70:73]
	v_mfma_f32_16x16x32_bf16 v[66:69], v[158:161], v[214:217], v[66:69]
	s_setprio 0
	s_barrier
	s_add_u32 vcc_lo, s44, 0xfff80080
	s_addc_u32 vcc_hi, s45, -1
	s_mov_b32 m0, s70
	s_nop 0
	global_load_lds_dwordx4 v190, vcc
	ds_read_b128 v[162:165], v222 offset:49152
	ds_read_b128 v[166:169], v222 offset:50176
	s_mov_b32 m0, s71
	s_add_i32 s44, s77, s53
	global_load_lds_dwordx4 v206, vcc
	ds_read_b128 v[170:173], v222 offset:51200
	ds_read_b128 v[174:177], v222 offset:52224
	s_add_u32 vcc_lo, s42, 0x80
	s_addc_u32 vcc_hi, s43, 0
	s_mov_b32 m0, s44
	s_nop 0
	global_load_lds_dwordx4 v192, vcc
	ds_read_b128 v[178:181], v222 offset:53248
	ds_read_b128 v[182:185], v222 offset:54272
	s_add_i32 m0, s44, 0x2000
	s_add_u32 s42, s42, 0x80080
	s_addc_u32 s43, s43, 0
	global_load_lds_dwordx4 v208, vcc
	ds_read_b128 v[186:189], v222 offset:55296
	ds_read_b128 v[214:217], v222 offset:56320
	s_add_i32 s44, s79, s53
	s_mov_b32 m0, s44
	s_nop 0
	global_load_lds_dwordx4 v192, s[42:43]
	s_add_i32 m0, s44, 0x2000
	s_nop 0
	global_load_lds_dwordx4 v208, s[42:43]
	s_waitcnt vmcnt(8)
	s_waitcnt lgkmcnt(0)
	s_barrier
	s_setprio 1
	s_waitcnt lgkmcnt(0)
	v_mfma_f32_16x16x32_bf16 v[62:65], v[118:121], v[162:165], v[62:65]
	v_mfma_f32_16x16x32_bf16 v[58:61], v[130:133], v[162:165], v[58:61]
	v_mfma_f32_16x16x32_bf16 v[46:49], v[118:121], v[170:173], v[46:49]
	v_mfma_f32_16x16x32_bf16 v[42:45], v[130:133], v[170:173], v[42:45]
	v_mfma_f32_16x16x32_bf16 v[30:33], v[118:121], v[178:181], v[30:33]
	v_mfma_f32_16x16x32_bf16 v[26:29], v[130:133], v[178:181], v[26:29]
	v_mfma_f32_16x16x32_bf16 v[14:17], v[118:121], v[186:189], v[14:17]
	v_mfma_f32_16x16x32_bf16 v[10:13], v[130:133], v[186:189], v[10:13]
	v_mfma_f32_16x16x32_bf16 v[62:65], v[122:125], v[166:169], v[62:65]
	v_mfma_f32_16x16x32_bf16 v[58:61], v[134:137], v[166:169], v[58:61]
	v_mfma_f32_16x16x32_bf16 v[46:49], v[122:125], v[174:177], v[46:49]
	v_mfma_f32_16x16x32_bf16 v[42:45], v[134:137], v[174:177], v[42:45]
	v_mfma_f32_16x16x32_bf16 v[30:33], v[122:125], v[182:185], v[30:33]
	v_mfma_f32_16x16x32_bf16 v[26:29], v[134:137], v[182:185], v[26:29]
	v_mfma_f32_16x16x32_bf16 v[14:17], v[122:125], v[214:217], v[14:17]
	v_mfma_f32_16x16x32_bf16 v[10:13], v[134:137], v[214:217], v[10:13]
	s_setprio 0
	s_setprio 1
	v_mfma_f32_16x16x32_bf16 v[54:57], v[146:149], v[162:165], v[54:57]
	v_mfma_f32_16x16x32_bf16 v[50:53], v[154:157], v[162:165], v[50:53]
	v_mfma_f32_16x16x32_bf16 v[38:41], v[146:149], v[170:173], v[38:41]
	v_mfma_f32_16x16x32_bf16 v[34:37], v[154:157], v[170:173], v[34:37]
	v_mfma_f32_16x16x32_bf16 v[22:25], v[146:149], v[178:181], v[22:25]
	v_mfma_f32_16x16x32_bf16 v[18:21], v[154:157], v[178:181], v[18:21]
	v_mfma_f32_16x16x32_bf16 v[6:9], v[146:149], v[186:189], v[6:9]
	v_mfma_f32_16x16x32_bf16 v[2:5], v[154:157], v[186:189], v[2:5]
	v_mfma_f32_16x16x32_bf16 v[54:57], v[150:153], v[166:169], v[54:57]
	v_mfma_f32_16x16x32_bf16 v[50:53], v[158:161], v[166:169], v[50:53]
	v_mfma_f32_16x16x32_bf16 v[38:41], v[150:153], v[174:177], v[38:41]
	v_mfma_f32_16x16x32_bf16 v[34:37], v[158:161], v[174:177], v[34:37]
	v_mfma_f32_16x16x32_bf16 v[22:25], v[150:153], v[182:185], v[22:25]
	v_mfma_f32_16x16x32_bf16 v[18:21], v[158:161], v[182:185], v[18:21]
	v_mfma_f32_16x16x32_bf16 v[6:9], v[150:153], v[214:217], v[6:9]
	v_mfma_f32_16x16x32_bf16 v[2:5], v[158:161], v[214:217], v[2:5]
	s_setprio 0
	s_barrier
	s_add_i32 s76, s76, 2
	s_add_u32 s40, s40, 0x100
	s_addc_u32 s41, s41, 0
	s_add_u32 s74, s74, 0x100
	s_addc_u32 s75, s75, 0
	s_cmp_gt_u32 s76, 29
	s_cbranch_scc0 .LBB0_524

; #define PG8_STAGE(bufoff, gbase, voff) do { _Pragma("unroll") for (int _i = 0; _i < 2; ++_i) \
;         __builtin_amdgcn_global_load_lds((const unsigned*)((const char*)(gbase) + (voff)[_i]), (PG8_LAS unsigned*)(lds + (bufoff) + ldsw + _i * 8192), 16, 0, 0); } while (0)
; #define PG8_LDA(dst, b, h) do { _Pragma("unroll") for (int m = 0; m < 4; ++m) _Pragma("unroll") for (int k = 0; k < 2; ++k) dst[m][k] = *(const PG8_LAS bf16x8*)(lds + PG8_SA(b, h) + aoff + m * 2048 + k * 1024); } while (0)
; template <class Epi, class Sched, bool ALIGN_EPI = false, bool SP2 = false>
; __device__ __forceinline__ void gemm_phase(PG8_LAS unsigned char* lds, const Gemm g, const Sched& S, const Epi& E, const int wave_id) {
;     ...
;         const char* nA = has_next ? (const char*)g.A + (size_t)nxt.lm * tstep : cA; const char* nB = has_next ? (const char*)g.Bt + (size_t)nxt.ln * tstep : cB;
; #pragma unroll 1
;         for (int t = 0; t < nt; t += 2) {
;             const bool last = (t == nt - 2);
;             const char* a1 = cA + (size_t)(t + 1) * kstep;
;             const char* a2 = last ? nA : cA + (size_t)(t + 2) * kstep; const char* b2 = last ? nB : cB + (size_t)(t + 2) * kstep;
;             const char* a3 = a2 + kstep; const char* b3 = b2 + kstep;
;             if (last && has_next) S.a_ready(nxt);
;             if constexpr (SP2) {
;             PG8_LDB(B0, 0, 0); PG8_LDB(B1, 0, 1); PG8_SCHED; PG8_LDA(At, 0, 0); PG8_STAGE(PG8_SA(1, 1), a1 + hstep, voffA);
;             PG8_WAIT_V(8); PG8_WAIT_L(0); PG8_BAR; PG8_MMA(0, 0, At, B0); PG8_MMA(0, 1, At, B1); PG8_BAR; PG8_SCHED;
;             PG8_LDA(At, 0, 1); PG8_STAGE(PG8_SB(0, 0), b2, voffB); PG8_STAGE(PG8_SB(0, 1), b2 + hstep, voffB); PG8_STAGE(PG8_SA(0, 0), a2, voffA);
;             PG8_WAIT_V(8); PG8_WAIT_L(0); PG8_BAR; PG8_MMA(1, 0, At, B0); PG8_MMA(1, 1, At, B1); PG8_BAR; PG8_SCHED;
;             PG8_LDB(B0, 1, 0); PG8_LDB(B1, 1, 1); PG8_SCHED; PG8_LDA(At, 1, 0); PG8_STAGE(PG8_SA(0, 1), a2 + hstep, voffA);
;             PG8_WAIT_V(8); PG8_WAIT_L(0); PG8_BAR; PG8_MMA(0, 0, At, B0); PG8_MMA(0, 1, At, B1); PG8_BAR; PG8_SCHED;
;             PG8_LDA(At, 1, 1); PG8_STAGE(PG8_SB(1, 0), b3, voffB); PG8_STAGE(PG8_SB(1, 1), b3 + hstep, voffB); PG8_STAGE(PG8_SA(1, 0), a3, voffA);
;             PG8_WAIT_V(8); PG8_WAIT_L(0); PG8_BAR; PG8_MMA(1, 0, At, B0); PG8_MMA(1, 1, At, B1); PG8_BAR; PG8_SCHED;
.LBB0_640:
	s_ashr_i32 s15, s14, 31
	s_lshl_b64 s[16:17], s[14:15], 20
	s_add_u32 s16, s47, s16
	s_addc_u32 s17, s48, s17
	s_and_b64 s[18:19], s[38:39], exec
	s_cselect_b32 s15, s17, s21
	s_cselect_b32 s71, s16, s20
	s_ashr_i32 s13, s12, 31
	s_lshl_b64 s[18:19], s[12:13], 20
	s_add_u32 s18, s49, s18
	s_addc_u32 s19, s52, s19
	s_and_b64 s[44:45], s[38:39], exec
	s_cselect_b32 s13, s19, s43
	s_cselect_b32 s72, s18, s42
	s_add_u32 s20, s20, 0x80080
	s_addc_u32 s21, s21, 0
	s_add_u32 s73, s42, 0x100
	s_addc_u32 s74, s43, 0
	s_mov_b32 s75, -2
	v_add_u32_e32 v144, 0x10000, v147
	s_add_u32 s42, s20, 0xfff80080
	s_addc_u32 s43, s21, -1
	s_add_i32 s76, 0, 0x10000
	s_cmp_eq_u32 s75, 28
	s_cselect_b32 s45, s15, s43
	s_cselect_b32 s44, s71, s42
	s_cselect_b32 s43, s13, s74
	s_cselect_b32 s42, s72, s73
	s_add_i32 s79, 0, 0x14000
	s_add_i32 m0, s53, 0xc000
	s_nop 0
	global_load_lds_dwordx4 v138, s[20:21]
	ds_read_b128 v[158:161], v144
	ds_read_b128 v[162:165], v144 offset:1024
	ds_read_b128 v[166:169], v144 offset:2048
	ds_read_b128 v[170:173], v144 offset:3072
	ds_read_b128 v[174:177], v144 offset:16384
	ds_read_b128 v[178:181], v144 offset:17408
	ds_read_b128 v[182:185], v144 offset:18432
	ds_read_b128 v[186:189], v144 offset:19456
	s_add_i32 m0, s53, 0xe000
	s_nop 0
	global_load_lds_dwordx4 v140, s[20:21]
	ds_read_b128 v[190:193], v155
	ds_read_b128 v[206:209], v155 offset:1024
	ds_read_b128 v[210:213], v155 offset:2048
	ds_read_b128 v[214:217], v155 offset:3072
	ds_read_b128 v[226:229], v155 offset:4096
	ds_read_b128 v[234:237], v155 offset:5120
	ds_read_b128 v[238:241], v155 offset:6144
	ds_read_b128 v[242:245], v155 offset:7168
	s_waitcnt vmcnt(8)
	s_waitcnt lgkmcnt(0)
	s_nop 0
	s_barrier
	s_setprio 1
	s_waitcnt lgkmcnt(0)
	v_mfma_f32_16x16x32_bf16 v[126:129], v[158:161], v[190:193], 0
	v_mfma_f32_16x16x32_bf16 v[118:121], v[166:169], v[190:193], 0
	v_mfma_f32_16x16x32_bf16 v[110:113], v[158:161], v[210:213], 0
	v_mfma_f32_16x16x32_bf16 v[102:105], v[166:169], v[210:213], 0
	v_mfma_f32_16x16x32_bf16 v[94:97], v[158:161], v[226:229], 0
	v_mfma_f32_16x16x32_bf16 v[86:89], v[166:169], v[226:229], 0
	v_mfma_f32_16x16x32_bf16 v[78:81], v[158:161], v[238:241], 0
	v_mfma_f32_16x16x32_bf16 v[70:73], v[166:169], v[238:241], 0
	v_mfma_f32_16x16x32_bf16 v[126:129], v[162:165], v[206:209], v[126:129]
	v_mfma_f32_16x16x32_bf16 v[118:121], v[170:173], v[206:209], v[118:121]
	v_mfma_f32_16x16x32_bf16 v[110:113], v[162:165], v[214:217], v[110:113]
	v_mfma_f32_16x16x32_bf16 v[102:105], v[170:173], v[214:217], v[102:105]
	v_mfma_f32_16x16x32_bf16 v[94:97], v[162:165], v[234:237], v[94:97]
	v_mfma_f32_16x16x32_bf16 v[86:89], v[170:173], v[234:237], v[86:89]
	v_mfma_f32_16x16x32_bf16 v[78:81], v[162:165], v[242:245], v[78:81]
	v_mfma_f32_16x16x32_bf16 v[70:73], v[170:173], v[242:245], v[70:73]
	s_setprio 0
	s_setprio 1
	v_mfma_f32_16x16x32_bf16 v[122:125], v[174:177], v[190:193], 0
	v_mfma_f32_16x16x32_bf16 v[114:117], v[182:185], v[190:193], 0
	v_mfma_f32_16x16x32_bf16 v[106:109], v[174:177], v[210:213], 0
	v_mfma_f32_16x16x32_bf16 v[98:101], v[182:185], v[210:213], 0
	v_mfma_f32_16x16x32_bf16 v[90:93], v[174:177], v[226:229], 0
	v_mfma_f32_16x16x32_bf16 v[82:85], v[182:185], v[226:229], 0
	v_mfma_f32_16x16x32_bf16 v[74:77], v[174:177], v[238:241], 0
	v_mfma_f32_16x16x32_bf16 v[66:69], v[182:185], v[238:241], 0
	v_mfma_f32_16x16x32_bf16 v[122:125], v[178:181], v[206:209], v[122:125]
	v_mfma_f32_16x16x32_bf16 v[114:117], v[186:189], v[206:209], v[114:117]
	v_mfma_f32_16x16x32_bf16 v[106:109], v[178:181], v[214:217], v[106:109]
	v_mfma_f32_16x16x32_bf16 v[98:101], v[186:189], v[214:217], v[98:101]
	v_mfma_f32_16x16x32_bf16 v[90:93], v[178:181], v[234:237], v[90:93]
	v_mfma_f32_16x16x32_bf16 v[82:85], v[186:189], v[234:237], v[82:85]
	v_mfma_f32_16x16x32_bf16 v[74:77], v[178:181], v[242:245], v[74:77]
	v_mfma_f32_16x16x32_bf16 v[66:69], v[186:189], v[242:245], v[66:69]
	s_setprio 0
	s_barrier
	s_add_i32 s76, s76, s41
	s_mov_b32 m0, s76
	s_nop 0
	global_load_lds_dwordx4 v132, s[42:43]
	ds_read_b128 v[190:193], v155 offset:16384
	ds_read_b128 v[206:209], v155 offset:17408
	s_add_i32 m0, s76, 0x2000
	s_add_u32 s76, s42, 0x80000
	s_addc_u32 s77, s43, 0
	s_add_i32 s79, s79, s41
	global_load_lds_dwordx4 v136, s[42:43]
	ds_read_b128 v[210:213], v155 offset:18432
	ds_read_b128 v[214:217], v155 offset:19456
	s_mov_b32 m0, s79
	s_nop 0
	global_load_lds_dwordx4 v132, s[76:77]
	ds_read_b128 v[226:229], v155 offset:20480
	ds_read_b128 v[234:237], v155 offset:21504
	s_add_i32 m0, s79, 0x2000
	s_nop 0
	global_load_lds_dwordx4 v136, s[76:77]
	ds_read_b128 v[238:241], v155 offset:22528
	ds_read_b128 v[242:245], v155 offset:23552
	s_mov_b32 m0, s53
	s_nop 0
	global_load_lds_dwordx4 v130, s[44:45]
	s_mov_b32 m0, s56
	s_nop 0
	global_load_lds_dwordx4 v134, s[44:45]
	s_waitcnt vmcnt(8)
	s_waitcnt lgkmcnt(0)
	s_nop 0
	s_barrier
; #define PG8_STAGE(bufoff, gbase, voff) do { _Pragma("unroll") for (int _i = 0; _i < 2; ++_i) \
;         __builtin_amdgcn_global_load_lds((const unsigned*)((const char*)(gbase) + (voff)[_i]), (PG8_LAS unsigned*)(lds + (bufoff) + ldsw + _i * 8192), 16, 0, 0); } while (0)
; #define PG8_LDA(dst, b, h) do { _Pragma("unroll") for (int m = 0; m < 4; ++m) _Pragma("unroll") for (int k = 0; k < 2; ++k) dst[m][k] = *(const PG8_LAS bf16x8*)(lds + PG8_SA(b, h) + aoff + m * 2048 + k * 1024); } while (0)
; #define PG8_LDB(dst, b, h) do { _Pragma("unroll") for (int n = 0; n < 2; ++n) _Pragma("unroll") for (int k = 0; k < 2; ++k) dst[n][k] = *(const PG8_LAS bf16x8*)(lds + PG8_SB(b, h) + boff + n * 2048 + k * 1024); } while (0)
; #define PG8_MMA(ai, bj, At, Bt) do { __builtin_amdgcn_s_setprio(1); _Pragma("unroll") for (int m = 0; m < 4; ++m) _Pragma("unroll") for (int n = 0; n < 2; ++n) _Pragma("unroll") for (int k = 0; k < 2; ++k) \
;         acc[ai][bj][m][n] = __builtin_amdgcn_mfma_f32_16x16x32_bf16(Bt[n][k], At[m][k], acc[ai][bj][m][n], 0, 0, 0); __builtin_amdgcn_s_setprio(0); } while (0)
; #define PG8_WAIT_V(n) asm volatile("s_waitcnt vmcnt(" #n ")" ::: "memory")
; #define PG8_WAIT_L(n) asm volatile("s_waitcnt lgkmcnt(" #n ")" ::: "memory")
; #define PG8_BAR __builtin_amdgcn_s_barrier()
; #define PG8_SCHED __builtin_amdgcn_sched_barrier(0)
; template <class Epi, class Sched, bool ALIGN_EPI = false, bool SP2 = false>
; __device__ __forceinline__ void gemm_phase(PG8_LAS unsigned char* lds, const Gemm g, const Sched& S, const Epi& E, const int wave_id) {
;     ...
;             PG8_WAIT_V(8); PG8_WAIT_L(0); PG8_BAR; PG8_MMA(0, 0, At, B0); PG8_MMA(0, 1, At, B1); PG8_BAR; PG8_SCHED;
;             PG8_LDA(At, 0, 1); PG8_STAGE(PG8_SB(0, 0), b2, voffB); PG8_STAGE(PG8_SB(0, 1), b2 + hstep, voffB); PG8_STAGE(PG8_SA(0, 0), a2, voffA);
;             PG8_WAIT_V(8); PG8_WAIT_L(0); PG8_BAR; PG8_MMA(1, 0, At, B0); PG8_MMA(1, 1, At, B1); PG8_BAR; PG8_SCHED;
;             PG8_LDB(B0, 1, 0); PG8_LDB(B1, 1, 1); PG8_SCHED; PG8_LDA(At, 1, 0); PG8_STAGE(PG8_SA(0, 1), a2 + hstep, voffA);
;             PG8_WAIT_V(8); PG8_WAIT_L(0); PG8_BAR; PG8_MMA(0, 0, At, B0); PG8_MMA(0, 1, At, B1); PG8_BAR; PG8_SCHED;
	s_setprio 1
	s_waitcnt lgkmcnt(0)
	v_mfma_f32_16x16x32_bf16 v[62:65], v[158:161], v[190:193], 0
	v_mfma_f32_16x16x32_bf16 v[54:57], v[166:169], v[190:193], 0
	v_mfma_f32_16x16x32_bf16 v[46:49], v[158:161], v[210:213], 0
	v_mfma_f32_16x16x32_bf16 v[38:41], v[166:169], v[210:213], 0
	v_mfma_f32_16x16x32_bf16 v[30:33], v[158:161], v[226:229], 0
	v_mfma_f32_16x16x32_bf16 v[22:25], v[166:169], v[226:229], 0
	v_mfma_f32_16x16x32_bf16 v[14:17], v[158:161], v[238:241], 0
	v_mfma_f32_16x16x32_bf16 v[6:9], v[166:169], v[238:241], 0
	v_mfma_f32_16x16x32_bf16 v[62:65], v[162:165], v[206:209], v[62:65]
	v_mfma_f32_16x16x32_bf16 v[54:57], v[170:173], v[206:209], v[54:57]
	v_mfma_f32_16x16x32_bf16 v[46:49], v[162:165], v[214:217], v[46:49]
	v_mfma_f32_16x16x32_bf16 v[38:41], v[170:173], v[214:217], v[38:41]
	v_mfma_f32_16x16x32_bf16 v[30:33], v[162:165], v[234:237], v[30:33]
	v_mfma_f32_16x16x32_bf16 v[22:25], v[170:173], v[234:237], v[22:25]
	v_mfma_f32_16x16x32_bf16 v[14:17], v[162:165], v[242:245], v[14:17]
	v_mfma_f32_16x16x32_bf16 v[6:9], v[170:173], v[242:245], v[6:9]
	s_setprio 0
	s_setprio 1
	v_mfma_f32_16x16x32_bf16 v[58:61], v[174:177], v[190:193], 0
	v_mfma_f32_16x16x32_bf16 v[50:53], v[182:185], v[190:193], 0
	v_mfma_f32_16x16x32_bf16 v[42:45], v[174:177], v[210:213], 0
	v_mfma_f32_16x16x32_bf16 v[34:37], v[182:185], v[210:213], 0
	v_mfma_f32_16x16x32_bf16 v[26:29], v[174:177], v[226:229], 0
	v_mfma_f32_16x16x32_bf16 v[18:21], v[182:185], v[226:229], 0
	v_mfma_f32_16x16x32_bf16 v[10:13], v[174:177], v[238:241], 0
	v_mfma_f32_16x16x32_bf16 v[2:5], v[182:185], v[238:241], 0
	v_mfma_f32_16x16x32_bf16 v[58:61], v[178:181], v[206:209], v[58:61]
	v_mfma_f32_16x16x32_bf16 v[50:53], v[186:189], v[206:209], v[50:53]
	v_mfma_f32_16x16x32_bf16 v[42:45], v[178:181], v[214:217], v[42:45]
	v_mfma_f32_16x16x32_bf16 v[34:37], v[186:189], v[214:217], v[34:37]
	v_mfma_f32_16x16x32_bf16 v[26:29], v[178:181], v[234:237], v[26:29]
	v_mfma_f32_16x16x32_bf16 v[18:21], v[186:189], v[234:237], v[18:21]
	v_mfma_f32_16x16x32_bf16 v[10:13], v[178:181], v[242:245], v[10:13]
	v_mfma_f32_16x16x32_bf16 v[2:5], v[186:189], v[242:245], v[2:5]
	s_setprio 0
	s_barrier
	s_add_i32 s76, 0, 0x18000
	s_add_i32 s77, 0, 0x1c000
	s_add_u32 s44, s44, 0x80000
	s_addc_u32 s45, s45, 0
	s_mov_b32 m0, s57
	s_nop 0
	global_load_lds_dwordx4 v130, s[44:45]
	ds_read_b128 v[158:161], v144 offset:32768
	ds_read_b128 v[162:165], v144 offset:33792
	ds_read_b128 v[166:169], v144 offset:34816
	ds_read_b128 v[170:173], v144 offset:35840
	ds_read_b128 v[174:177], v144 offset:49152
	ds_read_b128 v[178:181], v144 offset:50176
	ds_read_b128 v[182:185], v144 offset:51200
	ds_read_b128 v[186:189], v144 offset:52224
	s_mov_b32 m0, s64
	s_nop 0
	global_load_lds_dwordx4 v134, s[44:45]
	ds_read_b128 v[190:193], v155 offset:32768
	ds_read_b128 v[206:209], v155 offset:33792
	ds_read_b128 v[210:213], v155 offset:34816
	ds_read_b128 v[214:217], v155 offset:35840
	ds_read_b128 v[226:229], v155 offset:36864
	ds_read_b128 v[234:237], v155 offset:37888
	ds_read_b128 v[238:241], v155 offset:38912
	ds_read_b128 v[242:245], v155 offset:39936
	s_waitcnt vmcnt(8)
	s_waitcnt lgkmcnt(0)
	s_barrier
	s_setprio 1
	s_waitcnt lgkmcnt(0)
	v_mfma_f32_16x16x32_bf16 v[126:129], v[158:161], v[190:193], v[126:129]
	v_mfma_f32_16x16x32_bf16 v[118:121], v[166:169], v[190:193], v[118:121]
	v_mfma_f32_16x16x32_bf16 v[110:113], v[158:161], v[210:213], v[110:113]
	v_mfma_f32_16x16x32_bf16 v[102:105], v[166:169], v[210:213], v[102:105]
	v_mfma_f32_16x16x32_bf16 v[94:97], v[158:161], v[226:229], v[94:97]
	v_mfma_f32_16x16x32_bf16 v[86:89], v[166:169], v[226:229], v[86:89]
	v_mfma_f32_16x16x32_bf16 v[78:81], v[158:161], v[238:241], v[78:81]
	v_mfma_f32_16x16x32_bf16 v[70:73], v[166:169], v[238:241], v[70:73]
	v_mfma_f32_16x16x32_bf16 v[126:129], v[162:165], v[206:209], v[126:129]
	v_mfma_f32_16x16x32_bf16 v[118:121], v[170:173], v[206:209], v[118:121]
	v_mfma_f32_16x16x32_bf16 v[110:113], v[162:165], v[214:217], v[110:113]
	v_mfma_f32_16x16x32_bf16 v[102:105], v[170:173], v[214:217], v[102:105]
	v_mfma_f32_16x16x32_bf16 v[94:97], v[162:165], v[234:237], v[94:97]
	v_mfma_f32_16x16x32_bf16 v[86:89], v[170:173], v[234:237], v[86:89]
	v_mfma_f32_16x16x32_bf16 v[78:81], v[162:165], v[242:245], v[78:81]
	v_mfma_f32_16x16x32_bf16 v[70:73], v[170:173], v[242:245], v[70:73]
	s_setprio 0
	s_setprio 1
	v_mfma_f32_16x16x32_bf16 v[122:125], v[174:177], v[190:193], v[122:125]
	v_mfma_f32_16x16x32_bf16 v[114:117], v[182:185], v[190:193], v[114:117]
	v_mfma_f32_16x16x32_bf16 v[106:109], v[174:177], v[210:213], v[106:109]
	v_mfma_f32_16x16x32_bf16 v[98:101], v[182:185], v[210:213], v[98:101]
	v_mfma_f32_16x16x32_bf16 v[90:93], v[174:177], v[226:229], v[90:93]
	v_mfma_f32_16x16x32_bf16 v[82:85], v[182:185], v[226:229], v[82:85]
	v_mfma_f32_16x16x32_bf16 v[74:77], v[174:177], v[238:241], v[74:77]
	v_mfma_f32_16x16x32_bf16 v[66:69], v[182:185], v[238:241], v[66:69]
	v_mfma_f32_16x16x32_bf16 v[122:125], v[178:181], v[206:209], v[122:125]
	v_mfma_f32_16x16x32_bf16 v[114:117], v[186:189], v[206:209], v[114:117]
	v_mfma_f32_16x16x32_bf16 v[106:109], v[178:181], v[214:217], v[106:109]
	v_mfma_f32_16x16x32_bf16 v[98:101], v[186:189], v[214:217], v[98:101]
	v_mfma_f32_16x16x32_bf16 v[90:93], v[178:181], v[234:237], v[90:93]
	v_mfma_f32_16x16x32_bf16 v[82:85], v[186:189], v[234:237], v[82:85]
	v_mfma_f32_16x16x32_bf16 v[74:77], v[178:181], v[242:245], v[74:77]
	v_mfma_f32_16x16x32_bf16 v[66:69], v[186:189], v[242:245], v[66:69]
	s_setprio 0
	s_barrier
; #define PG8_STAGE(bufoff, gbase, voff) do { _Pragma("unroll") for (int _i = 0; _i < 2; ++_i) \
;         __builtin_amdgcn_global_load_lds((const unsigned*)((const char*)(gbase) + (voff)[_i]), (PG8_LAS unsigned*)(lds + (bufoff) + ldsw + _i * 8192), 16, 0, 0); } while (0)
; #define PG8_LDA(dst, b, h) do { _Pragma("unroll") for (int m = 0; m < 4; ++m) _Pragma("unroll") for (int k = 0; k < 2; ++k) dst[m][k] = *(const PG8_LAS bf16x8*)(lds + PG8_SA(b, h) + aoff + m * 2048 + k * 1024); } while (0)
; #define PG8_LDB(dst, b, h) do { _Pragma("unroll") for (int n = 0; n < 2; ++n) _Pragma("unroll") for (int k = 0; k < 2; ++k) dst[n][k] = *(const PG8_LAS bf16x8*)(lds + PG8_SB(b, h) + boff + n * 2048 + k * 1024); } while (0)
; #define PG8_MMA(ai, bj, At, Bt) do { __builtin_amdgcn_s_setprio(1); _Pragma("unroll") for (int m = 0; m < 4; ++m) _Pragma("unroll") for (int n = 0; n < 2; ++n) _Pragma("unroll") for (int k = 0; k < 2; ++k) \
;         acc[ai][bj][m][n] = __builtin_amdgcn_mfma_f32_16x16x32_bf16(Bt[n][k], At[m][k], acc[ai][bj][m][n], 0, 0, 0); __builtin_amdgcn_s_setprio(0); } while (0)
; #define PG8_WAIT_V(n) asm volatile("s_waitcnt vmcnt(" #n ")" ::: "memory")
; #define PG8_WAIT_L(n) asm volatile("s_waitcnt lgkmcnt(" #n ")" ::: "memory")
; #define PG8_BAR __builtin_amdgcn_s_barrier()
; template <class Epi, class Sched, bool ALIGN_EPI = false, bool SP2 = false>
; __device__ __forceinline__ void gemm_phase(PG8_LAS unsigned char* lds, const Gemm g, const Sched& S, const Epi& E, const int wave_id) {
;     ...
;         for (int t = 0; t < nt; t += 2) {
;             const bool last = (t == nt - 2);
;             const char* a1 = cA + (size_t)(t + 1) * kstep;
;             const char* a2 = last ? nA : cA + (size_t)(t + 2) * kstep; const char* b2 = last ? nB : cB + (size_t)(t + 2) * kstep;
;             const char* a3 = a2 + kstep; const char* b3 = b2 + kstep;
;     ...
;             PG8_LDB(B0, 1, 0); PG8_LDB(B1, 1, 1); PG8_SCHED; PG8_LDA(At, 1, 0); PG8_STAGE(PG8_SA(0, 1), a2 + hstep, voffA);
;             PG8_WAIT_V(8); PG8_WAIT_L(0); PG8_BAR; PG8_MMA(0, 0, At, B0); PG8_MMA(0, 1, At, B1); PG8_BAR; PG8_SCHED;
;             PG8_LDA(At, 1, 1); PG8_STAGE(PG8_SB(1, 0), b3, voffB); PG8_STAGE(PG8_SB(1, 1), b3 + hstep, voffB); PG8_STAGE(PG8_SA(1, 0), a3, voffA);
;             PG8_WAIT_V(8); PG8_WAIT_L(0); PG8_BAR; PG8_MMA(1, 0, At, B0); PG8_MMA(1, 1, At, B1); PG8_BAR; PG8_SCHED;
	s_add_u32 vcc_lo, s44, 0xfff80080
	s_addc_u32 vcc_hi, s45, -1
	s_mov_b32 m0, s65
	s_nop 0
	global_load_lds_dwordx4 v130, vcc
	ds_read_b128 v[190:193], v155 offset:49152
	ds_read_b128 v[206:209], v155 offset:50176
	s_mov_b32 m0, s68
	s_add_i32 s44, s76, s41
	global_load_lds_dwordx4 v134, vcc
	ds_read_b128 v[210:213], v155 offset:51200
	ds_read_b128 v[214:217], v155 offset:52224
	s_add_u32 vcc_lo, s42, 0x80
	s_addc_u32 vcc_hi, s43, 0
	s_mov_b32 m0, s44
	s_nop 0
	global_load_lds_dwordx4 v132, vcc
	ds_read_b128 v[226:229], v155 offset:53248
	ds_read_b128 v[234:237], v155 offset:54272
	s_add_i32 m0, s44, 0x2000
	s_add_u32 s42, s42, 0x80080
	s_addc_u32 s43, s43, 0
	global_load_lds_dwordx4 v136, vcc
	ds_read_b128 v[238:241], v155 offset:55296
	ds_read_b128 v[242:245], v155 offset:56320
	s_add_i32 s44, s77, s41
	s_mov_b32 m0, s44
	s_nop 0
	global_load_lds_dwordx4 v132, s[42:43]
	s_add_i32 m0, s44, 0x2000
	s_nop 0
	global_load_lds_dwordx4 v136, s[42:43]
	s_waitcnt vmcnt(8)
	s_waitcnt lgkmcnt(0)
	s_barrier
	s_setprio 1
	s_waitcnt lgkmcnt(0)
	v_mfma_f32_16x16x32_bf16 v[62:65], v[158:161], v[190:193], v[62:65]
	v_mfma_f32_16x16x32_bf16 v[54:57], v[166:169], v[190:193], v[54:57]
	v_mfma_f32_16x16x32_bf16 v[46:49], v[158:161], v[210:213], v[46:49]
	v_mfma_f32_16x16x32_bf16 v[38:41], v[166:169], v[210:213], v[38:41]
	v_mfma_f32_16x16x32_bf16 v[30:33], v[158:161], v[226:229], v[30:33]
	v_mfma_f32_16x16x32_bf16 v[22:25], v[166:169], v[226:229], v[22:25]
	v_mfma_f32_16x16x32_bf16 v[14:17], v[158:161], v[238:241], v[14:17]
	v_mfma_f32_16x16x32_bf16 v[6:9], v[166:169], v[238:241], v[6:9]
	v_mfma_f32_16x16x32_bf16 v[62:65], v[162:165], v[206:209], v[62:65]
	v_mfma_f32_16x16x32_bf16 v[54:57], v[170:173], v[206:209], v[54:57]
	v_mfma_f32_16x16x32_bf16 v[46:49], v[162:165], v[214:217], v[46:49]
	v_mfma_f32_16x16x32_bf16 v[38:41], v[170:173], v[214:217], v[38:41]
	v_mfma_f32_16x16x32_bf16 v[30:33], v[162:165], v[234:237], v[30:33]
	v_mfma_f32_16x16x32_bf16 v[22:25], v[170:173], v[234:237], v[22:25]
	v_mfma_f32_16x16x32_bf16 v[14:17], v[162:165], v[242:245], v[14:17]
	v_mfma_f32_16x16x32_bf16 v[6:9], v[170:173], v[242:245], v[6:9]
	s_setprio 0
	s_setprio 1
	v_mfma_f32_16x16x32_bf16 v[58:61], v[174:177], v[190:193], v[58:61]
	v_mfma_f32_16x16x32_bf16 v[50:53], v[182:185], v[190:193], v[50:53]
	v_mfma_f32_16x16x32_bf16 v[42:45], v[174:177], v[210:213], v[42:45]
	v_mfma_f32_16x16x32_bf16 v[34:37], v[182:185], v[210:213], v[34:37]
	v_mfma_f32_16x16x32_bf16 v[26:29], v[174:177], v[226:229], v[26:29]
	v_mfma_f32_16x16x32_bf16 v[18:21], v[182:185], v[226:229], v[18:21]
	v_mfma_f32_16x16x32_bf16 v[10:13], v[174:177], v[238:241], v[10:13]
	v_mfma_f32_16x16x32_bf16 v[2:5], v[182:185], v[238:241], v[2:5]
	v_mfma_f32_16x16x32_bf16 v[58:61], v[178:181], v[206:209], v[58:61]
	v_mfma_f32_16x16x32_bf16 v[50:53], v[186:189], v[206:209], v[50:53]
	v_mfma_f32_16x16x32_bf16 v[42:45], v[178:181], v[214:217], v[42:45]
	v_mfma_f32_16x16x32_bf16 v[34:37], v[186:189], v[214:217], v[34:37]
	v_mfma_f32_16x16x32_bf16 v[26:29], v[178:181], v[234:237], v[26:29]
	v_mfma_f32_16x16x32_bf16 v[18:21], v[186:189], v[234:237], v[18:21]
	v_mfma_f32_16x16x32_bf16 v[10:13], v[178:181], v[242:245], v[10:13]
	v_mfma_f32_16x16x32_bf16 v[2:5], v[186:189], v[242:245], v[2:5]
	s_setprio 0
	s_barrier
	s_add_i32 s75, s75, 2
	s_add_u32 s20, s20, 0x100
	s_addc_u32 s21, s21, 0
	s_add_u32 s73, s73, 0x100
	s_addc_u32 s74, s74, 0
	s_cmp_gt_u32 s75, 29
	s_cbranch_scc1 .Lpeel_exit_g3
.LBB0_641:
	s_add_u32 s42, s20, 0xfff80080
	s_addc_u32 s43, s21, -1
	s_add_i32 s76, 0, 0x10000
	s_cmp_eq_u32 s75, 28
	s_cselect_b32 s45, s15, s43
	s_cselect_b32 s44, s71, s42
	s_cselect_b32 s43, s13, s74
	s_cselect_b32 s42, s72, s73
	s_add_i32 s79, 0, 0x14000
	s_add_i32 m0, s53, 0xc000
	s_nop 0
	global_load_lds_dwordx4 v138, s[20:21]
	ds_read_b128 v[158:161], v144
	ds_read_b128 v[162:165], v144 offset:1024
	ds_read_b128 v[166:169], v144 offset:2048
	ds_read_b128 v[170:173], v144 offset:3072
	ds_read_b128 v[174:177], v144 offset:16384
	ds_read_b128 v[178:181], v144 offset:17408
	ds_read_b128 v[182:185], v144 offset:18432
	ds_read_b128 v[186:189], v144 offset:19456
	s_add_i32 m0, s53, 0xe000
	s_nop 0
	global_load_lds_dwordx4 v140, s[20:21]
	ds_read_b128 v[190:193], v155
	ds_read_b128 v[206:209], v155 offset:1024
	ds_read_b128 v[210:213], v155 offset:2048
	ds_read_b128 v[214:217], v155 offset:3072
	ds_read_b128 v[226:229], v155 offset:4096
	ds_read_b128 v[234:237], v155 offset:5120
	ds_read_b128 v[238:241], v155 offset:6144
	ds_read_b128 v[242:245], v155 offset:7168
	s_waitcnt vmcnt(8)
	s_waitcnt lgkmcnt(0)
	s_barrier
; #define PG8_STAGE(bufoff, gbase, voff) do { _Pragma("unroll") for (int _i = 0; _i < 2; ++_i) \
;         __builtin_amdgcn_global_load_lds((const unsigned*)((const char*)(gbase) + (voff)[_i]), (PG8_LAS unsigned*)(lds + (bufoff) + ldsw + _i * 8192), 16, 0, 0); } while (0)
; #define PG8_LDA(dst, b, h) do { _Pragma("unroll") for (int m = 0; m < 4; ++m) _Pragma("unroll") for (int k = 0; k < 2; ++k) dst[m][k] = *(const PG8_LAS bf16x8*)(lds + PG8_SA(b, h) + aoff + m * 2048 + k * 1024); } while (0)
; #define PG8_LDB(dst, b, h) do { _Pragma("unroll") for (int n = 0; n < 2; ++n) _Pragma("unroll") for (int k = 0; k < 2; ++k) dst[n][k] = *(const PG8_LAS bf16x8*)(lds + PG8_SB(b, h) + boff + n * 2048 + k * 1024); } while (0)
; #define PG8_MMA(ai, bj, At, Bt) do { __builtin_amdgcn_s_setprio(1); _Pragma("unroll") for (int m = 0; m < 4; ++m) _Pragma("unroll") for (int n = 0; n < 2; ++n) _Pragma("unroll") for (int k = 0; k < 2; ++k) \
;         acc[ai][bj][m][n] = __builtin_amdgcn_mfma_f32_16x16x32_bf16(Bt[n][k], At[m][k], acc[ai][bj][m][n], 0, 0, 0); __builtin_amdgcn_s_setprio(0); } while (0)
; #define PG8_WAIT_V(n) asm volatile("s_waitcnt vmcnt(" #n ")" ::: "memory")
; #define PG8_WAIT_L(n) asm volatile("s_waitcnt lgkmcnt(" #n ")" ::: "memory")
; #define PG8_BAR __builtin_amdgcn_s_barrier()
; #define PG8_SCHED __builtin_amdgcn_sched_barrier(0)
; template <class Epi, class Sched, bool ALIGN_EPI = false, bool SP2 = false>
; __device__ __forceinline__ void gemm_phase(PG8_LAS unsigned char* lds, const Gemm g, const Sched& S, const Epi& E, const int wave_id) {
;     ...
;             PG8_LDB(B0, 0, 0); PG8_LDB(B1, 0, 1); PG8_SCHED; PG8_LDA(At, 0, 0); PG8_STAGE(PG8_SA(1, 1), a1 + hstep, voffA);
;             PG8_WAIT_V(8); PG8_WAIT_L(0); PG8_BAR; PG8_MMA(0, 0, At, B0); PG8_MMA(0, 1, At, B1); PG8_BAR; PG8_SCHED;
;             PG8_LDA(At, 0, 1); PG8_STAGE(PG8_SB(0, 0), b2, voffB); PG8_STAGE(PG8_SB(0, 1), b2 + hstep, voffB); PG8_STAGE(PG8_SA(0, 0), a2, voffA);
;             PG8_WAIT_V(8); PG8_WAIT_L(0); PG8_BAR; PG8_MMA(1, 0, At, B0); PG8_MMA(1, 1, At, B1); PG8_BAR; PG8_SCHED;
	s_setprio 1
	s_waitcnt lgkmcnt(0)
	v_mfma_f32_16x16x32_bf16 v[126:129], v[158:161], v[190:193], v[126:129]
	v_mfma_f32_16x16x32_bf16 v[118:121], v[166:169], v[190:193], v[118:121]
	v_mfma_f32_16x16x32_bf16 v[110:113], v[158:161], v[210:213], v[110:113]
	v_mfma_f32_16x16x32_bf16 v[102:105], v[166:169], v[210:213], v[102:105]
	v_mfma_f32_16x16x32_bf16 v[94:97], v[158:161], v[226:229], v[94:97]
	v_mfma_f32_16x16x32_bf16 v[86:89], v[166:169], v[226:229], v[86:89]
	v_mfma_f32_16x16x32_bf16 v[78:81], v[158:161], v[238:241], v[78:81]
	v_mfma_f32_16x16x32_bf16 v[70:73], v[166:169], v[238:241], v[70:73]
	v_mfma_f32_16x16x32_bf16 v[126:129], v[162:165], v[206:209], v[126:129]
	v_mfma_f32_16x16x32_bf16 v[118:121], v[170:173], v[206:209], v[118:121]
	v_mfma_f32_16x16x32_bf16 v[110:113], v[162:165], v[214:217], v[110:113]
	v_mfma_f32_16x16x32_bf16 v[102:105], v[170:173], v[214:217], v[102:105]
	v_mfma_f32_16x16x32_bf16 v[94:97], v[162:165], v[234:237], v[94:97]
	v_mfma_f32_16x16x32_bf16 v[86:89], v[170:173], v[234:237], v[86:89]
	v_mfma_f32_16x16x32_bf16 v[78:81], v[162:165], v[242:245], v[78:81]
	v_mfma_f32_16x16x32_bf16 v[70:73], v[170:173], v[242:245], v[70:73]
	s_setprio 0
	s_setprio 1
	v_mfma_f32_16x16x32_bf16 v[122:125], v[174:177], v[190:193], v[122:125]
	v_mfma_f32_16x16x32_bf16 v[114:117], v[182:185], v[190:193], v[114:117]
	v_mfma_f32_16x16x32_bf16 v[106:109], v[174:177], v[210:213], v[106:109]
	v_mfma_f32_16x16x32_bf16 v[98:101], v[182:185], v[210:213], v[98:101]
	v_mfma_f32_16x16x32_bf16 v[90:93], v[174:177], v[226:229], v[90:93]
	v_mfma_f32_16x16x32_bf16 v[82:85], v[182:185], v[226:229], v[82:85]
	v_mfma_f32_16x16x32_bf16 v[74:77], v[174:177], v[238:241], v[74:77]
	v_mfma_f32_16x16x32_bf16 v[66:69], v[182:185], v[238:241], v[66:69]
	v_mfma_f32_16x16x32_bf16 v[122:125], v[178:181], v[206:209], v[122:125]
	v_mfma_f32_16x16x32_bf16 v[114:117], v[186:189], v[206:209], v[114:117]
	v_mfma_f32_16x16x32_bf16 v[106:109], v[178:181], v[214:217], v[106:109]
	v_mfma_f32_16x16x32_bf16 v[98:101], v[186:189], v[214:217], v[98:101]
	v_mfma_f32_16x16x32_bf16 v[90:93], v[178:181], v[234:237], v[90:93]
	v_mfma_f32_16x16x32_bf16 v[82:85], v[186:189], v[234:237], v[82:85]
	v_mfma_f32_16x16x32_bf16 v[74:77], v[178:181], v[242:245], v[74:77]
	v_mfma_f32_16x16x32_bf16 v[66:69], v[186:189], v[242:245], v[66:69]
	s_setprio 0
	s_barrier
	s_add_i32 s76, s76, s41
	s_mov_b32 m0, s76
	s_nop 0
	global_load_lds_dwordx4 v132, s[42:43]
	ds_read_b128 v[190:193], v155 offset:16384
	ds_read_b128 v[206:209], v155 offset:17408
	s_add_i32 m0, s76, 0x2000
	s_add_u32 s76, s42, 0x80000
	s_addc_u32 s77, s43, 0
	s_add_i32 s79, s79, s41
	global_load_lds_dwordx4 v136, s[42:43]
	ds_read_b128 v[210:213], v155 offset:18432
	ds_read_b128 v[214:217], v155 offset:19456
	s_mov_b32 m0, s79
	s_nop 0
	global_load_lds_dwordx4 v132, s[76:77]
	ds_read_b128 v[226:229], v155 offset:20480
	ds_read_b128 v[234:237], v155 offset:21504
	s_add_i32 m0, s79, 0x2000
	s_nop 0
	global_load_lds_dwordx4 v136, s[76:77]
	ds_read_b128 v[238:241], v155 offset:22528
	ds_read_b128 v[242:245], v155 offset:23552
	s_mov_b32 m0, s53
	s_nop 0
	global_load_lds_dwordx4 v130, s[44:45]
	s_mov_b32 m0, s56
	s_nop 0
	global_load_lds_dwordx4 v134, s[44:45]
	s_waitcnt vmcnt(8)
	s_waitcnt lgkmcnt(0)
	s_nop 0
	s_barrier
	s_setprio 1
	s_waitcnt lgkmcnt(0)
	v_mfma_f32_16x16x32_bf16 v[62:65], v[158:161], v[190:193], v[62:65]
	v_mfma_f32_16x16x32_bf16 v[54:57], v[166:169], v[190:193], v[54:57]
	v_mfma_f32_16x16x32_bf16 v[46:49], v[158:161], v[210:213], v[46:49]
	v_mfma_f32_16x16x32_bf16 v[38:41], v[166:169], v[210:213], v[38:41]
	v_mfma_f32_16x16x32_bf16 v[30:33], v[158:161], v[226:229], v[30:33]
	v_mfma_f32_16x16x32_bf16 v[22:25], v[166:169], v[226:229], v[22:25]
	v_mfma_f32_16x16x32_bf16 v[14:17], v[158:161], v[238:241], v[14:17]
	v_mfma_f32_16x16x32_bf16 v[6:9], v[166:169], v[238:241], v[6:9]
	v_mfma_f32_16x16x32_bf16 v[62:65], v[162:165], v[206:209], v[62:65]
	v_mfma_f32_16x16x32_bf16 v[54:57], v[170:173], v[206:209], v[54:57]
	v_mfma_f32_16x16x32_bf16 v[46:49], v[162:165], v[214:217], v[46:49]
	v_mfma_f32_16x16x32_bf16 v[38:41], v[170:173], v[214:217], v[38:41]
	v_mfma_f32_16x16x32_bf16 v[30:33], v[162:165], v[234:237], v[30:33]
	v_mfma_f32_16x16x32_bf16 v[22:25], v[170:173], v[234:237], v[22:25]
	v_mfma_f32_16x16x32_bf16 v[14:17], v[162:165], v[242:245], v[14:17]
	v_mfma_f32_16x16x32_bf16 v[6:9], v[170:173], v[242:245], v[6:9]
	s_setprio 0
	s_setprio 1
	v_mfma_f32_16x16x32_bf16 v[58:61], v[174:177], v[190:193], v[58:61]
	v_mfma_f32_16x16x32_bf16 v[50:53], v[182:185], v[190:193], v[50:53]
	v_mfma_f32_16x16x32_bf16 v[42:45], v[174:177], v[210:213], v[42:45]
	v_mfma_f32_16x16x32_bf16 v[34:37], v[182:185], v[210:213], v[34:37]
	v_mfma_f32_16x16x32_bf16 v[26:29], v[174:177], v[226:229], v[26:29]
	v_mfma_f32_16x16x32_bf16 v[18:21], v[182:185], v[226:229], v[18:21]
	v_mfma_f32_16x16x32_bf16 v[10:13], v[174:177], v[238:241], v[10:13]
	v_mfma_f32_16x16x32_bf16 v[2:5], v[182:185], v[238:241], v[2:5]
	v_mfma_f32_16x16x32_bf16 v[58:61], v[178:181], v[206:209], v[58:61]
	v_mfma_f32_16x16x32_bf16 v[50:53], v[186:189], v[206:209], v[50:53]
	v_mfma_f32_16x16x32_bf16 v[42:45], v[178:181], v[214:217], v[42:45]
	v_mfma_f32_16x16x32_bf16 v[34:37], v[186:189], v[214:217], v[34:37]
	v_mfma_f32_16x16x32_bf16 v[26:29], v[178:181], v[234:237], v[26:29]
	v_mfma_f32_16x16x32_bf16 v[18:21], v[186:189], v[234:237], v[18:21]
	v_mfma_f32_16x16x32_bf16 v[10:13], v[178:181], v[242:245], v[10:13]
	v_mfma_f32_16x16x32_bf16 v[2:5], v[186:189], v[242:245], v[2:5]
	s_setprio 0
	s_barrier
; #define PG8_STAGE(bufoff, gbase, voff) do { _Pragma("unroll") for (int _i = 0; _i < 2; ++_i) \
;         __builtin_amdgcn_global_load_lds((const unsigned*)((const char*)(gbase) + (voff)[_i]), (PG8_LAS unsigned*)(lds + (bufoff) + ldsw + _i * 8192), 16, 0, 0); } while (0)
; #define PG8_LDA(dst, b, h) do { _Pragma("unroll") for (int m = 0; m < 4; ++m) _Pragma("unroll") for (int k = 0; k < 2; ++k) dst[m][k] = *(const PG8_LAS bf16x8*)(lds + PG8_SA(b, h) + aoff + m * 2048 + k * 1024); } while (0)
; #define PG8_LDB(dst, b, h) do { _Pragma("unroll") for (int n = 0; n < 2; ++n) _Pragma("unroll") for (int k = 0; k < 2; ++k) dst[n][k] = *(const PG8_LAS bf16x8*)(lds + PG8_SB(b, h) + boff + n * 2048 + k * 1024); } while (0)
; #define PG8_MMA(ai, bj, At, Bt) do { __builtin_amdgcn_s_setprio(1); _Pragma("unroll") for (int m = 0; m < 4; ++m) _Pragma("unroll") for (int n = 0; n < 2; ++n) _Pragma("unroll") for (int k = 0; k < 2; ++k) \
;         acc[ai][bj][m][n] = __builtin_amdgcn_mfma_f32_16x16x32_bf16(Bt[n][k], At[m][k], acc[ai][bj][m][n], 0, 0, 0); __builtin_amdgcn_s_setprio(0); } while (0)
; #define PG8_WAIT_V(n) asm volatile("s_waitcnt vmcnt(" #n ")" ::: "memory")
; #define PG8_WAIT_L(n) asm volatile("s_waitcnt lgkmcnt(" #n ")" ::: "memory")
; #define PG8_BAR __builtin_amdgcn_s_barrier()
; #define PG8_SCHED __builtin_amdgcn_sched_barrier(0)
; template <class Epi, class Sched, bool ALIGN_EPI = false, bool SP2 = false>
; __device__ __forceinline__ void gemm_phase(PG8_LAS unsigned char* lds, const Gemm g, const Sched& S, const Epi& E, const int wave_id) {
;     ...
;             PG8_LDB(B0, 1, 0); PG8_LDB(B1, 1, 1); PG8_SCHED; PG8_LDA(At, 1, 0); PG8_STAGE(PG8_SA(0, 1), a2 + hstep, voffA);
;             PG8_WAIT_V(8); PG8_WAIT_L(0); PG8_BAR; PG8_MMA(0, 0, At, B0); PG8_MMA(0, 1, At, B1); PG8_BAR; PG8_SCHED;
;             PG8_LDA(At, 1, 1); PG8_STAGE(PG8_SB(1, 0), b3, voffB); PG8_STAGE(PG8_SB(1, 1), b3 + hstep, voffB); PG8_STAGE(PG8_SA(1, 0), a3, voffA);
;             PG8_WAIT_V(8); PG8_WAIT_L(0); PG8_BAR; PG8_MMA(1, 0, At, B0); PG8_MMA(1, 1, At, B1); PG8_BAR; PG8_SCHED;
	s_add_i32 s76, 0, 0x18000
	s_add_i32 s77, 0, 0x1c000
	s_add_u32 s44, s44, 0x80000
	s_addc_u32 s45, s45, 0
	s_mov_b32 m0, s57
	s_nop 0
	global_load_lds_dwordx4 v130, s[44:45]
	ds_read_b128 v[158:161], v144 offset:32768
	ds_read_b128 v[162:165], v144 offset:33792
	ds_read_b128 v[166:169], v144 offset:34816
	ds_read_b128 v[170:173], v144 offset:35840
	ds_read_b128 v[174:177], v144 offset:49152
	ds_read_b128 v[178:181], v144 offset:50176
	ds_read_b128 v[182:185], v144 offset:51200
	ds_read_b128 v[186:189], v144 offset:52224
	s_mov_b32 m0, s64
	s_nop 0
	global_load_lds_dwordx4 v134, s[44:45]
	ds_read_b128 v[190:193], v155 offset:32768
	ds_read_b128 v[206:209], v155 offset:33792
	ds_read_b128 v[210:213], v155 offset:34816
	ds_read_b128 v[214:217], v155 offset:35840
	ds_read_b128 v[226:229], v155 offset:36864
	ds_read_b128 v[234:237], v155 offset:37888
	ds_read_b128 v[238:241], v155 offset:38912
	ds_read_b128 v[242:245], v155 offset:39936
	s_waitcnt vmcnt(8)
	s_waitcnt lgkmcnt(0)
	s_barrier
	s_setprio 1
	s_waitcnt lgkmcnt(0)
	v_mfma_f32_16x16x32_bf16 v[126:129], v[158:161], v[190:193], v[126:129]
	v_mfma_f32_16x16x32_bf16 v[118:121], v[166:169], v[190:193], v[118:121]
	v_mfma_f32_16x16x32_bf16 v[110:113], v[158:161], v[210:213], v[110:113]
	v_mfma_f32_16x16x32_bf16 v[102:105], v[166:169], v[210:213], v[102:105]
	v_mfma_f32_16x16x32_bf16 v[94:97], v[158:161], v[226:229], v[94:97]
	v_mfma_f32_16x16x32_bf16 v[86:89], v[166:169], v[226:229], v[86:89]
	v_mfma_f32_16x16x32_bf16 v[78:81], v[158:161], v[238:241], v[78:81]
	v_mfma_f32_16x16x32_bf16 v[70:73], v[166:169], v[238:241], v[70:73]
	v_mfma_f32_16x16x32_bf16 v[126:129], v[162:165], v[206:209], v[126:129]
	v_mfma_f32_16x16x32_bf16 v[118:121], v[170:173], v[206:209], v[118:121]
	v_mfma_f32_16x16x32_bf16 v[110:113], v[162:165], v[214:217], v[110:113]
	v_mfma_f32_16x16x32_bf16 v[102:105], v[170:173], v[214:217], v[102:105]
	v_mfma_f32_16x16x32_bf16 v[94:97], v[162:165], v[234:237], v[94:97]
	v_mfma_f32_16x16x32_bf16 v[86:89], v[170:173], v[234:237], v[86:89]
	v_mfma_f32_16x16x32_bf16 v[78:81], v[162:165], v[242:245], v[78:81]
	v_mfma_f32_16x16x32_bf16 v[70:73], v[170:173], v[242:245], v[70:73]
	s_setprio 0
	s_setprio 1
	v_mfma_f32_16x16x32_bf16 v[122:125], v[174:177], v[190:193], v[122:125]
	v_mfma_f32_16x16x32_bf16 v[114:117], v[182:185], v[190:193], v[114:117]
	v_mfma_f32_16x16x32_bf16 v[106:109], v[174:177], v[210:213], v[106:109]
	v_mfma_f32_16x16x32_bf16 v[98:101], v[182:185], v[210:213], v[98:101]
	v_mfma_f32_16x16x32_bf16 v[90:93], v[174:177], v[226:229], v[90:93]
	v_mfma_f32_16x16x32_bf16 v[82:85], v[182:185], v[226:229], v[82:85]
	v_mfma_f32_16x16x32_bf16 v[74:77], v[174:177], v[238:241], v[74:77]
	v_mfma_f32_16x16x32_bf16 v[66:69], v[182:185], v[238:241], v[66:69]
	v_mfma_f32_16x16x32_bf16 v[122:125], v[178:181], v[206:209], v[122:125]
	v_mfma_f32_16x16x32_bf16 v[114:117], v[186:189], v[206:209], v[114:117]
	v_mfma_f32_16x16x32_bf16 v[106:109], v[178:181], v[214:217], v[106:109]
	v_mfma_f32_16x16x32_bf16 v[98:101], v[186:189], v[214:217], v[98:101]
	v_mfma_f32_16x16x32_bf16 v[90:93], v[178:181], v[234:237], v[90:93]
	v_mfma_f32_16x16x32_bf16 v[82:85], v[186:189], v[234:237], v[82:85]
	v_mfma_f32_16x16x32_bf16 v[74:77], v[178:181], v[242:245], v[74:77]
	v_mfma_f32_16x16x32_bf16 v[66:69], v[186:189], v[242:245], v[66:69]
	s_setprio 0
	s_barrier
	s_add_u32 vcc_lo, s44, 0xfff80080
	s_addc_u32 vcc_hi, s45, -1
	s_mov_b32 m0, s65
	s_nop 0
	global_load_lds_dwordx4 v130, vcc
	ds_read_b128 v[190:193], v155 offset:49152
	ds_read_b128 v[206:209], v155 offset:50176
	s_mov_b32 m0, s68
	s_add_i32 s44, s76, s41
	global_load_lds_dwordx4 v134, vcc
	ds_read_b128 v[210:213], v155 offset:51200
	ds_read_b128 v[214:217], v155 offset:52224
	s_add_u32 vcc_lo, s42, 0x80
	s_addc_u32 vcc_hi, s43, 0
	s_mov_b32 m0, s44
	s_nop 0
	global_load_lds_dwordx4 v132, vcc
	ds_read_b128 v[226:229], v155 offset:53248
	ds_read_b128 v[234:237], v155 offset:54272
	s_add_i32 m0, s44, 0x2000
	s_add_u32 s42, s42, 0x80080
	s_addc_u32 s43, s43, 0
	global_load_lds_dwordx4 v136, vcc
	ds_read_b128 v[238:241], v155 offset:55296
	ds_read_b128 v[242:245], v155 offset:56320
	s_add_i32 s44, s77, s41
	s_mov_b32 m0, s44
	s_nop 0
	global_load_lds_dwordx4 v132, s[42:43]
	s_add_i32 m0, s44, 0x2000
	s_nop 0
	global_load_lds_dwordx4 v136, s[42:43]
	s_waitcnt vmcnt(8)
	s_waitcnt lgkmcnt(0)
	s_barrier
	s_setprio 1
	s_waitcnt lgkmcnt(0)
	v_mfma_f32_16x16x32_bf16 v[62:65], v[158:161], v[190:193], v[62:65]
	v_mfma_f32_16x16x32_bf16 v[54:57], v[166:169], v[190:193], v[54:57]
	v_mfma_f32_16x16x32_bf16 v[46:49], v[158:161], v[210:213], v[46:49]
	v_mfma_f32_16x16x32_bf16 v[38:41], v[166:169], v[210:213], v[38:41]
	v_mfma_f32_16x16x32_bf16 v[30:33], v[158:161], v[226:229], v[30:33]
	v_mfma_f32_16x16x32_bf16 v[22:25], v[166:169], v[226:229], v[22:25]
	v_mfma_f32_16x16x32_bf16 v[14:17], v[158:161], v[238:241], v[14:17]
	v_mfma_f32_16x16x32_bf16 v[6:9], v[166:169], v[238:241], v[6:9]
	v_mfma_f32_16x16x32_bf16 v[62:65], v[162:165], v[206:209], v[62:65]
	v_mfma_f32_16x16x32_bf16 v[54:57], v[170:173], v[206:209], v[54:57]
	v_mfma_f32_16x16x32_bf16 v[46:49], v[162:165], v[214:217], v[46:49]
	v_mfma_f32_16x16x32_bf16 v[38:41], v[170:173], v[214:217], v[38:41]
	v_mfma_f32_16x16x32_bf16 v[30:33], v[162:165], v[234:237], v[30:33]
	v_mfma_f32_16x16x32_bf16 v[22:25], v[170:173], v[234:237], v[22:25]
	v_mfma_f32_16x16x32_bf16 v[14:17], v[162:165], v[242:245], v[14:17]
	v_mfma_f32_16x16x32_bf16 v[6:9], v[170:173], v[242:245], v[6:9]
	s_setprio 0
	s_setprio 1
	v_mfma_f32_16x16x32_bf16 v[58:61], v[174:177], v[190:193], v[58:61]
	v_mfma_f32_16x16x32_bf16 v[50:53], v[182:185], v[190:193], v[50:53]
	v_mfma_f32_16x16x32_bf16 v[42:45], v[174:177], v[210:213], v[42:45]
	v_mfma_f32_16x16x32_bf16 v[34:37], v[182:185], v[210:213], v[34:37]
	v_mfma_f32_16x16x32_bf16 v[26:29], v[174:177], v[226:229], v[26:29]
	v_mfma_f32_16x16x32_bf16 v[18:21], v[182:185], v[226:229], v[18:21]
	v_mfma_f32_16x16x32_bf16 v[10:13], v[174:177], v[238:241], v[10:13]
	v_mfma_f32_16x16x32_bf16 v[2:5], v[182:185], v[238:241], v[2:5]
	v_mfma_f32_16x16x32_bf16 v[58:61], v[178:181], v[206:209], v[58:61]
	v_mfma_f32_16x16x32_bf16 v[50:53], v[186:189], v[206:209], v[50:53]
	v_mfma_f32_16x16x32_bf16 v[42:45], v[178:181], v[214:217], v[42:45]
	v_mfma_f32_16x16x32_bf16 v[34:37], v[186:189], v[214:217], v[34:37]
	v_mfma_f32_16x16x32_bf16 v[26:29], v[178:181], v[234:237], v[26:29]
	v_mfma_f32_16x16x32_bf16 v[18:21], v[186:189], v[234:237], v[18:21]
	v_mfma_f32_16x16x32_bf16 v[10:13], v[178:181], v[242:245], v[10:13]
	v_mfma_f32_16x16x32_bf16 v[2:5], v[186:189], v[242:245], v[2:5]
	s_setprio 0
	s_barrier
	s_add_i32 s75, s75, 2
	s_add_u32 s20, s20, 0x100
	s_addc_u32 s21, s21, 0
	s_add_u32 s73, s73, 0x100
	s_addc_u32 s74, s74, 0
	s_cmp_gt_u32 s75, 29
	s_cbranch_scc0 .LBB0_641

; #define PG8_STAGE(bufoff, gbase, voff) do { _Pragma("unroll") for (int _i = 0; _i < 2; ++_i) \
;         __builtin_amdgcn_global_load_lds((const unsigned*)((const char*)(gbase) + (voff)[_i]), (PG8_LAS unsigned*)(lds + (bufoff) + ldsw + _i * 8192), 16, 0, 0); } while (0)
; #define PG8_LDA(dst, b, h) do { _Pragma("unroll") for (int m = 0; m < 4; ++m) _Pragma("unroll") for (int k = 0; k < 2; ++k) dst[m][k] = *(const PG8_LAS bf16x8*)(lds + PG8_SA(b, h) + aoff + m * 2048 + k * 1024); } while (0)
; #define PG8_LDB(dst, b, h) do { _Pragma("unroll") for (int n = 0; n < 2; ++n) _Pragma("unroll") for (int k = 0; k < 2; ++k) dst[n][k] = *(const PG8_LAS bf16x8*)(lds + PG8_SB(b, h) + boff + n * 2048 + k * 1024); } while (0)
; #define PG8_MMA(ai, bj, At, Bt) do { __builtin_amdgcn_s_setprio(1); _Pragma("unroll") for (int m = 0; m < 4; ++m) _Pragma("unroll") for (int n = 0; n < 2; ++n) _Pragma("unroll") for (int k = 0; k < 2; ++k) \
;         acc[ai][bj][m][n] = __builtin_amdgcn_mfma_f32_16x16x32_bf16(Bt[n][k], At[m][k], acc[ai][bj][m][n], 0, 0, 0); __builtin_amdgcn_s_setprio(0); } while (0)
; #define PG8_WAIT_V(n) asm volatile("s_waitcnt vmcnt(" #n ")" ::: "memory")
; #define PG8_WAIT_L(n) asm volatile("s_waitcnt lgkmcnt(" #n ")" ::: "memory")
; template <class Epi, class Sched, bool ALIGN_EPI = false, bool SP2 = false>
; __device__ __forceinline__ void gemm_phase(PG8_LAS unsigned char* lds, const Gemm g, const Sched& S, const Epi& E, const int wave_id) {
;     ...
;             const bool last = (t == nt - 2);
;             const char* a1 = cA + (size_t)(t + 1) * kstep;
;             const char* a2 = last ? nA : cA + (size_t)(t + 2) * kstep; const char* b2 = last ? nB : cB + (size_t)(t + 2) * kstep;
;             const char* a3 = a2 + kstep; const char* b3 = b2 + kstep;
;             if (last && has_next) S.a_ready(nxt);
;             if constexpr (SP2) {
;             PG8_LDB(B0, 0, 0); PG8_LDB(B1, 0, 1); PG8_SCHED; PG8_LDA(At, 0, 0); PG8_STAGE(PG8_SA(1, 1), a1 + hstep, voffA);
;             PG8_WAIT_V(8); PG8_WAIT_L(0); PG8_BAR; PG8_MMA(0, 0, At, B0); PG8_MMA(0, 1, At, B1); PG8_BAR; PG8_SCHED;
;             PG8_LDA(At, 0, 1); PG8_STAGE(PG8_SB(0, 0), b2, voffB); PG8_STAGE(PG8_SB(0, 1), b2 + hstep, voffB); PG8_STAGE(PG8_SA(0, 0), a2, voffA);
;             PG8_WAIT_V(8); PG8_WAIT_L(0); PG8_BAR; PG8_MMA(1, 0, At, B0); PG8_MMA(1, 1, At, B1); PG8_BAR; PG8_SCHED;
.LBB0_758:
	s_add_u32 s74, s20, 0x100
	s_addc_u32 s75, s21, 0
	s_mov_b32 s76, -2
	v_add_u32_e32 v226, 0x10000, v218
	s_add_u32 s20, s18, 0x100
	s_addc_u32 s21, s19, 0
	s_add_i32 s77, 0, 0x10000
	s_cmpk_eq_i32 s76, 0x54
	s_cselect_b32 s43, s15, s21
	s_cselect_b32 s42, s14, s20
	s_cselect_b32 s41, s17, s75
	s_cselect_b32 s40, s16, s74
	s_add_i32 s79, 0, 0x14000
	s_add_i32 m0, s52, 0xc000
	s_nop 0
	global_load_lds_dwordx4 v210, s[18:19]
	ds_read_b128 v[118:121], v226
	ds_read_b128 v[122:125], v226 offset:1024
	ds_read_b128 v[130:133], v226 offset:2048
	ds_read_b128 v[134:137], v226 offset:3072
	ds_read_b128 v[146:149], v226 offset:16384
	ds_read_b128 v[150:153], v226 offset:17408
	ds_read_b128 v[154:157], v226 offset:18432
	ds_read_b128 v[158:161], v226 offset:19456
	s_add_i32 m0, s52, 0xe000
	s_nop 0
	global_load_lds_dwordx4 v212, s[18:19]
	ds_read_b128 v[162:165], v222
	ds_read_b128 v[166:169], v222 offset:1024
	ds_read_b128 v[170:173], v222 offset:2048
	ds_read_b128 v[174:177], v222 offset:3072
	ds_read_b128 v[178:181], v222 offset:4096
	ds_read_b128 v[182:185], v222 offset:5120
	ds_read_b128 v[186:189], v222 offset:6144
	ds_read_b128 v[214:217], v222 offset:7168
	s_waitcnt vmcnt(8)
	s_waitcnt lgkmcnt(0)
	s_barrier
	s_setprio 1
	s_waitcnt lgkmcnt(0)
	v_mfma_f32_16x16x32_bf16 v[142:145], v[118:121], v[162:165], 0
	v_mfma_f32_16x16x32_bf16 v[138:141], v[130:133], v[162:165], 0
	v_mfma_f32_16x16x32_bf16 v[110:113], v[118:121], v[170:173], 0
	v_mfma_f32_16x16x32_bf16 v[106:109], v[130:133], v[170:173], 0
	v_mfma_f32_16x16x32_bf16 v[94:97], v[118:121], v[178:181], 0
	v_mfma_f32_16x16x32_bf16 v[90:93], v[130:133], v[178:181], 0
	v_mfma_f32_16x16x32_bf16 v[78:81], v[118:121], v[186:189], 0
	v_mfma_f32_16x16x32_bf16 v[74:77], v[130:133], v[186:189], 0
	v_mfma_f32_16x16x32_bf16 v[142:145], v[122:125], v[166:169], v[142:145]
	v_mfma_f32_16x16x32_bf16 v[138:141], v[134:137], v[166:169], v[138:141]
	v_mfma_f32_16x16x32_bf16 v[110:113], v[122:125], v[174:177], v[110:113]
	v_mfma_f32_16x16x32_bf16 v[106:109], v[134:137], v[174:177], v[106:109]
	v_mfma_f32_16x16x32_bf16 v[94:97], v[122:125], v[182:185], v[94:97]
	v_mfma_f32_16x16x32_bf16 v[90:93], v[134:137], v[182:185], v[90:93]
	v_mfma_f32_16x16x32_bf16 v[78:81], v[122:125], v[214:217], v[78:81]
	v_mfma_f32_16x16x32_bf16 v[74:77], v[134:137], v[214:217], v[74:77]
	s_setprio 0
	s_setprio 1
	v_mfma_f32_16x16x32_bf16 v[126:129], v[146:149], v[162:165], 0
	v_mfma_f32_16x16x32_bf16 v[114:117], v[154:157], v[162:165], 0
	v_mfma_f32_16x16x32_bf16 v[102:105], v[146:149], v[170:173], 0
	v_mfma_f32_16x16x32_bf16 v[98:101], v[154:157], v[170:173], 0
	v_mfma_f32_16x16x32_bf16 v[86:89], v[146:149], v[178:181], 0
	v_mfma_f32_16x16x32_bf16 v[82:85], v[154:157], v[178:181], 0
	v_mfma_f32_16x16x32_bf16 v[70:73], v[146:149], v[186:189], 0
	v_mfma_f32_16x16x32_bf16 v[66:69], v[154:157], v[186:189], 0
	v_mfma_f32_16x16x32_bf16 v[126:129], v[150:153], v[166:169], v[126:129]
	v_mfma_f32_16x16x32_bf16 v[114:117], v[158:161], v[166:169], v[114:117]
	v_mfma_f32_16x16x32_bf16 v[102:105], v[150:153], v[174:177], v[102:105]
	v_mfma_f32_16x16x32_bf16 v[98:101], v[158:161], v[174:177], v[98:101]
	v_mfma_f32_16x16x32_bf16 v[86:89], v[150:153], v[182:185], v[86:89]
	v_mfma_f32_16x16x32_bf16 v[82:85], v[158:161], v[182:185], v[82:85]
	v_mfma_f32_16x16x32_bf16 v[70:73], v[150:153], v[214:217], v[70:73]
	v_mfma_f32_16x16x32_bf16 v[66:69], v[158:161], v[214:217], v[66:69]
	s_setprio 0
	s_barrier
	s_add_i32 s18, s77, s49
	s_mov_b32 m0, s18
	s_nop 0
	global_load_lds_dwordx4 v192, s[40:41]
	ds_read_b128 v[162:165], v222 offset:16384
	ds_read_b128 v[166:169], v222 offset:17408
	s_add_i32 m0, s18, 0x2000
	s_add_u32 s18, s40, 0x160000
	s_addc_u32 s19, s41, 0
	s_add_i32 s77, s79, s49
	global_load_lds_dwordx4 v208, s[40:41]
	ds_read_b128 v[170:173], v222 offset:18432
	ds_read_b128 v[174:177], v222 offset:19456
	s_mov_b32 m0, s77
	s_nop 0
	global_load_lds_dwordx4 v192, s[18:19]
	ds_read_b128 v[178:181], v222 offset:20480
	ds_read_b128 v[182:185], v222 offset:21504
	s_add_i32 m0, s77, 0x2000
	s_nop 0
	global_load_lds_dwordx4 v208, s[18:19]
	ds_read_b128 v[186:189], v222 offset:22528
	ds_read_b128 v[214:217], v222 offset:23552
	s_mov_b32 m0, s52
	s_nop 0
	global_load_lds_dwordx4 v190, s[42:43]
	s_mov_b32 m0, s53
	s_nop 0
	global_load_lds_dwordx4 v206, s[42:43]
	s_waitcnt vmcnt(8)
	s_waitcnt lgkmcnt(0)
	s_nop 0
	s_barrier
	s_setprio 1
	s_waitcnt lgkmcnt(0)
	v_mfma_f32_16x16x32_bf16 v[62:65], v[118:121], v[162:165], 0
	v_mfma_f32_16x16x32_bf16 v[58:61], v[130:133], v[162:165], 0
	v_mfma_f32_16x16x32_bf16 v[46:49], v[118:121], v[170:173], 0
	v_mfma_f32_16x16x32_bf16 v[42:45], v[130:133], v[170:173], 0
	v_mfma_f32_16x16x32_bf16 v[30:33], v[118:121], v[178:181], 0
	v_mfma_f32_16x16x32_bf16 v[26:29], v[130:133], v[178:181], 0
	v_mfma_f32_16x16x32_bf16 v[14:17], v[118:121], v[186:189], 0
	v_mfma_f32_16x16x32_bf16 v[10:13], v[130:133], v[186:189], 0
	v_mfma_f32_16x16x32_bf16 v[62:65], v[122:125], v[166:169], v[62:65]
	v_mfma_f32_16x16x32_bf16 v[58:61], v[134:137], v[166:169], v[58:61]
	v_mfma_f32_16x16x32_bf16 v[46:49], v[122:125], v[174:177], v[46:49]
	v_mfma_f32_16x16x32_bf16 v[42:45], v[134:137], v[174:177], v[42:45]
	v_mfma_f32_16x16x32_bf16 v[30:33], v[122:125], v[182:185], v[30:33]
	v_mfma_f32_16x16x32_bf16 v[26:29], v[134:137], v[182:185], v[26:29]
	v_mfma_f32_16x16x32_bf16 v[14:17], v[122:125], v[214:217], v[14:17]
	v_mfma_f32_16x16x32_bf16 v[10:13], v[134:137], v[214:217], v[10:13]
	s_setprio 0
	s_setprio 1
	v_mfma_f32_16x16x32_bf16 v[54:57], v[146:149], v[162:165], 0
	v_mfma_f32_16x16x32_bf16 v[50:53], v[154:157], v[162:165], 0
	v_mfma_f32_16x16x32_bf16 v[38:41], v[146:149], v[170:173], 0
	v_mfma_f32_16x16x32_bf16 v[34:37], v[154:157], v[170:173], 0
	v_mfma_f32_16x16x32_bf16 v[22:25], v[146:149], v[178:181], 0
	v_mfma_f32_16x16x32_bf16 v[18:21], v[154:157], v[178:181], 0
	v_mfma_f32_16x16x32_bf16 v[6:9], v[146:149], v[186:189], 0
	v_mfma_f32_16x16x32_bf16 v[2:5], v[154:157], v[186:189], 0
	v_mfma_f32_16x16x32_bf16 v[54:57], v[150:153], v[166:169], v[54:57]
	v_mfma_f32_16x16x32_bf16 v[50:53], v[158:161], v[166:169], v[50:53]
	v_mfma_f32_16x16x32_bf16 v[38:41], v[150:153], v[174:177], v[38:41]
	v_mfma_f32_16x16x32_bf16 v[34:37], v[158:161], v[174:177], v[34:37]
	v_mfma_f32_16x16x32_bf16 v[22:25], v[150:153], v[182:185], v[22:25]
	v_mfma_f32_16x16x32_bf16 v[18:21], v[158:161], v[182:185], v[18:21]
	v_mfma_f32_16x16x32_bf16 v[6:9], v[150:153], v[214:217], v[6:9]
	v_mfma_f32_16x16x32_bf16 v[2:5], v[158:161], v[214:217], v[2:5]
	s_setprio 0
	s_barrier
; #define PG8_STAGE(bufoff, gbase, voff) do { _Pragma("unroll") for (int _i = 0; _i < 2; ++_i) \
;         __builtin_amdgcn_global_load_lds((const unsigned*)((const char*)(gbase) + (voff)[_i]), (PG8_LAS unsigned*)(lds + (bufoff) + ldsw + _i * 8192), 16, 0, 0); } while (0)
; #define PG8_LDA(dst, b, h) do { _Pragma("unroll") for (int m = 0; m < 4; ++m) _Pragma("unroll") for (int k = 0; k < 2; ++k) dst[m][k] = *(const PG8_LAS bf16x8*)(lds + PG8_SA(b, h) + aoff + m * 2048 + k * 1024); } while (0)
; #define PG8_LDB(dst, b, h) do { _Pragma("unroll") for (int n = 0; n < 2; ++n) _Pragma("unroll") for (int k = 0; k < 2; ++k) dst[n][k] = *(const PG8_LAS bf16x8*)(lds + PG8_SB(b, h) + boff + n * 2048 + k * 1024); } while (0)
; #define PG8_MMA(ai, bj, At, Bt) do { __builtin_amdgcn_s_setprio(1); _Pragma("unroll") for (int m = 0; m < 4; ++m) _Pragma("unroll") for (int n = 0; n < 2; ++n) _Pragma("unroll") for (int k = 0; k < 2; ++k) \
;         acc[ai][bj][m][n] = __builtin_amdgcn_mfma_f32_16x16x32_bf16(Bt[n][k], At[m][k], acc[ai][bj][m][n], 0, 0, 0); __builtin_amdgcn_s_setprio(0); } while (0)
; #define PG8_WAIT_V(n) asm volatile("s_waitcnt vmcnt(" #n ")" ::: "memory")
; #define PG8_WAIT_L(n) asm volatile("s_waitcnt lgkmcnt(" #n ")" ::: "memory")
; #define PG8_BAR __builtin_amdgcn_s_barrier()
; #define PG8_SCHED __builtin_amdgcn_sched_barrier(0)
; template <class Epi, class Sched, bool ALIGN_EPI = false, bool SP2 = false>
; __device__ __forceinline__ void gemm_phase(PG8_LAS unsigned char* lds, const Gemm g, const Sched& S, const Epi& E, const int wave_id) {
;     ...
;             PG8_LDB(B0, 1, 0); PG8_LDB(B1, 1, 1); PG8_SCHED; PG8_LDA(At, 1, 0); PG8_STAGE(PG8_SA(0, 1), a2 + hstep, voffA);
;             PG8_WAIT_V(8); PG8_WAIT_L(0); PG8_BAR; PG8_MMA(0, 0, At, B0); PG8_MMA(0, 1, At, B1); PG8_BAR; PG8_SCHED;
;             PG8_LDA(At, 1, 1); PG8_STAGE(PG8_SB(1, 0), b3, voffB); PG8_STAGE(PG8_SB(1, 1), b3 + hstep, voffB); PG8_STAGE(PG8_SA(1, 0), a3, voffA);
;             PG8_WAIT_V(8); PG8_WAIT_L(0); PG8_BAR; PG8_MMA(1, 0, At, B0); PG8_MMA(1, 1, At, B1); PG8_BAR; PG8_SCHED;
	s_add_i32 s77, 0, 0x18000
	s_add_i32 s79, 0, 0x1c000
	s_add_u32 s18, s42, 0x160000
	s_addc_u32 s19, s43, 0
	s_mov_b32 m0, s56
	s_nop 0
	global_load_lds_dwordx4 v190, s[18:19]
	ds_read_b128 v[118:121], v226 offset:32768
	ds_read_b128 v[122:125], v226 offset:33792
	ds_read_b128 v[130:133], v226 offset:34816
	ds_read_b128 v[134:137], v226 offset:35840
	ds_read_b128 v[146:149], v226 offset:49152
	ds_read_b128 v[150:153], v226 offset:50176
	ds_read_b128 v[154:157], v226 offset:51200
	ds_read_b128 v[158:161], v226 offset:52224
	s_mov_b32 m0, s57
	s_nop 0
	global_load_lds_dwordx4 v206, s[18:19]
	ds_read_b128 v[162:165], v222 offset:32768
	ds_read_b128 v[166:169], v222 offset:33792
	ds_read_b128 v[170:173], v222 offset:34816
	ds_read_b128 v[174:177], v222 offset:35840
	ds_read_b128 v[178:181], v222 offset:36864
	ds_read_b128 v[182:185], v222 offset:37888
	ds_read_b128 v[186:189], v222 offset:38912
	ds_read_b128 v[214:217], v222 offset:39936
	s_waitcnt vmcnt(8)
	s_waitcnt lgkmcnt(0)
	s_barrier
	s_setprio 1
	s_waitcnt lgkmcnt(0)
	v_mfma_f32_16x16x32_bf16 v[142:145], v[118:121], v[162:165], v[142:145]
	v_mfma_f32_16x16x32_bf16 v[138:141], v[130:133], v[162:165], v[138:141]
	v_mfma_f32_16x16x32_bf16 v[110:113], v[118:121], v[170:173], v[110:113]
	v_mfma_f32_16x16x32_bf16 v[106:109], v[130:133], v[170:173], v[106:109]
	v_mfma_f32_16x16x32_bf16 v[94:97], v[118:121], v[178:181], v[94:97]
	v_mfma_f32_16x16x32_bf16 v[90:93], v[130:133], v[178:181], v[90:93]
	v_mfma_f32_16x16x32_bf16 v[78:81], v[118:121], v[186:189], v[78:81]
	v_mfma_f32_16x16x32_bf16 v[74:77], v[130:133], v[186:189], v[74:77]
	v_mfma_f32_16x16x32_bf16 v[142:145], v[122:125], v[166:169], v[142:145]
	v_mfma_f32_16x16x32_bf16 v[138:141], v[134:137], v[166:169], v[138:141]
	v_mfma_f32_16x16x32_bf16 v[110:113], v[122:125], v[174:177], v[110:113]
	v_mfma_f32_16x16x32_bf16 v[106:109], v[134:137], v[174:177], v[106:109]
	v_mfma_f32_16x16x32_bf16 v[94:97], v[122:125], v[182:185], v[94:97]
	v_mfma_f32_16x16x32_bf16 v[90:93], v[134:137], v[182:185], v[90:93]
	v_mfma_f32_16x16x32_bf16 v[78:81], v[122:125], v[214:217], v[78:81]
	v_mfma_f32_16x16x32_bf16 v[74:77], v[134:137], v[214:217], v[74:77]
	s_setprio 0
	s_setprio 1
	v_mfma_f32_16x16x32_bf16 v[126:129], v[146:149], v[162:165], v[126:129]
	v_mfma_f32_16x16x32_bf16 v[114:117], v[154:157], v[162:165], v[114:117]
	v_mfma_f32_16x16x32_bf16 v[102:105], v[146:149], v[170:173], v[102:105]
	v_mfma_f32_16x16x32_bf16 v[98:101], v[154:157], v[170:173], v[98:101]
	v_mfma_f32_16x16x32_bf16 v[86:89], v[146:149], v[178:181], v[86:89]
	v_mfma_f32_16x16x32_bf16 v[82:85], v[154:157], v[178:181], v[82:85]
	v_mfma_f32_16x16x32_bf16 v[70:73], v[146:149], v[186:189], v[70:73]
	v_mfma_f32_16x16x32_bf16 v[66:69], v[154:157], v[186:189], v[66:69]
	v_mfma_f32_16x16x32_bf16 v[126:129], v[150:153], v[166:169], v[126:129]
	v_mfma_f32_16x16x32_bf16 v[114:117], v[158:161], v[166:169], v[114:117]
	v_mfma_f32_16x16x32_bf16 v[102:105], v[150:153], v[174:177], v[102:105]
	v_mfma_f32_16x16x32_bf16 v[98:101], v[158:161], v[174:177], v[98:101]
	v_mfma_f32_16x16x32_bf16 v[86:89], v[150:153], v[182:185], v[86:89]
	v_mfma_f32_16x16x32_bf16 v[82:85], v[158:161], v[182:185], v[82:85]
	v_mfma_f32_16x16x32_bf16 v[70:73], v[150:153], v[214:217], v[70:73]
	v_mfma_f32_16x16x32_bf16 v[66:69], v[158:161], v[214:217], v[66:69]
	s_setprio 0
	s_barrier
	s_add_u32 vcc_lo, s42, 0x80
	s_addc_u32 vcc_hi, s43, 0
	s_mov_b32 m0, s68
	s_nop 0
	global_load_lds_dwordx4 v190, vcc
	ds_read_b128 v[162:165], v222 offset:49152
	ds_read_b128 v[166:169], v222 offset:50176
	s_mov_b32 m0, s69
	s_add_i32 s18, s77, s49
	global_load_lds_dwordx4 v206, vcc
	ds_read_b128 v[170:173], v222 offset:51200
	ds_read_b128 v[174:177], v222 offset:52224
	s_add_u32 vcc_lo, s40, 0x80
	s_addc_u32 vcc_hi, s41, 0
	s_mov_b32 m0, s18
	s_nop 0
	global_load_lds_dwordx4 v192, vcc
	ds_read_b128 v[178:181], v222 offset:53248
	ds_read_b128 v[182:185], v222 offset:54272
	s_add_i32 m0, s18, 0x2000
	s_add_u32 s18, s40, 0x160080
	s_addc_u32 s19, s41, 0
	global_load_lds_dwordx4 v208, vcc
	ds_read_b128 v[186:189], v222 offset:55296
	ds_read_b128 v[214:217], v222 offset:56320
	s_add_i32 s40, s79, s49
	s_mov_b32 m0, s40
	s_nop 0
	global_load_lds_dwordx4 v192, s[18:19]
	s_add_i32 m0, s40, 0x2000
	s_nop 0
	global_load_lds_dwordx4 v208, s[18:19]
	s_waitcnt vmcnt(8)
	s_waitcnt lgkmcnt(0)
	s_barrier
	s_setprio 1
	s_waitcnt lgkmcnt(0)
	v_mfma_f32_16x16x32_bf16 v[62:65], v[118:121], v[162:165], v[62:65]
	v_mfma_f32_16x16x32_bf16 v[58:61], v[130:133], v[162:165], v[58:61]
	v_mfma_f32_16x16x32_bf16 v[46:49], v[118:121], v[170:173], v[46:49]
	v_mfma_f32_16x16x32_bf16 v[42:45], v[130:133], v[170:173], v[42:45]
	v_mfma_f32_16x16x32_bf16 v[30:33], v[118:121], v[178:181], v[30:33]
	v_mfma_f32_16x16x32_bf16 v[26:29], v[130:133], v[178:181], v[26:29]
	v_mfma_f32_16x16x32_bf16 v[14:17], v[118:121], v[186:189], v[14:17]
	v_mfma_f32_16x16x32_bf16 v[10:13], v[130:133], v[186:189], v[10:13]
	v_mfma_f32_16x16x32_bf16 v[62:65], v[122:125], v[166:169], v[62:65]
	v_mfma_f32_16x16x32_bf16 v[58:61], v[134:137], v[166:169], v[58:61]
	v_mfma_f32_16x16x32_bf16 v[46:49], v[122:125], v[174:177], v[46:49]
	v_mfma_f32_16x16x32_bf16 v[42:45], v[134:137], v[174:177], v[42:45]
	v_mfma_f32_16x16x32_bf16 v[30:33], v[122:125], v[182:185], v[30:33]
	v_mfma_f32_16x16x32_bf16 v[26:29], v[134:137], v[182:185], v[26:29]
	v_mfma_f32_16x16x32_bf16 v[14:17], v[122:125], v[214:217], v[14:17]
	v_mfma_f32_16x16x32_bf16 v[10:13], v[134:137], v[214:217], v[10:13]
	s_setprio 0
	s_setprio 1
	v_mfma_f32_16x16x32_bf16 v[54:57], v[146:149], v[162:165], v[54:57]
	v_mfma_f32_16x16x32_bf16 v[50:53], v[154:157], v[162:165], v[50:53]
	v_mfma_f32_16x16x32_bf16 v[38:41], v[146:149], v[170:173], v[38:41]
	v_mfma_f32_16x16x32_bf16 v[34:37], v[154:157], v[170:173], v[34:37]
	v_mfma_f32_16x16x32_bf16 v[22:25], v[146:149], v[178:181], v[22:25]
	v_mfma_f32_16x16x32_bf16 v[18:21], v[154:157], v[178:181], v[18:21]
	v_mfma_f32_16x16x32_bf16 v[6:9], v[146:149], v[186:189], v[6:9]
	v_mfma_f32_16x16x32_bf16 v[2:5], v[154:157], v[186:189], v[2:5]
	v_mfma_f32_16x16x32_bf16 v[54:57], v[150:153], v[166:169], v[54:57]
	v_mfma_f32_16x16x32_bf16 v[50:53], v[158:161], v[166:169], v[50:53]
	v_mfma_f32_16x16x32_bf16 v[38:41], v[150:153], v[174:177], v[38:41]
	v_mfma_f32_16x16x32_bf16 v[34:37], v[158:161], v[174:177], v[34:37]
	v_mfma_f32_16x16x32_bf16 v[22:25], v[150:153], v[182:185], v[22:25]
	v_mfma_f32_16x16x32_bf16 v[18:21], v[158:161], v[182:185], v[18:21]
	v_mfma_f32_16x16x32_bf16 v[6:9], v[150:153], v[214:217], v[6:9]
	v_mfma_f32_16x16x32_bf16 v[2:5], v[158:161], v[214:217], v[2:5]
	s_setprio 0
	s_barrier
	s_add_i32 s76, s76, 2
	s_add_u32 s74, s74, 0x100
	s_addc_u32 s75, s75, 0
	s_cmpk_gt_u32 s76, 0x55
	s_mov_b64 s[18:19], s[20:21]
	s_cbranch_scc1 .Lpeel_exit_g4
; #define PG8_STAGE(bufoff, gbase, voff) do { _Pragma("unroll") for (int _i = 0; _i < 2; ++_i) \
;         __builtin_amdgcn_global_load_lds((const unsigned*)((const char*)(gbase) + (voff)[_i]), (PG8_LAS unsigned*)(lds + (bufoff) + ldsw + _i * 8192), 16, 0, 0); } while (0)
; #define PG8_LDA(dst, b, h) do { _Pragma("unroll") for (int m = 0; m < 4; ++m) _Pragma("unroll") for (int k = 0; k < 2; ++k) dst[m][k] = *(const PG8_LAS bf16x8*)(lds + PG8_SA(b, h) + aoff + m * 2048 + k * 1024); } while (0)
; #define PG8_LDB(dst, b, h) do { _Pragma("unroll") for (int n = 0; n < 2; ++n) _Pragma("unroll") for (int k = 0; k < 2; ++k) dst[n][k] = *(const PG8_LAS bf16x8*)(lds + PG8_SB(b, h) + boff + n * 2048 + k * 1024); } while (0)
; #define PG8_MMA(ai, bj, At, Bt) do { __builtin_amdgcn_s_setprio(1); _Pragma("unroll") for (int m = 0; m < 4; ++m) _Pragma("unroll") for (int n = 0; n < 2; ++n) _Pragma("unroll") for (int k = 0; k < 2; ++k) \
;         acc[ai][bj][m][n] = __builtin_amdgcn_mfma_f32_16x16x32_bf16(Bt[n][k], At[m][k], acc[ai][bj][m][n], 0, 0, 0); __builtin_amdgcn_s_setprio(0); } while (0)
; #define PG8_WAIT_V(n) asm volatile("s_waitcnt vmcnt(" #n ")" ::: "memory")
; #define PG8_WAIT_L(n) asm volatile("s_waitcnt lgkmcnt(" #n ")" ::: "memory")
; template <class Epi, class Sched, bool ALIGN_EPI = false, bool SP2 = false>
; __device__ __forceinline__ void gemm_phase(PG8_LAS unsigned char* lds, const Gemm g, const Sched& S, const Epi& E, const int wave_id) {
;     ...
;             const bool last = (t == nt - 2);
;             const char* a1 = cA + (size_t)(t + 1) * kstep;
;             const char* a2 = last ? nA : cA + (size_t)(t + 2) * kstep; const char* b2 = last ? nB : cB + (size_t)(t + 2) * kstep;
;             const char* a3 = a2 + kstep; const char* b3 = b2 + kstep;
;             if (last && has_next) S.a_ready(nxt);
;             if constexpr (SP2) {
;             PG8_LDB(B0, 0, 0); PG8_LDB(B1, 0, 1); PG8_SCHED; PG8_LDA(At, 0, 0); PG8_STAGE(PG8_SA(1, 1), a1 + hstep, voffA);
;             PG8_WAIT_V(8); PG8_WAIT_L(0); PG8_BAR; PG8_MMA(0, 0, At, B0); PG8_MMA(0, 1, At, B1); PG8_BAR; PG8_SCHED;
;             PG8_LDA(At, 0, 1); PG8_STAGE(PG8_SB(0, 0), b2, voffB); PG8_STAGE(PG8_SB(0, 1), b2 + hstep, voffB); PG8_STAGE(PG8_SA(0, 0), a2, voffA);
;             PG8_WAIT_V(8); PG8_WAIT_L(0); PG8_BAR; PG8_MMA(1, 0, At, B0); PG8_MMA(1, 1, At, B1); PG8_BAR; PG8_SCHED;
.LBB0_759:
	s_add_u32 s20, s18, 0x100
	s_addc_u32 s21, s19, 0
	s_add_i32 s77, 0, 0x10000
	s_cmpk_eq_i32 s76, 0x54
	s_cselect_b32 s43, s15, s21
	s_cselect_b32 s42, s14, s20
	s_cselect_b32 s41, s17, s75
	s_cselect_b32 s40, s16, s74
	s_add_i32 s79, 0, 0x14000
	s_add_i32 m0, s52, 0xc000
	s_nop 0
	global_load_lds_dwordx4 v210, s[18:19]
	ds_read_b128 v[118:121], v226
	ds_read_b128 v[122:125], v226 offset:1024
	ds_read_b128 v[130:133], v226 offset:2048
	ds_read_b128 v[134:137], v226 offset:3072
	ds_read_b128 v[146:149], v226 offset:16384
	ds_read_b128 v[150:153], v226 offset:17408
	ds_read_b128 v[154:157], v226 offset:18432
	ds_read_b128 v[158:161], v226 offset:19456
	s_add_i32 m0, s52, 0xe000
	s_nop 0
	global_load_lds_dwordx4 v212, s[18:19]
	ds_read_b128 v[162:165], v222
	ds_read_b128 v[166:169], v222 offset:1024
	ds_read_b128 v[170:173], v222 offset:2048
	ds_read_b128 v[174:177], v222 offset:3072
	ds_read_b128 v[178:181], v222 offset:4096
	ds_read_b128 v[182:185], v222 offset:5120
	ds_read_b128 v[186:189], v222 offset:6144
	ds_read_b128 v[214:217], v222 offset:7168
	s_waitcnt vmcnt(8)
	s_waitcnt lgkmcnt(0)
	s_barrier
	s_setprio 1
	s_waitcnt lgkmcnt(0)
	v_mfma_f32_16x16x32_bf16 v[142:145], v[118:121], v[162:165], v[142:145]
	v_mfma_f32_16x16x32_bf16 v[138:141], v[130:133], v[162:165], v[138:141]
	v_mfma_f32_16x16x32_bf16 v[110:113], v[118:121], v[170:173], v[110:113]
	v_mfma_f32_16x16x32_bf16 v[106:109], v[130:133], v[170:173], v[106:109]
	v_mfma_f32_16x16x32_bf16 v[94:97], v[118:121], v[178:181], v[94:97]
	v_mfma_f32_16x16x32_bf16 v[90:93], v[130:133], v[178:181], v[90:93]
	v_mfma_f32_16x16x32_bf16 v[78:81], v[118:121], v[186:189], v[78:81]
	v_mfma_f32_16x16x32_bf16 v[74:77], v[130:133], v[186:189], v[74:77]
	v_mfma_f32_16x16x32_bf16 v[142:145], v[122:125], v[166:169], v[142:145]
	v_mfma_f32_16x16x32_bf16 v[138:141], v[134:137], v[166:169], v[138:141]
	v_mfma_f32_16x16x32_bf16 v[110:113], v[122:125], v[174:177], v[110:113]
	v_mfma_f32_16x16x32_bf16 v[106:109], v[134:137], v[174:177], v[106:109]
	v_mfma_f32_16x16x32_bf16 v[94:97], v[122:125], v[182:185], v[94:97]
	v_mfma_f32_16x16x32_bf16 v[90:93], v[134:137], v[182:185], v[90:93]
	v_mfma_f32_16x16x32_bf16 v[78:81], v[122:125], v[214:217], v[78:81]
	v_mfma_f32_16x16x32_bf16 v[74:77], v[134:137], v[214:217], v[74:77]
	s_setprio 0
	s_setprio 1
	v_mfma_f32_16x16x32_bf16 v[126:129], v[146:149], v[162:165], v[126:129]
	v_mfma_f32_16x16x32_bf16 v[114:117], v[154:157], v[162:165], v[114:117]
	v_mfma_f32_16x16x32_bf16 v[102:105], v[146:149], v[170:173], v[102:105]
	v_mfma_f32_16x16x32_bf16 v[98:101], v[154:157], v[170:173], v[98:101]
	v_mfma_f32_16x16x32_bf16 v[86:89], v[146:149], v[178:181], v[86:89]
	v_mfma_f32_16x16x32_bf16 v[82:85], v[154:157], v[178:181], v[82:85]
	v_mfma_f32_16x16x32_bf16 v[70:73], v[146:149], v[186:189], v[70:73]
	v_mfma_f32_16x16x32_bf16 v[66:69], v[154:157], v[186:189], v[66:69]
	v_mfma_f32_16x16x32_bf16 v[126:129], v[150:153], v[166:169], v[126:129]
	v_mfma_f32_16x16x32_bf16 v[114:117], v[158:161], v[166:169], v[114:117]
	v_mfma_f32_16x16x32_bf16 v[102:105], v[150:153], v[174:177], v[102:105]
	v_mfma_f32_16x16x32_bf16 v[98:101], v[158:161], v[174:177], v[98:101]
	v_mfma_f32_16x16x32_bf16 v[86:89], v[150:153], v[182:185], v[86:89]
	v_mfma_f32_16x16x32_bf16 v[82:85], v[158:161], v[182:185], v[82:85]
	v_mfma_f32_16x16x32_bf16 v[70:73], v[150:153], v[214:217], v[70:73]
	v_mfma_f32_16x16x32_bf16 v[66:69], v[158:161], v[214:217], v[66:69]
	s_setprio 0
	s_barrier
	s_add_i32 s18, s77, s49
	s_mov_b32 m0, s18
	s_nop 0
	global_load_lds_dwordx4 v192, s[40:41]
	ds_read_b128 v[162:165], v222 offset:16384
	ds_read_b128 v[166:169], v222 offset:17408
	s_add_i32 m0, s18, 0x2000
	s_add_u32 s18, s40, 0x160000
	s_addc_u32 s19, s41, 0
	s_add_i32 s77, s79, s49
	global_load_lds_dwordx4 v208, s[40:41]
	ds_read_b128 v[170:173], v222 offset:18432
	ds_read_b128 v[174:177], v222 offset:19456
	s_mov_b32 m0, s77
	s_nop 0
	global_load_lds_dwordx4 v192, s[18:19]
	ds_read_b128 v[178:181], v222 offset:20480
	ds_read_b128 v[182:185], v222 offset:21504
	s_add_i32 m0, s77, 0x2000
	s_nop 0
	global_load_lds_dwordx4 v208, s[18:19]
	ds_read_b128 v[186:189], v222 offset:22528
	ds_read_b128 v[214:217], v222 offset:23552
	s_mov_b32 m0, s52
	s_nop 0
	global_load_lds_dwordx4 v190, s[42:43]
	s_mov_b32 m0, s53
	s_nop 0
	global_load_lds_dwordx4 v206, s[42:43]
	s_waitcnt vmcnt(8)
	s_waitcnt lgkmcnt(0)
	s_nop 0
	s_barrier
	s_setprio 1
	s_waitcnt lgkmcnt(0)
	v_mfma_f32_16x16x32_bf16 v[62:65], v[118:121], v[162:165], v[62:65]
	v_mfma_f32_16x16x32_bf16 v[58:61], v[130:133], v[162:165], v[58:61]
	v_mfma_f32_16x16x32_bf16 v[46:49], v[118:121], v[170:173], v[46:49]
	v_mfma_f32_16x16x32_bf16 v[42:45], v[130:133], v[170:173], v[42:45]
	v_mfma_f32_16x16x32_bf16 v[30:33], v[118:121], v[178:181], v[30:33]
	v_mfma_f32_16x16x32_bf16 v[26:29], v[130:133], v[178:181], v[26:29]
	v_mfma_f32_16x16x32_bf16 v[14:17], v[118:121], v[186:189], v[14:17]
	v_mfma_f32_16x16x32_bf16 v[10:13], v[130:133], v[186:189], v[10:13]
	v_mfma_f32_16x16x32_bf16 v[62:65], v[122:125], v[166:169], v[62:65]
	v_mfma_f32_16x16x32_bf16 v[58:61], v[134:137], v[166:169], v[58:61]
	v_mfma_f32_16x16x32_bf16 v[46:49], v[122:125], v[174:177], v[46:49]
	v_mfma_f32_16x16x32_bf16 v[42:45], v[134:137], v[174:177], v[42:45]
	v_mfma_f32_16x16x32_bf16 v[30:33], v[122:125], v[182:185], v[30:33]
	v_mfma_f32_16x16x32_bf16 v[26:29], v[134:137], v[182:185], v[26:29]
	v_mfma_f32_16x16x32_bf16 v[14:17], v[122:125], v[214:217], v[14:17]
	v_mfma_f32_16x16x32_bf16 v[10:13], v[134:137], v[214:217], v[10:13]
	s_setprio 0
	s_setprio 1
	v_mfma_f32_16x16x32_bf16 v[54:57], v[146:149], v[162:165], v[54:57]
	v_mfma_f32_16x16x32_bf16 v[50:53], v[154:157], v[162:165], v[50:53]
	v_mfma_f32_16x16x32_bf16 v[38:41], v[146:149], v[170:173], v[38:41]
	v_mfma_f32_16x16x32_bf16 v[34:37], v[154:157], v[170:173], v[34:37]
	v_mfma_f32_16x16x32_bf16 v[22:25], v[146:149], v[178:181], v[22:25]
	v_mfma_f32_16x16x32_bf16 v[18:21], v[154:157], v[178:181], v[18:21]
	v_mfma_f32_16x16x32_bf16 v[6:9], v[146:149], v[186:189], v[6:9]
	v_mfma_f32_16x16x32_bf16 v[2:5], v[154:157], v[186:189], v[2:5]
	v_mfma_f32_16x16x32_bf16 v[54:57], v[150:153], v[166:169], v[54:57]
	v_mfma_f32_16x16x32_bf16 v[50:53], v[158:161], v[166:169], v[50:53]
	v_mfma_f32_16x16x32_bf16 v[38:41], v[150:153], v[174:177], v[38:41]
	v_mfma_f32_16x16x32_bf16 v[34:37], v[158:161], v[174:177], v[34:37]
	v_mfma_f32_16x16x32_bf16 v[22:25], v[150:153], v[182:185], v[22:25]
	v_mfma_f32_16x16x32_bf16 v[18:21], v[158:161], v[182:185], v[18:21]
	v_mfma_f32_16x16x32_bf16 v[6:9], v[150:153], v[214:217], v[6:9]
	v_mfma_f32_16x16x32_bf16 v[2:5], v[158:161], v[214:217], v[2:5]
	s_setprio 0
	s_barrier
; #define PG8_STAGE(bufoff, gbase, voff) do { _Pragma("unroll") for (int _i = 0; _i < 2; ++_i) \
;         __builtin_amdgcn_global_load_lds((const unsigned*)((const char*)(gbase) + (voff)[_i]), (PG8_LAS unsigned*)(lds + (bufoff) + ldsw + _i * 8192), 16, 0, 0); } while (0)
; #define PG8_LDA(dst, b, h) do { _Pragma("unroll") for (int m = 0; m < 4; ++m) _Pragma("unroll") for (int k = 0; k < 2; ++k) dst[m][k] = *(const PG8_LAS bf16x8*)(lds + PG8_SA(b, h) + aoff + m * 2048 + k * 1024); } while (0)
; #define PG8_LDB(dst, b, h) do { _Pragma("unroll") for (int n = 0; n < 2; ++n) _Pragma("unroll") for (int k = 0; k < 2; ++k) dst[n][k] = *(const PG8_LAS bf16x8*)(lds + PG8_SB(b, h) + boff + n * 2048 + k * 1024); } while (0)
; #define PG8_MMA(ai, bj, At, Bt) do { __builtin_amdgcn_s_setprio(1); _Pragma("unroll") for (int m = 0; m < 4; ++m) _Pragma("unroll") for (int n = 0; n < 2; ++n) _Pragma("unroll") for (int k = 0; k < 2; ++k) \
;         acc[ai][bj][m][n] = __builtin_amdgcn_mfma_f32_16x16x32_bf16(Bt[n][k], At[m][k], acc[ai][bj][m][n], 0, 0, 0); __builtin_amdgcn_s_setprio(0); } while (0)
; #define PG8_WAIT_V(n) asm volatile("s_waitcnt vmcnt(" #n ")" ::: "memory")
; #define PG8_WAIT_L(n) asm volatile("s_waitcnt lgkmcnt(" #n ")" ::: "memory")
; #define PG8_BAR __builtin_amdgcn_s_barrier()
; #define PG8_SCHED __builtin_amdgcn_sched_barrier(0)
; template <class Epi, class Sched, bool ALIGN_EPI = false, bool SP2 = false>
; __device__ __forceinline__ void gemm_phase(PG8_LAS unsigned char* lds, const Gemm g, const Sched& S, const Epi& E, const int wave_id) {
;     ...
;             PG8_LDB(B0, 1, 0); PG8_LDB(B1, 1, 1); PG8_SCHED; PG8_LDA(At, 1, 0); PG8_STAGE(PG8_SA(0, 1), a2 + hstep, voffA);
;             PG8_WAIT_V(8); PG8_WAIT_L(0); PG8_BAR; PG8_MMA(0, 0, At, B0); PG8_MMA(0, 1, At, B1); PG8_BAR; PG8_SCHED;
;             PG8_LDA(At, 1, 1); PG8_STAGE(PG8_SB(1, 0), b3, voffB); PG8_STAGE(PG8_SB(1, 1), b3 + hstep, voffB); PG8_STAGE(PG8_SA(1, 0), a3, voffA);
;             PG8_WAIT_V(8); PG8_WAIT_L(0); PG8_BAR; PG8_MMA(1, 0, At, B0); PG8_MMA(1, 1, At, B1); PG8_BAR; PG8_SCHED;
	s_add_i32 s77, 0, 0x18000
	s_add_i32 s79, 0, 0x1c000
	s_add_u32 s18, s42, 0x160000
	s_addc_u32 s19, s43, 0
	s_mov_b32 m0, s56
	s_nop 0
	global_load_lds_dwordx4 v190, s[18:19]
	ds_read_b128 v[118:121], v226 offset:32768
	ds_read_b128 v[122:125], v226 offset:33792
	ds_read_b128 v[130:133], v226 offset:34816
	ds_read_b128 v[134:137], v226 offset:35840
	ds_read_b128 v[146:149], v226 offset:49152
	ds_read_b128 v[150:153], v226 offset:50176
	ds_read_b128 v[154:157], v226 offset:51200
	ds_read_b128 v[158:161], v226 offset:52224
	s_mov_b32 m0, s57
	s_nop 0
	global_load_lds_dwordx4 v206, s[18:19]
	ds_read_b128 v[162:165], v222 offset:32768
	ds_read_b128 v[166:169], v222 offset:33792
	ds_read_b128 v[170:173], v222 offset:34816
	ds_read_b128 v[174:177], v222 offset:35840
	ds_read_b128 v[178:181], v222 offset:36864
	ds_read_b128 v[182:185], v222 offset:37888
	ds_read_b128 v[186:189], v222 offset:38912
	ds_read_b128 v[214:217], v222 offset:39936
	s_waitcnt vmcnt(8)
	s_waitcnt lgkmcnt(0)
	s_barrier
	s_setprio 1
	s_waitcnt lgkmcnt(0)
	v_mfma_f32_16x16x32_bf16 v[142:145], v[118:121], v[162:165], v[142:145]
	v_mfma_f32_16x16x32_bf16 v[138:141], v[130:133], v[162:165], v[138:141]
	v_mfma_f32_16x16x32_bf16 v[110:113], v[118:121], v[170:173], v[110:113]
	v_mfma_f32_16x16x32_bf16 v[106:109], v[130:133], v[170:173], v[106:109]
	v_mfma_f32_16x16x32_bf16 v[94:97], v[118:121], v[178:181], v[94:97]
	v_mfma_f32_16x16x32_bf16 v[90:93], v[130:133], v[178:181], v[90:93]
	v_mfma_f32_16x16x32_bf16 v[78:81], v[118:121], v[186:189], v[78:81]
	v_mfma_f32_16x16x32_bf16 v[74:77], v[130:133], v[186:189], v[74:77]
	v_mfma_f32_16x16x32_bf16 v[142:145], v[122:125], v[166:169], v[142:145]
	v_mfma_f32_16x16x32_bf16 v[138:141], v[134:137], v[166:169], v[138:141]
	v_mfma_f32_16x16x32_bf16 v[110:113], v[122:125], v[174:177], v[110:113]
	v_mfma_f32_16x16x32_bf16 v[106:109], v[134:137], v[174:177], v[106:109]
	v_mfma_f32_16x16x32_bf16 v[94:97], v[122:125], v[182:185], v[94:97]
	v_mfma_f32_16x16x32_bf16 v[90:93], v[134:137], v[182:185], v[90:93]
	v_mfma_f32_16x16x32_bf16 v[78:81], v[122:125], v[214:217], v[78:81]
	v_mfma_f32_16x16x32_bf16 v[74:77], v[134:137], v[214:217], v[74:77]
	s_setprio 0
	s_setprio 1
	v_mfma_f32_16x16x32_bf16 v[126:129], v[146:149], v[162:165], v[126:129]
	v_mfma_f32_16x16x32_bf16 v[114:117], v[154:157], v[162:165], v[114:117]
	v_mfma_f32_16x16x32_bf16 v[102:105], v[146:149], v[170:173], v[102:105]
	v_mfma_f32_16x16x32_bf16 v[98:101], v[154:157], v[170:173], v[98:101]
	v_mfma_f32_16x16x32_bf16 v[86:89], v[146:149], v[178:181], v[86:89]
	v_mfma_f32_16x16x32_bf16 v[82:85], v[154:157], v[178:181], v[82:85]
	v_mfma_f32_16x16x32_bf16 v[70:73], v[146:149], v[186:189], v[70:73]
	v_mfma_f32_16x16x32_bf16 v[66:69], v[154:157], v[186:189], v[66:69]
	v_mfma_f32_16x16x32_bf16 v[126:129], v[150:153], v[166:169], v[126:129]
	v_mfma_f32_16x16x32_bf16 v[114:117], v[158:161], v[166:169], v[114:117]
	v_mfma_f32_16x16x32_bf16 v[102:105], v[150:153], v[174:177], v[102:105]
	v_mfma_f32_16x16x32_bf16 v[98:101], v[158:161], v[174:177], v[98:101]
	v_mfma_f32_16x16x32_bf16 v[86:89], v[150:153], v[182:185], v[86:89]
	v_mfma_f32_16x16x32_bf16 v[82:85], v[158:161], v[182:185], v[82:85]
	v_mfma_f32_16x16x32_bf16 v[70:73], v[150:153], v[214:217], v[70:73]
	v_mfma_f32_16x16x32_bf16 v[66:69], v[158:161], v[214:217], v[66:69]
	s_setprio 0
	s_barrier
	s_add_u32 vcc_lo, s42, 0x80
	s_addc_u32 vcc_hi, s43, 0
	s_mov_b32 m0, s68
	s_nop 0
	global_load_lds_dwordx4 v190, vcc
	ds_read_b128 v[162:165], v222 offset:49152
	ds_read_b128 v[166:169], v222 offset:50176
	s_mov_b32 m0, s69
	s_add_i32 s18, s77, s49
	global_load_lds_dwordx4 v206, vcc
	ds_read_b128 v[170:173], v222 offset:51200
	ds_read_b128 v[174:177], v222 offset:52224
	s_add_u32 vcc_lo, s40, 0x80
	s_addc_u32 vcc_hi, s41, 0
	s_mov_b32 m0, s18
	s_nop 0
	global_load_lds_dwordx4 v192, vcc
	ds_read_b128 v[178:181], v222 offset:53248
	ds_read_b128 v[182:185], v222 offset:54272
	s_add_i32 m0, s18, 0x2000
	s_add_u32 s18, s40, 0x160080
	s_addc_u32 s19, s41, 0
	global_load_lds_dwordx4 v208, vcc
	ds_read_b128 v[186:189], v222 offset:55296
	ds_read_b128 v[214:217], v222 offset:56320
	s_add_i32 s40, s79, s49
	s_mov_b32 m0, s40
	s_nop 0
	global_load_lds_dwordx4 v192, s[18:19]
	s_add_i32 m0, s40, 0x2000
	s_nop 0
	global_load_lds_dwordx4 v208, s[18:19]
	s_waitcnt vmcnt(8)
	s_waitcnt lgkmcnt(0)
	s_barrier
	s_setprio 1
	s_waitcnt lgkmcnt(0)
	v_mfma_f32_16x16x32_bf16 v[62:65], v[118:121], v[162:165], v[62:65]
	v_mfma_f32_16x16x32_bf16 v[58:61], v[130:133], v[162:165], v[58:61]
	v_mfma_f32_16x16x32_bf16 v[46:49], v[118:121], v[170:173], v[46:49]
	v_mfma_f32_16x16x32_bf16 v[42:45], v[130:133], v[170:173], v[42:45]
	v_mfma_f32_16x16x32_bf16 v[30:33], v[118:121], v[178:181], v[30:33]
	v_mfma_f32_16x16x32_bf16 v[26:29], v[130:133], v[178:181], v[26:29]
	v_mfma_f32_16x16x32_bf16 v[14:17], v[118:121], v[186:189], v[14:17]
	v_mfma_f32_16x16x32_bf16 v[10:13], v[130:133], v[186:189], v[10:13]
	v_mfma_f32_16x16x32_bf16 v[62:65], v[122:125], v[166:169], v[62:65]
	v_mfma_f32_16x16x32_bf16 v[58:61], v[134:137], v[166:169], v[58:61]
	v_mfma_f32_16x16x32_bf16 v[46:49], v[122:125], v[174:177], v[46:49]
	v_mfma_f32_16x16x32_bf16 v[42:45], v[134:137], v[174:177], v[42:45]
	v_mfma_f32_16x16x32_bf16 v[30:33], v[122:125], v[182:185], v[30:33]
	v_mfma_f32_16x16x32_bf16 v[26:29], v[134:137], v[182:185], v[26:29]
	v_mfma_f32_16x16x32_bf16 v[14:17], v[122:125], v[214:217], v[14:17]
	v_mfma_f32_16x16x32_bf16 v[10:13], v[134:137], v[214:217], v[10:13]
	s_setprio 0
	s_setprio 1
	v_mfma_f32_16x16x32_bf16 v[54:57], v[146:149], v[162:165], v[54:57]
	v_mfma_f32_16x16x32_bf16 v[50:53], v[154:157], v[162:165], v[50:53]
	v_mfma_f32_16x16x32_bf16 v[38:41], v[146:149], v[170:173], v[38:41]
	v_mfma_f32_16x16x32_bf16 v[34:37], v[154:157], v[170:173], v[34:37]
	v_mfma_f32_16x16x32_bf16 v[22:25], v[146:149], v[178:181], v[22:25]
	v_mfma_f32_16x16x32_bf16 v[18:21], v[154:157], v[178:181], v[18:21]
	v_mfma_f32_16x16x32_bf16 v[6:9], v[146:149], v[186:189], v[6:9]
	v_mfma_f32_16x16x32_bf16 v[2:5], v[154:157], v[186:189], v[2:5]
	v_mfma_f32_16x16x32_bf16 v[54:57], v[150:153], v[166:169], v[54:57]
	v_mfma_f32_16x16x32_bf16 v[50:53], v[158:161], v[166:169], v[50:53]
	v_mfma_f32_16x16x32_bf16 v[38:41], v[150:153], v[174:177], v[38:41]
	v_mfma_f32_16x16x32_bf16 v[34:37], v[158:161], v[174:177], v[34:37]
	v_mfma_f32_16x16x32_bf16 v[22:25], v[150:153], v[182:185], v[22:25]
	v_mfma_f32_16x16x32_bf16 v[18:21], v[158:161], v[182:185], v[18:21]
	v_mfma_f32_16x16x32_bf16 v[6:9], v[150:153], v[214:217], v[6:9]
	v_mfma_f32_16x16x32_bf16 v[2:5], v[158:161], v[214:217], v[2:5]
	s_setprio 0
	s_barrier
	s_add_i32 s76, s76, 2
	s_add_u32 s74, s74, 0x100
	s_addc_u32 s75, s75, 0
	s_cmpk_gt_u32 s76, 0x55
	s_mov_b64 s[18:19], s[20:21]
	s_cbranch_scc0 .LBB0_759

;     __host__ __device__ bool next(int i, Unit& u) const { const bool ok = StaticOrder::next(i, u); u.lm = 0; u.ln = 0; return ok; }
; #define PG8_STAGE(bufoff, gbase, voff) do { _Pragma("unroll") for (int _i = 0; _i < 2; ++_i) \
;         __builtin_amdgcn_global_load_lds((const unsigned*)((const char*)(gbase) + (voff)[_i]), (PG8_LAS unsigned*)(lds + (bufoff) + ldsw + _i * 8192), 16, 0, 0); } while (0)
; #define PG8_LDA(dst, b, h) do { _Pragma("unroll") for (int m = 0; m < 4; ++m) _Pragma("unroll") for (int k = 0; k < 2; ++k) dst[m][k] = *(const PG8_LAS bf16x8*)(lds + PG8_SA(b, h) + aoff + m * 2048 + k * 1024); } while (0)
; #define PG8_LDB(dst, b, h) do { _Pragma("unroll") for (int n = 0; n < 2; ++n) _Pragma("unroll") for (int k = 0; k < 2; ++k) dst[n][k] = *(const PG8_LAS bf16x8*)(lds + PG8_SB(b, h) + boff + n * 2048 + k * 1024); } while (0)
; #define PG8_WAIT_V(n) asm volatile("s_waitcnt vmcnt(" #n ")" ::: "memory")
; #define PG8_BAR __builtin_amdgcn_s_barrier()
; template <class Epi, class Sched, bool ALIGN_EPI = false, bool SP2 = false>
; __device__ __forceinline__ void gemm_phase(PG8_LAS unsigned char* lds, const Gemm g, const Sched& S, const Epi& E, const int wave_id) {
;     ...
;         const bool has_next = S.next(ui + 1, nxt);
;         const char* nA = has_next ? (const char*)g.A + (size_t)nxt.lm * tstep : cA; const char* nB = has_next ? (const char*)g.Bt + (size_t)nxt.ln * tstep : cB;
; #pragma unroll 1
;         for (int t = 0; t < nt; t += 2) {
;             const bool last = (t == nt - 2);
;             const char* a1 = cA + (size_t)(t + 1) * kstep;
;             const char* a2 = last ? nA : cA + (size_t)(t + 2) * kstep; const char* b2 = last ? nB : cB + (size_t)(t + 2) * kstep;
;             const char* a3 = a2 + kstep; const char* b3 = b2 + kstep;
;             if (last && has_next) S.a_ready(nxt);
;             if constexpr (SP2) {
;             PG8_LDB(B0, 0, 0); PG8_LDB(B1, 0, 1); PG8_SCHED; PG8_LDA(At, 0, 0); PG8_STAGE(PG8_SA(1, 1), a1 + hstep, voffA);
;             PG8_WAIT_V(8); PG8_WAIT_L(0); PG8_BAR; PG8_MMA(0, 0, At, B0); PG8_MMA(0, 1, At, B1); PG8_BAR; PG8_SCHED;
;             PG8_LDA(At, 0, 1); PG8_STAGE(PG8_SB(0, 0), b2, voffB); PG8_STAGE(PG8_SB(0, 1), b2 + hstep, voffB); PG8_STAGE(PG8_SA(0, 0), a2, voffA);
;             PG8_WAIT_V(8); PG8_WAIT_L(0); PG8_BAR; PG8_MMA(1, 0, At, B0); PG8_MMA(1, 1, At, B1); PG8_BAR; PG8_SCHED;
.LBB0_798:
	s_ashr_i32 s19, s18, 31
	s_lshl_b64 s[20:21], s[18:19], 17
	s_add_u32 s20, s56, s20
	s_addc_u32 s21, s57, s21
	s_and_b64 s[38:39], s[36:37], exec
	s_cselect_b32 s19, s21, s15
	s_cselect_b32 s77, s20, s14
	s_ashr_i32 s17, s16, 31
	s_lshl_b64 s[38:39], s[16:17], 17
	s_add_u32 s38, s64, s38
	s_addc_u32 s39, s65, s39
	s_and_b64 s[40:41], s[36:37], exec
	s_cselect_b32 s17, s39, s13
	s_cselect_b32 s79, s38, s12
	s_mov_b64 s[44:45], 0
	s_mov_b64 s[40:41], -1
	s_mov_b64 s[42:43], 0
	s_add_u32 s52, s14, s44
	s_addc_u32 s53, s15, s45
	s_add_u32 s48, s52, 0x100
	s_addc_u32 s49, s53, 0
	s_and_b64 s[46:47], s[42:43], exec
	s_cselect_b32 s47, s19, s49
	s_cselect_b32 s46, s77, s48
	s_add_u32 s44, s12, s44
	s_addc_u32 s45, s13, s45
	s_add_u32 s44, s44, 0x100
	s_addc_u32 s45, s45, 0
	s_add_i32 s96, 0, 0x10000
	s_and_b64 s[42:43], s[42:43], exec
	s_cselect_b32 s49, s17, s45
	s_cselect_b32 s48, s79, s44
	s_add_i32 s43, 0, 0x14000
	s_add_u32 s82, s52, 0x10080
	s_addc_u32 s83, s53, 0
	s_add_i32 s93, s96, s68
	s_add_i32 m0, s69, 0xc000
	s_add_i32 vcc_lo, s69, 0xe000
	s_add_i32 s88, s93, 0x2000
	v_add_u32_e32 v141, s96, v138
	s_add_u32 s52, s48, 0x10000
	ds_read_b128 v[142:145], v141
	ds_read_b128 v[146:149], v141 offset:1024
	ds_read_b128 v[150:153], v141 offset:2048
	ds_read_b128 v[154:157], v141 offset:3072
	v_add_u32_e32 v141, s43, v138
	s_addc_u32 s53, s49, 0
	s_add_i32 s92, s43, s68
	ds_read_b128 v[158:161], v141
	ds_read_b128 v[162:165], v141 offset:1024
	ds_read_b128 v[166:169], v141 offset:2048
	ds_read_b128 v[170:173], v141 offset:3072
	s_add_i32 s89, s92, 0x2000
	s_add_i32 s85, 0, 0x18000
	s_add_i32 s84, 0, 0x1c000
	s_add_u32 s44, s46, 0x10000
	s_addc_u32 s45, s47, 0
	s_add_i32 s81, s85, s68
	s_add_i32 s80, s81, 0x2000
	s_add_u32 s42, s48, 0x10080
	s_addc_u32 s43, s49, 0
	s_add_i32 s97, s84, s68
	s_add_i32 s96, s97, 0x2000
	v_lshl_add_u64 v[226:227], s[82:83], 0, v[130:131]
	ds_read_b128 v[174:177], v140
	ds_read_b128 v[178:181], v140 offset:1024
	ds_read_b128 v[182:185], v140 offset:2048
	ds_read_b128 v[186:189], v140 offset:3072
	ds_read_b128 v[190:193], v140 offset:4096
	ds_read_b128 v[206:209], v140 offset:5120
	ds_read_b128 v[210:213], v140 offset:6144
	ds_read_b128 v[214:217], v140 offset:7168
	global_load_lds_dwordx4 v[226:227], off
	v_lshl_add_u64 v[226:227], s[82:83], 0, v[134:135]
	s_mov_b32 m0, vcc_lo
	s_nop 0
	global_load_lds_dwordx4 v[226:227], off
	s_waitcnt vmcnt(8)
	s_waitcnt lgkmcnt(0)
	s_nop 0
	s_barrier
	s_setprio 1
	s_waitcnt lgkmcnt(0)
	v_mfma_f32_16x16x32_bf16 v[126:129], v[142:145], v[174:177], 0
	v_mfma_f32_16x16x32_bf16 v[122:125], v[150:153], v[174:177], 0
	v_mfma_f32_16x16x32_bf16 v[118:121], v[142:145], v[182:185], 0
	v_mfma_f32_16x16x32_bf16 v[114:117], v[150:153], v[182:185], 0
	v_mfma_f32_16x16x32_bf16 v[102:105], v[142:145], v[190:193], 0
	v_mfma_f32_16x16x32_bf16 v[98:101], v[150:153], v[190:193], 0
	v_mfma_f32_16x16x32_bf16 v[86:89], v[142:145], v[210:213], 0
	v_mfma_f32_16x16x32_bf16 v[82:85], v[150:153], v[210:213], 0
	v_mfma_f32_16x16x32_bf16 v[126:129], v[146:149], v[178:181], v[126:129]
	v_mfma_f32_16x16x32_bf16 v[122:125], v[154:157], v[178:181], v[122:125]
	v_mfma_f32_16x16x32_bf16 v[118:121], v[146:149], v[186:189], v[118:121]
	v_mfma_f32_16x16x32_bf16 v[114:117], v[154:157], v[186:189], v[114:117]
	v_mfma_f32_16x16x32_bf16 v[102:105], v[146:149], v[206:209], v[102:105]
	v_mfma_f32_16x16x32_bf16 v[98:101], v[154:157], v[206:209], v[98:101]
	v_mfma_f32_16x16x32_bf16 v[86:89], v[146:149], v[214:217], v[86:89]
	v_mfma_f32_16x16x32_bf16 v[82:85], v[154:157], v[214:217], v[82:85]
	s_setprio 0
	s_setprio 1
	v_mfma_f32_16x16x32_bf16 v[110:113], v[158:161], v[174:177], 0
	v_mfma_f32_16x16x32_bf16 v[106:109], v[166:169], v[174:177], 0
	v_mfma_f32_16x16x32_bf16 v[94:97], v[158:161], v[182:185], 0
	v_mfma_f32_16x16x32_bf16 v[90:93], v[166:169], v[182:185], 0
	v_mfma_f32_16x16x32_bf16 v[78:81], v[158:161], v[190:193], 0
	v_mfma_f32_16x16x32_bf16 v[74:77], v[166:169], v[190:193], 0
	v_mfma_f32_16x16x32_bf16 v[70:73], v[158:161], v[210:213], 0
	v_mfma_f32_16x16x32_bf16 v[66:69], v[166:169], v[210:213], 0
	v_mfma_f32_16x16x32_bf16 v[110:113], v[162:165], v[178:181], v[110:113]
	v_mfma_f32_16x16x32_bf16 v[106:109], v[170:173], v[178:181], v[106:109]
	v_mfma_f32_16x16x32_bf16 v[94:97], v[162:165], v[186:189], v[94:97]
	v_mfma_f32_16x16x32_bf16 v[90:93], v[170:173], v[186:189], v[90:93]
	v_mfma_f32_16x16x32_bf16 v[78:81], v[162:165], v[206:209], v[78:81]
	v_mfma_f32_16x16x32_bf16 v[74:77], v[170:173], v[206:209], v[74:77]
	v_mfma_f32_16x16x32_bf16 v[70:73], v[162:165], v[214:217], v[70:73]
	v_mfma_f32_16x16x32_bf16 v[66:69], v[170:173], v[214:217], v[66:69]
	s_setprio 0
	s_barrier
	s_mov_b32 m0, s93
	v_lshl_add_u64 v[226:227], s[48:49], 0, v[132:133]
	ds_read_b128 v[174:177], v140 offset:16384
	ds_read_b128 v[178:181], v140 offset:17408
	ds_read_b128 v[182:185], v140 offset:18432
	ds_read_b128 v[186:189], v140 offset:19456
	ds_read_b128 v[190:193], v140 offset:20480
	ds_read_b128 v[206:209], v140 offset:21504
	ds_read_b128 v[210:213], v140 offset:22528
	ds_read_b128 v[214:217], v140 offset:23552
	global_load_lds_dwordx4 v[226:227], off
	v_lshl_add_u64 v[228:229], s[48:49], 0, v[136:137]
	s_mov_b32 m0, s88
	v_lshl_add_u64 v[230:231], s[52:53], 0, v[132:133]
	global_load_lds_dwordx4 v[228:229], off
	s_mov_b32 m0, s92
	v_lshl_add_u64 v[234:235], s[46:47], 0, v[134:135]
	global_load_lds_dwordx4 v[230:231], off
	v_lshl_add_u64 v[230:231], s[52:53], 0, v[136:137]
	s_mov_b32 m0, s89
	s_nop 0
	global_load_lds_dwordx4 v[230:231], off
	v_lshl_add_u64 v[230:231], s[46:47], 0, v[130:131]
	s_mov_b32 m0, s69
	s_nop 0
	global_load_lds_dwordx4 v[230:231], off
	s_mov_b32 m0, s70
	s_nop 0
	global_load_lds_dwordx4 v[234:235], off
	s_waitcnt vmcnt(8)
	s_waitcnt lgkmcnt(0)
	s_barrier
; #define PG8_STAGE(bufoff, gbase, voff) do { _Pragma("unroll") for (int _i = 0; _i < 2; ++_i) \
;         __builtin_amdgcn_global_load_lds((const unsigned*)((const char*)(gbase) + (voff)[_i]), (PG8_LAS unsigned*)(lds + (bufoff) + ldsw + _i * 8192), 16, 0, 0); } while (0)
; #define PG8_LDA(dst, b, h) do { _Pragma("unroll") for (int m = 0; m < 4; ++m) _Pragma("unroll") for (int k = 0; k < 2; ++k) dst[m][k] = *(const PG8_LAS bf16x8*)(lds + PG8_SA(b, h) + aoff + m * 2048 + k * 1024); } while (0)
; #define PG8_LDB(dst, b, h) do { _Pragma("unroll") for (int n = 0; n < 2; ++n) _Pragma("unroll") for (int k = 0; k < 2; ++k) dst[n][k] = *(const PG8_LAS bf16x8*)(lds + PG8_SB(b, h) + boff + n * 2048 + k * 1024); } while (0)
; #define PG8_MMA(ai, bj, At, Bt) do { __builtin_amdgcn_s_setprio(1); _Pragma("unroll") for (int m = 0; m < 4; ++m) _Pragma("unroll") for (int n = 0; n < 2; ++n) _Pragma("unroll") for (int k = 0; k < 2; ++k) \
;         acc[ai][bj][m][n] = __builtin_amdgcn_mfma_f32_16x16x32_bf16(Bt[n][k], At[m][k], acc[ai][bj][m][n], 0, 0, 0); __builtin_amdgcn_s_setprio(0); } while (0)
; #define PG8_WAIT_V(n) asm volatile("s_waitcnt vmcnt(" #n ")" ::: "memory")
; #define PG8_WAIT_L(n) asm volatile("s_waitcnt lgkmcnt(" #n ")" ::: "memory")
; #define PG8_BAR __builtin_amdgcn_s_barrier()
; #define PG8_SCHED __builtin_amdgcn_sched_barrier(0)
; template <class Epi, class Sched, bool ALIGN_EPI = false, bool SP2 = false>
; __device__ __forceinline__ void gemm_phase(PG8_LAS unsigned char* lds, const Gemm g, const Sched& S, const Epi& E, const int wave_id) {
;     ...
;             PG8_WAIT_V(8); PG8_WAIT_L(0); PG8_BAR; PG8_MMA(0, 0, At, B0); PG8_MMA(0, 1, At, B1); PG8_BAR; PG8_SCHED;
;             PG8_LDA(At, 0, 1); PG8_STAGE(PG8_SB(0, 0), b2, voffB); PG8_STAGE(PG8_SB(0, 1), b2 + hstep, voffB); PG8_STAGE(PG8_SA(0, 0), a2, voffA);
;             PG8_WAIT_V(8); PG8_WAIT_L(0); PG8_BAR; PG8_MMA(1, 0, At, B0); PG8_MMA(1, 1, At, B1); PG8_BAR; PG8_SCHED;
;             PG8_LDB(B0, 1, 0); PG8_LDB(B1, 1, 1); PG8_SCHED; PG8_LDA(At, 1, 0); PG8_STAGE(PG8_SA(0, 1), a2 + hstep, voffA);
;             PG8_WAIT_V(8); PG8_WAIT_L(0); PG8_BAR; PG8_MMA(0, 0, At, B0); PG8_MMA(0, 1, At, B1); PG8_BAR; PG8_SCHED;
	s_setprio 1
	s_waitcnt lgkmcnt(0)
	v_mfma_f32_16x16x32_bf16 v[62:65], v[142:145], v[174:177], 0
	v_mfma_f32_16x16x32_bf16 v[58:61], v[150:153], v[174:177], 0
	v_mfma_f32_16x16x32_bf16 v[54:57], v[142:145], v[182:185], 0
	v_mfma_f32_16x16x32_bf16 v[50:53], v[150:153], v[182:185], 0
	v_mfma_f32_16x16x32_bf16 v[38:41], v[142:145], v[190:193], 0
	v_mfma_f32_16x16x32_bf16 v[34:37], v[150:153], v[190:193], 0
	v_mfma_f32_16x16x32_bf16 v[22:25], v[142:145], v[210:213], 0
	v_mfma_f32_16x16x32_bf16 v[18:21], v[150:153], v[210:213], 0
	v_mfma_f32_16x16x32_bf16 v[62:65], v[146:149], v[178:181], v[62:65]
	v_mfma_f32_16x16x32_bf16 v[58:61], v[154:157], v[178:181], v[58:61]
	v_mfma_f32_16x16x32_bf16 v[54:57], v[146:149], v[186:189], v[54:57]
	v_mfma_f32_16x16x32_bf16 v[50:53], v[154:157], v[186:189], v[50:53]
	v_mfma_f32_16x16x32_bf16 v[38:41], v[146:149], v[206:209], v[38:41]
	v_mfma_f32_16x16x32_bf16 v[34:37], v[154:157], v[206:209], v[34:37]
	v_mfma_f32_16x16x32_bf16 v[22:25], v[146:149], v[214:217], v[22:25]
	v_mfma_f32_16x16x32_bf16 v[18:21], v[154:157], v[214:217], v[18:21]
	s_setprio 0
	s_setprio 1
	v_mfma_f32_16x16x32_bf16 v[46:49], v[158:161], v[174:177], 0
	v_mfma_f32_16x16x32_bf16 v[42:45], v[166:169], v[174:177], 0
	v_mfma_f32_16x16x32_bf16 v[30:33], v[158:161], v[182:185], 0
	v_mfma_f32_16x16x32_bf16 v[26:29], v[166:169], v[182:185], 0
	v_mfma_f32_16x16x32_bf16 v[14:17], v[158:161], v[190:193], 0
	v_mfma_f32_16x16x32_bf16 v[10:13], v[166:169], v[190:193], 0
	v_mfma_f32_16x16x32_bf16 v[6:9], v[158:161], v[210:213], 0
	v_mfma_f32_16x16x32_bf16 v[2:5], v[166:169], v[210:213], 0
	v_mfma_f32_16x16x32_bf16 v[46:49], v[162:165], v[178:181], v[46:49]
	v_mfma_f32_16x16x32_bf16 v[42:45], v[170:173], v[178:181], v[42:45]
	v_mfma_f32_16x16x32_bf16 v[30:33], v[162:165], v[186:189], v[30:33]
	v_mfma_f32_16x16x32_bf16 v[26:29], v[170:173], v[186:189], v[26:29]
	v_mfma_f32_16x16x32_bf16 v[14:17], v[162:165], v[206:209], v[14:17]
	v_mfma_f32_16x16x32_bf16 v[10:13], v[170:173], v[206:209], v[10:13]
	v_mfma_f32_16x16x32_bf16 v[6:9], v[162:165], v[214:217], v[6:9]
	v_mfma_f32_16x16x32_bf16 v[2:5], v[170:173], v[214:217], v[2:5]
	s_setprio 0
	s_barrier
	v_add_u32_e32 v141, s85, v138
	ds_read_b128 v[142:145], v141
	ds_read_b128 v[146:149], v141 offset:1024
	ds_read_b128 v[150:153], v141 offset:2048
	ds_read_b128 v[154:157], v141 offset:3072
	v_add_u32_e32 v141, s84, v138
	ds_read_b128 v[158:161], v141
	ds_read_b128 v[162:165], v141 offset:1024
	ds_read_b128 v[166:169], v141 offset:2048
	ds_read_b128 v[170:173], v141 offset:3072
	s_mov_b32 m0, s71
	v_lshl_add_u64 v[236:237], s[44:45], 0, v[130:131]
	ds_read_b128 v[174:177], v140 offset:32768
	ds_read_b128 v[178:181], v140 offset:33792
	ds_read_b128 v[182:185], v140 offset:34816
	ds_read_b128 v[186:189], v140 offset:35840
	ds_read_b128 v[190:193], v140 offset:36864
	ds_read_b128 v[206:209], v140 offset:37888
	ds_read_b128 v[210:213], v140 offset:38912
	ds_read_b128 v[214:217], v140 offset:39936
	global_load_lds_dwordx4 v[236:237], off
	v_lshl_add_u64 v[236:237], s[44:45], 0, v[134:135]
	s_mov_b32 m0, s72
	s_nop 0
	global_load_lds_dwordx4 v[236:237], off
	s_waitcnt vmcnt(8)
	s_waitcnt lgkmcnt(0)
	s_barrier
	s_setprio 1
	s_waitcnt lgkmcnt(0)
	v_mfma_f32_16x16x32_bf16 v[126:129], v[142:145], v[174:177], v[126:129]
	v_mfma_f32_16x16x32_bf16 v[122:125], v[150:153], v[174:177], v[122:125]
	v_mfma_f32_16x16x32_bf16 v[118:121], v[142:145], v[182:185], v[118:121]
	v_mfma_f32_16x16x32_bf16 v[114:117], v[150:153], v[182:185], v[114:117]
	v_mfma_f32_16x16x32_bf16 v[102:105], v[142:145], v[190:193], v[102:105]
	v_mfma_f32_16x16x32_bf16 v[98:101], v[150:153], v[190:193], v[98:101]
	v_mfma_f32_16x16x32_bf16 v[86:89], v[142:145], v[210:213], v[86:89]
	v_mfma_f32_16x16x32_bf16 v[82:85], v[150:153], v[210:213], v[82:85]
	v_mfma_f32_16x16x32_bf16 v[126:129], v[146:149], v[178:181], v[126:129]
	v_mfma_f32_16x16x32_bf16 v[122:125], v[154:157], v[178:181], v[122:125]
	v_mfma_f32_16x16x32_bf16 v[118:121], v[146:149], v[186:189], v[118:121]
	v_mfma_f32_16x16x32_bf16 v[114:117], v[154:157], v[186:189], v[114:117]
	v_mfma_f32_16x16x32_bf16 v[102:105], v[146:149], v[206:209], v[102:105]
	v_mfma_f32_16x16x32_bf16 v[98:101], v[154:157], v[206:209], v[98:101]
	v_mfma_f32_16x16x32_bf16 v[86:89], v[146:149], v[214:217], v[86:89]
	v_mfma_f32_16x16x32_bf16 v[82:85], v[154:157], v[214:217], v[82:85]
	s_setprio 0
	s_setprio 1
	v_mfma_f32_16x16x32_bf16 v[110:113], v[158:161], v[174:177], v[110:113]
	v_mfma_f32_16x16x32_bf16 v[106:109], v[166:169], v[174:177], v[106:109]
	v_mfma_f32_16x16x32_bf16 v[94:97], v[158:161], v[182:185], v[94:97]
	v_mfma_f32_16x16x32_bf16 v[90:93], v[166:169], v[182:185], v[90:93]
	v_mfma_f32_16x16x32_bf16 v[78:81], v[158:161], v[190:193], v[78:81]
	v_mfma_f32_16x16x32_bf16 v[74:77], v[166:169], v[190:193], v[74:77]
	v_mfma_f32_16x16x32_bf16 v[70:73], v[158:161], v[210:213], v[70:73]
	v_mfma_f32_16x16x32_bf16 v[66:69], v[166:169], v[210:213], v[66:69]
	v_mfma_f32_16x16x32_bf16 v[110:113], v[162:165], v[178:181], v[110:113]
	v_mfma_f32_16x16x32_bf16 v[106:109], v[170:173], v[178:181], v[106:109]
	v_mfma_f32_16x16x32_bf16 v[94:97], v[162:165], v[186:189], v[94:97]
	v_mfma_f32_16x16x32_bf16 v[90:93], v[170:173], v[186:189], v[90:93]
	v_mfma_f32_16x16x32_bf16 v[78:81], v[162:165], v[206:209], v[78:81]
	v_mfma_f32_16x16x32_bf16 v[74:77], v[170:173], v[206:209], v[74:77]
	v_mfma_f32_16x16x32_bf16 v[70:73], v[162:165], v[214:217], v[70:73]
	v_mfma_f32_16x16x32_bf16 v[66:69], v[170:173], v[214:217], v[66:69]
	s_setprio 0
	s_barrier
; #define PG8_STAGE(bufoff, gbase, voff) do { _Pragma("unroll") for (int _i = 0; _i < 2; ++_i) \
;         __builtin_amdgcn_global_load_lds((const unsigned*)((const char*)(gbase) + (voff)[_i]), (PG8_LAS unsigned*)(lds + (bufoff) + ldsw + _i * 8192), 16, 0, 0); } while (0)
; #define PG8_LDA(dst, b, h) do { _Pragma("unroll") for (int m = 0; m < 4; ++m) _Pragma("unroll") for (int k = 0; k < 2; ++k) dst[m][k] = *(const PG8_LAS bf16x8*)(lds + PG8_SA(b, h) + aoff + m * 2048 + k * 1024); } while (0)
; #define PG8_LDB(dst, b, h) do { _Pragma("unroll") for (int n = 0; n < 2; ++n) _Pragma("unroll") for (int k = 0; k < 2; ++k) dst[n][k] = *(const PG8_LAS bf16x8*)(lds + PG8_SB(b, h) + boff + n * 2048 + k * 1024); } while (0)
; #define PG8_MMA(ai, bj, At, Bt) do { __builtin_amdgcn_s_setprio(1); _Pragma("unroll") for (int m = 0; m < 4; ++m) _Pragma("unroll") for (int n = 0; n < 2; ++n) _Pragma("unroll") for (int k = 0; k < 2; ++k) \
;         acc[ai][bj][m][n] = __builtin_amdgcn_mfma_f32_16x16x32_bf16(Bt[n][k], At[m][k], acc[ai][bj][m][n], 0, 0, 0); __builtin_amdgcn_s_setprio(0); } while (0)
; #define PG8_WAIT_V(n) asm volatile("s_waitcnt vmcnt(" #n ")" ::: "memory")
; #define PG8_WAIT_L(n) asm volatile("s_waitcnt lgkmcnt(" #n ")" ::: "memory")
; template <class Epi, class Sched, bool ALIGN_EPI = false, bool SP2 = false>
; __device__ __forceinline__ void gemm_phase(PG8_LAS unsigned char* lds, const Gemm g, const Sched& S, const Epi& E, const int wave_id) {
;     ...
;             const bool last = (t == nt - 2);
;             const char* a1 = cA + (size_t)(t + 1) * kstep;
;             const char* a2 = last ? nA : cA + (size_t)(t + 2) * kstep; const char* b2 = last ? nB : cB + (size_t)(t + 2) * kstep;
;             const char* a3 = a2 + kstep; const char* b3 = b2 + kstep;
;             if (last && has_next) S.a_ready(nxt);
;             if constexpr (SP2) {
;             PG8_LDB(B0, 0, 0); PG8_LDB(B1, 0, 1); PG8_SCHED; PG8_LDA(At, 0, 0); PG8_STAGE(PG8_SA(1, 1), a1 + hstep, voffA);
;             PG8_WAIT_V(8); PG8_WAIT_L(0); PG8_BAR; PG8_MMA(0, 0, At, B0); PG8_MMA(0, 1, At, B1); PG8_BAR; PG8_SCHED;
;     ...
;             PG8_LDA(At, 1, 1); PG8_STAGE(PG8_SB(1, 0), b3, voffB); PG8_STAGE(PG8_SB(1, 1), b3 + hstep, voffB); PG8_STAGE(PG8_SA(1, 0), a3, voffA);
;             PG8_WAIT_V(8); PG8_WAIT_L(0); PG8_BAR; PG8_MMA(1, 0, At, B0); PG8_MMA(1, 1, At, B1); PG8_BAR; PG8_SCHED;
	s_mov_b32 m0, s81
	v_lshl_add_u64 v[226:227], v[226:227], 0, s[30:31]
	ds_read_b128 v[174:177], v140 offset:49152
	ds_read_b128 v[178:181], v140 offset:50176
	ds_read_b128 v[182:185], v140 offset:51200
	ds_read_b128 v[186:189], v140 offset:52224
	ds_read_b128 v[190:193], v140 offset:53248
	ds_read_b128 v[206:209], v140 offset:54272
	ds_read_b128 v[210:213], v140 offset:55296
	ds_read_b128 v[214:217], v140 offset:56320
	global_load_lds_dwordx4 v[226:227], off
	v_lshl_add_u64 v[226:227], v[228:229], 0, s[30:31]
	s_mov_b32 m0, s80
	s_nop 0
	global_load_lds_dwordx4 v[226:227], off
	v_lshl_add_u64 v[226:227], s[42:43], 0, v[132:133]
	s_mov_b32 m0, s97
	s_nop 0
	global_load_lds_dwordx4 v[226:227], off
	v_lshl_add_u64 v[226:227], s[42:43], 0, v[136:137]
	s_mov_b32 m0, s96
	s_nop 0
	global_load_lds_dwordx4 v[226:227], off
	v_lshl_add_u64 v[226:227], v[230:231], 0, s[30:31]
	s_mov_b32 m0, s73
	s_nop 0
	global_load_lds_dwordx4 v[226:227], off
	v_lshl_add_u64 v[226:227], v[234:235], 0, s[30:31]
	s_mov_b32 m0, s74
	s_nop 0
	global_load_lds_dwordx4 v[226:227], off
	s_waitcnt vmcnt(8)
	s_waitcnt lgkmcnt(0)
	s_barrier
	s_setprio 1
	s_waitcnt lgkmcnt(0)
	v_mfma_f32_16x16x32_bf16 v[62:65], v[142:145], v[174:177], v[62:65]
	v_mfma_f32_16x16x32_bf16 v[58:61], v[150:153], v[174:177], v[58:61]
	v_mfma_f32_16x16x32_bf16 v[54:57], v[142:145], v[182:185], v[54:57]
	v_mfma_f32_16x16x32_bf16 v[50:53], v[150:153], v[182:185], v[50:53]
	v_mfma_f32_16x16x32_bf16 v[38:41], v[142:145], v[190:193], v[38:41]
	v_mfma_f32_16x16x32_bf16 v[34:37], v[150:153], v[190:193], v[34:37]
	v_mfma_f32_16x16x32_bf16 v[22:25], v[142:145], v[210:213], v[22:25]
	v_mfma_f32_16x16x32_bf16 v[18:21], v[150:153], v[210:213], v[18:21]
	v_mfma_f32_16x16x32_bf16 v[62:65], v[146:149], v[178:181], v[62:65]
	v_mfma_f32_16x16x32_bf16 v[58:61], v[154:157], v[178:181], v[58:61]
	v_mfma_f32_16x16x32_bf16 v[54:57], v[146:149], v[186:189], v[54:57]
	v_mfma_f32_16x16x32_bf16 v[50:53], v[154:157], v[186:189], v[50:53]
	v_mfma_f32_16x16x32_bf16 v[38:41], v[146:149], v[206:209], v[38:41]
	v_mfma_f32_16x16x32_bf16 v[34:37], v[154:157], v[206:209], v[34:37]
	v_mfma_f32_16x16x32_bf16 v[22:25], v[146:149], v[214:217], v[22:25]
	v_mfma_f32_16x16x32_bf16 v[18:21], v[154:157], v[214:217], v[18:21]
	s_setprio 0
	s_setprio 1
	v_mfma_f32_16x16x32_bf16 v[46:49], v[158:161], v[174:177], v[46:49]
	v_mfma_f32_16x16x32_bf16 v[42:45], v[166:169], v[174:177], v[42:45]
	v_mfma_f32_16x16x32_bf16 v[30:33], v[158:161], v[182:185], v[30:33]
	v_mfma_f32_16x16x32_bf16 v[26:29], v[166:169], v[182:185], v[26:29]
	v_mfma_f32_16x16x32_bf16 v[14:17], v[158:161], v[190:193], v[14:17]
	v_mfma_f32_16x16x32_bf16 v[10:13], v[166:169], v[190:193], v[10:13]
	v_mfma_f32_16x16x32_bf16 v[6:9], v[158:161], v[210:213], v[6:9]
	v_mfma_f32_16x16x32_bf16 v[2:5], v[166:169], v[210:213], v[2:5]
	v_mfma_f32_16x16x32_bf16 v[46:49], v[162:165], v[178:181], v[46:49]
	v_mfma_f32_16x16x32_bf16 v[42:45], v[170:173], v[178:181], v[42:45]
	v_mfma_f32_16x16x32_bf16 v[30:33], v[162:165], v[186:189], v[30:33]
	v_mfma_f32_16x16x32_bf16 v[26:29], v[170:173], v[186:189], v[26:29]
	v_mfma_f32_16x16x32_bf16 v[14:17], v[162:165], v[206:209], v[14:17]
	v_mfma_f32_16x16x32_bf16 v[10:13], v[170:173], v[206:209], v[10:13]
	v_mfma_f32_16x16x32_bf16 v[6:9], v[162:165], v[214:217], v[6:9]
	v_mfma_f32_16x16x32_bf16 v[2:5], v[170:173], v[214:217], v[2:5]
	s_setprio 0
	s_barrier
	s_andn2_b64 vcc, exec, s[40:41]
	s_mov_b64 s[42:43], -1
	s_mov_b64 s[40:41], 0
	s_mov_b64 s[44:45], 0x100
	s_cbranch_vccnz .Lpeel_exit_pp
.LBB0_799:
	s_add_u32 s52, s14, s44
	s_addc_u32 s53, s15, s45
	s_add_u32 s48, s52, 0x100
	s_addc_u32 s49, s53, 0
	s_and_b64 s[46:47], s[42:43], exec
	s_cselect_b32 s47, s19, s49
	s_cselect_b32 s46, s77, s48
	s_add_u32 s44, s12, s44
	s_addc_u32 s45, s13, s45
	s_add_u32 s44, s44, 0x100
	s_addc_u32 s45, s45, 0
	s_add_i32 s96, 0, 0x10000
	s_and_b64 s[42:43], s[42:43], exec
	s_cselect_b32 s49, s17, s45
	s_cselect_b32 s48, s79, s44
	s_add_i32 s43, 0, 0x14000
	s_add_u32 s82, s52, 0x10080
	s_addc_u32 s83, s53, 0
	s_add_i32 s93, s96, s68
	s_add_i32 m0, s69, 0xc000
	s_add_i32 vcc_lo, s69, 0xe000
	s_add_i32 s88, s93, 0x2000
	v_add_u32_e32 v141, s96, v138
	s_add_u32 s52, s48, 0x10000
	ds_read_b128 v[142:145], v141
	ds_read_b128 v[146:149], v141 offset:1024
	ds_read_b128 v[150:153], v141 offset:2048
	ds_read_b128 v[154:157], v141 offset:3072
	v_add_u32_e32 v141, s43, v138
	s_addc_u32 s53, s49, 0
	s_add_i32 s92, s43, s68
	ds_read_b128 v[158:161], v141
	ds_read_b128 v[162:165], v141 offset:1024
	ds_read_b128 v[166:169], v141 offset:2048
	ds_read_b128 v[170:173], v141 offset:3072
	s_add_i32 s89, s92, 0x2000
	s_add_i32 s85, 0, 0x18000
	s_add_i32 s84, 0, 0x1c000
	s_add_u32 s44, s46, 0x10000
	s_addc_u32 s45, s47, 0
	s_add_i32 s81, s85, s68
	s_add_i32 s80, s81, 0x2000
	s_add_u32 s42, s48, 0x10080
	s_addc_u32 s43, s49, 0
	s_add_i32 s97, s84, s68
	s_add_i32 s96, s97, 0x2000
	v_lshl_add_u64 v[226:227], s[82:83], 0, v[130:131]
	ds_read_b128 v[174:177], v140
	ds_read_b128 v[178:181], v140 offset:1024
	ds_read_b128 v[182:185], v140 offset:2048
	ds_read_b128 v[186:189], v140 offset:3072
	ds_read_b128 v[190:193], v140 offset:4096
	ds_read_b128 v[206:209], v140 offset:5120
	ds_read_b128 v[210:213], v140 offset:6144
	ds_read_b128 v[214:217], v140 offset:7168
	global_load_lds_dwordx4 v[226:227], off
	v_lshl_add_u64 v[226:227], s[82:83], 0, v[134:135]
	s_mov_b32 m0, vcc_lo
	s_nop 0
	global_load_lds_dwordx4 v[226:227], off
	s_waitcnt vmcnt(8)
	s_waitcnt lgkmcnt(0)
	s_nop 0
	s_barrier
; #define PG8_STAGE(bufoff, gbase, voff) do { _Pragma("unroll") for (int _i = 0; _i < 2; ++_i) \
;         __builtin_amdgcn_global_load_lds((const unsigned*)((const char*)(gbase) + (voff)[_i]), (PG8_LAS unsigned*)(lds + (bufoff) + ldsw + _i * 8192), 16, 0, 0); } while (0)
; #define PG8_LDA(dst, b, h) do { _Pragma("unroll") for (int m = 0; m < 4; ++m) _Pragma("unroll") for (int k = 0; k < 2; ++k) dst[m][k] = *(const PG8_LAS bf16x8*)(lds + PG8_SA(b, h) + aoff + m * 2048 + k * 1024); } while (0)
; #define PG8_LDB(dst, b, h) do { _Pragma("unroll") for (int n = 0; n < 2; ++n) _Pragma("unroll") for (int k = 0; k < 2; ++k) dst[n][k] = *(const PG8_LAS bf16x8*)(lds + PG8_SB(b, h) + boff + n * 2048 + k * 1024); } while (0)
; #define PG8_MMA(ai, bj, At, Bt) do { __builtin_amdgcn_s_setprio(1); _Pragma("unroll") for (int m = 0; m < 4; ++m) _Pragma("unroll") for (int n = 0; n < 2; ++n) _Pragma("unroll") for (int k = 0; k < 2; ++k) \
;         acc[ai][bj][m][n] = __builtin_amdgcn_mfma_f32_16x16x32_bf16(Bt[n][k], At[m][k], acc[ai][bj][m][n], 0, 0, 0); __builtin_amdgcn_s_setprio(0); } while (0)
; #define PG8_WAIT_V(n) asm volatile("s_waitcnt vmcnt(" #n ")" ::: "memory")
; #define PG8_WAIT_L(n) asm volatile("s_waitcnt lgkmcnt(" #n ")" ::: "memory")
; #define PG8_BAR __builtin_amdgcn_s_barrier()
; #define PG8_SCHED __builtin_amdgcn_sched_barrier(0)
; template <class Epi, class Sched, bool ALIGN_EPI = false, bool SP2 = false>
; __device__ __forceinline__ void gemm_phase(PG8_LAS unsigned char* lds, const Gemm g, const Sched& S, const Epi& E, const int wave_id) {
;     ...
;             PG8_WAIT_V(8); PG8_WAIT_L(0); PG8_BAR; PG8_MMA(0, 0, At, B0); PG8_MMA(0, 1, At, B1); PG8_BAR; PG8_SCHED;
;             PG8_LDA(At, 0, 1); PG8_STAGE(PG8_SB(0, 0), b2, voffB); PG8_STAGE(PG8_SB(0, 1), b2 + hstep, voffB); PG8_STAGE(PG8_SA(0, 0), a2, voffA);
;             PG8_WAIT_V(8); PG8_WAIT_L(0); PG8_BAR; PG8_MMA(1, 0, At, B0); PG8_MMA(1, 1, At, B1); PG8_BAR; PG8_SCHED;
;             PG8_LDB(B0, 1, 0); PG8_LDB(B1, 1, 1); PG8_SCHED; PG8_LDA(At, 1, 0); PG8_STAGE(PG8_SA(0, 1), a2 + hstep, voffA);
;             PG8_WAIT_V(8); PG8_WAIT_L(0); PG8_BAR; PG8_MMA(0, 0, At, B0); PG8_MMA(0, 1, At, B1); PG8_BAR; PG8_SCHED;
	s_setprio 1
	s_waitcnt lgkmcnt(0)
	v_mfma_f32_16x16x32_bf16 v[126:129], v[142:145], v[174:177], v[126:129]
	v_mfma_f32_16x16x32_bf16 v[122:125], v[150:153], v[174:177], v[122:125]
	v_mfma_f32_16x16x32_bf16 v[118:121], v[142:145], v[182:185], v[118:121]
	v_mfma_f32_16x16x32_bf16 v[114:117], v[150:153], v[182:185], v[114:117]
	v_mfma_f32_16x16x32_bf16 v[102:105], v[142:145], v[190:193], v[102:105]
	v_mfma_f32_16x16x32_bf16 v[98:101], v[150:153], v[190:193], v[98:101]
	v_mfma_f32_16x16x32_bf16 v[86:89], v[142:145], v[210:213], v[86:89]
	v_mfma_f32_16x16x32_bf16 v[82:85], v[150:153], v[210:213], v[82:85]
	v_mfma_f32_16x16x32_bf16 v[126:129], v[146:149], v[178:181], v[126:129]
	v_mfma_f32_16x16x32_bf16 v[122:125], v[154:157], v[178:181], v[122:125]
	v_mfma_f32_16x16x32_bf16 v[118:121], v[146:149], v[186:189], v[118:121]
	v_mfma_f32_16x16x32_bf16 v[114:117], v[154:157], v[186:189], v[114:117]
	v_mfma_f32_16x16x32_bf16 v[102:105], v[146:149], v[206:209], v[102:105]
	v_mfma_f32_16x16x32_bf16 v[98:101], v[154:157], v[206:209], v[98:101]
	v_mfma_f32_16x16x32_bf16 v[86:89], v[146:149], v[214:217], v[86:89]
	v_mfma_f32_16x16x32_bf16 v[82:85], v[154:157], v[214:217], v[82:85]
	s_setprio 0
	s_setprio 1
	v_mfma_f32_16x16x32_bf16 v[110:113], v[158:161], v[174:177], v[110:113]
	v_mfma_f32_16x16x32_bf16 v[106:109], v[166:169], v[174:177], v[106:109]
	v_mfma_f32_16x16x32_bf16 v[94:97], v[158:161], v[182:185], v[94:97]
	v_mfma_f32_16x16x32_bf16 v[90:93], v[166:169], v[182:185], v[90:93]
	v_mfma_f32_16x16x32_bf16 v[78:81], v[158:161], v[190:193], v[78:81]
	v_mfma_f32_16x16x32_bf16 v[74:77], v[166:169], v[190:193], v[74:77]
	v_mfma_f32_16x16x32_bf16 v[70:73], v[158:161], v[210:213], v[70:73]
	v_mfma_f32_16x16x32_bf16 v[66:69], v[166:169], v[210:213], v[66:69]
	v_mfma_f32_16x16x32_bf16 v[110:113], v[162:165], v[178:181], v[110:113]
	v_mfma_f32_16x16x32_bf16 v[106:109], v[170:173], v[178:181], v[106:109]
	v_mfma_f32_16x16x32_bf16 v[94:97], v[162:165], v[186:189], v[94:97]
	v_mfma_f32_16x16x32_bf16 v[90:93], v[170:173], v[186:189], v[90:93]
	v_mfma_f32_16x16x32_bf16 v[78:81], v[162:165], v[206:209], v[78:81]
	v_mfma_f32_16x16x32_bf16 v[74:77], v[170:173], v[206:209], v[74:77]
	v_mfma_f32_16x16x32_bf16 v[70:73], v[162:165], v[214:217], v[70:73]
	v_mfma_f32_16x16x32_bf16 v[66:69], v[170:173], v[214:217], v[66:69]
	s_setprio 0
	s_barrier
	s_mov_b32 m0, s93
	v_lshl_add_u64 v[226:227], s[48:49], 0, v[132:133]
	ds_read_b128 v[174:177], v140 offset:16384
	ds_read_b128 v[178:181], v140 offset:17408
	ds_read_b128 v[182:185], v140 offset:18432
	ds_read_b128 v[186:189], v140 offset:19456
	ds_read_b128 v[190:193], v140 offset:20480
	ds_read_b128 v[206:209], v140 offset:21504
	ds_read_b128 v[210:213], v140 offset:22528
	ds_read_b128 v[214:217], v140 offset:23552
	global_load_lds_dwordx4 v[226:227], off
	v_lshl_add_u64 v[228:229], s[48:49], 0, v[136:137]
	s_mov_b32 m0, s88
	v_lshl_add_u64 v[230:231], s[52:53], 0, v[132:133]
	global_load_lds_dwordx4 v[228:229], off
	s_mov_b32 m0, s92
	v_lshl_add_u64 v[234:235], s[46:47], 0, v[134:135]
	global_load_lds_dwordx4 v[230:231], off
	v_lshl_add_u64 v[230:231], s[52:53], 0, v[136:137]
	s_mov_b32 m0, s89
	s_nop 0
	global_load_lds_dwordx4 v[230:231], off
	v_lshl_add_u64 v[230:231], s[46:47], 0, v[130:131]
	s_mov_b32 m0, s69
	s_nop 0
	global_load_lds_dwordx4 v[230:231], off
	s_mov_b32 m0, s70
	s_nop 0
	global_load_lds_dwordx4 v[234:235], off
	s_waitcnt vmcnt(8)
	s_waitcnt lgkmcnt(0)
	s_barrier
	s_setprio 1
	s_waitcnt lgkmcnt(0)
	v_mfma_f32_16x16x32_bf16 v[62:65], v[142:145], v[174:177], v[62:65]
	v_mfma_f32_16x16x32_bf16 v[58:61], v[150:153], v[174:177], v[58:61]
	v_mfma_f32_16x16x32_bf16 v[54:57], v[142:145], v[182:185], v[54:57]
	v_mfma_f32_16x16x32_bf16 v[50:53], v[150:153], v[182:185], v[50:53]
	v_mfma_f32_16x16x32_bf16 v[38:41], v[142:145], v[190:193], v[38:41]
	v_mfma_f32_16x16x32_bf16 v[34:37], v[150:153], v[190:193], v[34:37]
	v_mfma_f32_16x16x32_bf16 v[22:25], v[142:145], v[210:213], v[22:25]
	v_mfma_f32_16x16x32_bf16 v[18:21], v[150:153], v[210:213], v[18:21]
	v_mfma_f32_16x16x32_bf16 v[62:65], v[146:149], v[178:181], v[62:65]
	v_mfma_f32_16x16x32_bf16 v[58:61], v[154:157], v[178:181], v[58:61]
	v_mfma_f32_16x16x32_bf16 v[54:57], v[146:149], v[186:189], v[54:57]
	v_mfma_f32_16x16x32_bf16 v[50:53], v[154:157], v[186:189], v[50:53]
	v_mfma_f32_16x16x32_bf16 v[38:41], v[146:149], v[206:209], v[38:41]
	v_mfma_f32_16x16x32_bf16 v[34:37], v[154:157], v[206:209], v[34:37]
	v_mfma_f32_16x16x32_bf16 v[22:25], v[146:149], v[214:217], v[22:25]
	v_mfma_f32_16x16x32_bf16 v[18:21], v[154:157], v[214:217], v[18:21]
	s_setprio 0
	s_setprio 1
	v_mfma_f32_16x16x32_bf16 v[46:49], v[158:161], v[174:177], v[46:49]
	v_mfma_f32_16x16x32_bf16 v[42:45], v[166:169], v[174:177], v[42:45]
	v_mfma_f32_16x16x32_bf16 v[30:33], v[158:161], v[182:185], v[30:33]
	v_mfma_f32_16x16x32_bf16 v[26:29], v[166:169], v[182:185], v[26:29]
	v_mfma_f32_16x16x32_bf16 v[14:17], v[158:161], v[190:193], v[14:17]
	v_mfma_f32_16x16x32_bf16 v[10:13], v[166:169], v[190:193], v[10:13]
	v_mfma_f32_16x16x32_bf16 v[6:9], v[158:161], v[210:213], v[6:9]
	v_mfma_f32_16x16x32_bf16 v[2:5], v[166:169], v[210:213], v[2:5]
	v_mfma_f32_16x16x32_bf16 v[46:49], v[162:165], v[178:181], v[46:49]
	v_mfma_f32_16x16x32_bf16 v[42:45], v[170:173], v[178:181], v[42:45]
	v_mfma_f32_16x16x32_bf16 v[30:33], v[162:165], v[186:189], v[30:33]
	v_mfma_f32_16x16x32_bf16 v[26:29], v[170:173], v[186:189], v[26:29]
	v_mfma_f32_16x16x32_bf16 v[14:17], v[162:165], v[206:209], v[14:17]
	v_mfma_f32_16x16x32_bf16 v[10:13], v[170:173], v[206:209], v[10:13]
	v_mfma_f32_16x16x32_bf16 v[6:9], v[162:165], v[214:217], v[6:9]
	v_mfma_f32_16x16x32_bf16 v[2:5], v[170:173], v[214:217], v[2:5]
	s_setprio 0
	s_barrier
; #define PG8_STAGE(bufoff, gbase, voff) do { _Pragma("unroll") for (int _i = 0; _i < 2; ++_i) \
;         __builtin_amdgcn_global_load_lds((const unsigned*)((const char*)(gbase) + (voff)[_i]), (PG8_LAS unsigned*)(lds + (bufoff) + ldsw + _i * 8192), 16, 0, 0); } while (0)
; #define PG8_LDA(dst, b, h) do { _Pragma("unroll") for (int m = 0; m < 4; ++m) _Pragma("unroll") for (int k = 0; k < 2; ++k) dst[m][k] = *(const PG8_LAS bf16x8*)(lds + PG8_SA(b, h) + aoff + m * 2048 + k * 1024); } while (0)
; #define PG8_LDB(dst, b, h) do { _Pragma("unroll") for (int n = 0; n < 2; ++n) _Pragma("unroll") for (int k = 0; k < 2; ++k) dst[n][k] = *(const PG8_LAS bf16x8*)(lds + PG8_SB(b, h) + boff + n * 2048 + k * 1024); } while (0)
; #define PG8_MMA(ai, bj, At, Bt) do { __builtin_amdgcn_s_setprio(1); _Pragma("unroll") for (int m = 0; m < 4; ++m) _Pragma("unroll") for (int n = 0; n < 2; ++n) _Pragma("unroll") for (int k = 0; k < 2; ++k) \
;         acc[ai][bj][m][n] = __builtin_amdgcn_mfma_f32_16x16x32_bf16(Bt[n][k], At[m][k], acc[ai][bj][m][n], 0, 0, 0); __builtin_amdgcn_s_setprio(0); } while (0)
; #define PG8_WAIT_V(n) asm volatile("s_waitcnt vmcnt(" #n ")" ::: "memory")
; #define PG8_WAIT_L(n) asm volatile("s_waitcnt lgkmcnt(" #n ")" ::: "memory")
; #define PG8_BAR __builtin_amdgcn_s_barrier()
; #define PG8_SCHED __builtin_amdgcn_sched_barrier(0)
; template <class Epi, class Sched, bool ALIGN_EPI = false, bool SP2 = false>
; __device__ __forceinline__ void gemm_phase(PG8_LAS unsigned char* lds, const Gemm g, const Sched& S, const Epi& E, const int wave_id) {
;     ...
;             PG8_LDB(B0, 1, 0); PG8_LDB(B1, 1, 1); PG8_SCHED; PG8_LDA(At, 1, 0); PG8_STAGE(PG8_SA(0, 1), a2 + hstep, voffA);
;             PG8_WAIT_V(8); PG8_WAIT_L(0); PG8_BAR; PG8_MMA(0, 0, At, B0); PG8_MMA(0, 1, At, B1); PG8_BAR; PG8_SCHED;
;             PG8_LDA(At, 1, 1); PG8_STAGE(PG8_SB(1, 0), b3, voffB); PG8_STAGE(PG8_SB(1, 1), b3 + hstep, voffB); PG8_STAGE(PG8_SA(1, 0), a3, voffA);
;             PG8_WAIT_V(8); PG8_WAIT_L(0); PG8_BAR; PG8_MMA(1, 0, At, B0); PG8_MMA(1, 1, At, B1); PG8_BAR; PG8_SCHED;
	v_add_u32_e32 v141, s85, v138
	ds_read_b128 v[142:145], v141
	ds_read_b128 v[146:149], v141 offset:1024
	ds_read_b128 v[150:153], v141 offset:2048
	ds_read_b128 v[154:157], v141 offset:3072
	v_add_u32_e32 v141, s84, v138
	ds_read_b128 v[158:161], v141
	ds_read_b128 v[162:165], v141 offset:1024
	ds_read_b128 v[166:169], v141 offset:2048
	ds_read_b128 v[170:173], v141 offset:3072
	s_mov_b32 m0, s71
	v_lshl_add_u64 v[236:237], s[44:45], 0, v[130:131]
	ds_read_b128 v[174:177], v140 offset:32768
	ds_read_b128 v[178:181], v140 offset:33792
	ds_read_b128 v[182:185], v140 offset:34816
	ds_read_b128 v[186:189], v140 offset:35840
	ds_read_b128 v[190:193], v140 offset:36864
	ds_read_b128 v[206:209], v140 offset:37888
	ds_read_b128 v[210:213], v140 offset:38912
	ds_read_b128 v[214:217], v140 offset:39936
	global_load_lds_dwordx4 v[236:237], off
	v_lshl_add_u64 v[236:237], s[44:45], 0, v[134:135]
	s_mov_b32 m0, s72
	s_nop 0
	global_load_lds_dwordx4 v[236:237], off
	s_waitcnt vmcnt(8)
	s_waitcnt lgkmcnt(0)
	s_barrier
	s_setprio 1
	s_waitcnt lgkmcnt(0)
	v_mfma_f32_16x16x32_bf16 v[126:129], v[142:145], v[174:177], v[126:129]
	v_mfma_f32_16x16x32_bf16 v[122:125], v[150:153], v[174:177], v[122:125]
	v_mfma_f32_16x16x32_bf16 v[118:121], v[142:145], v[182:185], v[118:121]
	v_mfma_f32_16x16x32_bf16 v[114:117], v[150:153], v[182:185], v[114:117]
	v_mfma_f32_16x16x32_bf16 v[102:105], v[142:145], v[190:193], v[102:105]
	v_mfma_f32_16x16x32_bf16 v[98:101], v[150:153], v[190:193], v[98:101]
	v_mfma_f32_16x16x32_bf16 v[86:89], v[142:145], v[210:213], v[86:89]
	v_mfma_f32_16x16x32_bf16 v[82:85], v[150:153], v[210:213], v[82:85]
	v_mfma_f32_16x16x32_bf16 v[126:129], v[146:149], v[178:181], v[126:129]
	v_mfma_f32_16x16x32_bf16 v[122:125], v[154:157], v[178:181], v[122:125]
	v_mfma_f32_16x16x32_bf16 v[118:121], v[146:149], v[186:189], v[118:121]
	v_mfma_f32_16x16x32_bf16 v[114:117], v[154:157], v[186:189], v[114:117]
	v_mfma_f32_16x16x32_bf16 v[102:105], v[146:149], v[206:209], v[102:105]
	v_mfma_f32_16x16x32_bf16 v[98:101], v[154:157], v[206:209], v[98:101]
	v_mfma_f32_16x16x32_bf16 v[86:89], v[146:149], v[214:217], v[86:89]
	v_mfma_f32_16x16x32_bf16 v[82:85], v[154:157], v[214:217], v[82:85]
	s_setprio 0
	s_setprio 1
	v_mfma_f32_16x16x32_bf16 v[110:113], v[158:161], v[174:177], v[110:113]
	v_mfma_f32_16x16x32_bf16 v[106:109], v[166:169], v[174:177], v[106:109]
	v_mfma_f32_16x16x32_bf16 v[94:97], v[158:161], v[182:185], v[94:97]
	v_mfma_f32_16x16x32_bf16 v[90:93], v[166:169], v[182:185], v[90:93]
	v_mfma_f32_16x16x32_bf16 v[78:81], v[158:161], v[190:193], v[78:81]
	v_mfma_f32_16x16x32_bf16 v[74:77], v[166:169], v[190:193], v[74:77]
	v_mfma_f32_16x16x32_bf16 v[70:73], v[158:161], v[210:213], v[70:73]
	v_mfma_f32_16x16x32_bf16 v[66:69], v[166:169], v[210:213], v[66:69]
	v_mfma_f32_16x16x32_bf16 v[110:113], v[162:165], v[178:181], v[110:113]
	v_mfma_f32_16x16x32_bf16 v[106:109], v[170:173], v[178:181], v[106:109]
	v_mfma_f32_16x16x32_bf16 v[94:97], v[162:165], v[186:189], v[94:97]
	v_mfma_f32_16x16x32_bf16 v[90:93], v[170:173], v[186:189], v[90:93]
	v_mfma_f32_16x16x32_bf16 v[78:81], v[162:165], v[206:209], v[78:81]
	v_mfma_f32_16x16x32_bf16 v[74:77], v[170:173], v[206:209], v[74:77]
	v_mfma_f32_16x16x32_bf16 v[70:73], v[162:165], v[214:217], v[70:73]
	v_mfma_f32_16x16x32_bf16 v[66:69], v[170:173], v[214:217], v[66:69]
	s_setprio 0
	s_barrier
	s_mov_b32 m0, s81
	v_lshl_add_u64 v[226:227], v[226:227], 0, s[30:31]
	ds_read_b128 v[174:177], v140 offset:49152
	ds_read_b128 v[178:181], v140 offset:50176
	ds_read_b128 v[182:185], v140 offset:51200
	ds_read_b128 v[186:189], v140 offset:52224
	ds_read_b128 v[190:193], v140 offset:53248
	ds_read_b128 v[206:209], v140 offset:54272
	ds_read_b128 v[210:213], v140 offset:55296
	ds_read_b128 v[214:217], v140 offset:56320
	global_load_lds_dwordx4 v[226:227], off
	v_lshl_add_u64 v[226:227], v[228:229], 0, s[30:31]
	s_mov_b32 m0, s80
	s_nop 0
	global_load_lds_dwordx4 v[226:227], off
	v_lshl_add_u64 v[226:227], s[42:43], 0, v[132:133]
	s_mov_b32 m0, s97
	s_nop 0
	global_load_lds_dwordx4 v[226:227], off
	v_lshl_add_u64 v[226:227], s[42:43], 0, v[136:137]
	s_mov_b32 m0, s96
	s_nop 0
	global_load_lds_dwordx4 v[226:227], off
	v_lshl_add_u64 v[226:227], v[230:231], 0, s[30:31]
	s_mov_b32 m0, s73
	s_nop 0
	global_load_lds_dwordx4 v[226:227], off
	v_lshl_add_u64 v[226:227], v[234:235], 0, s[30:31]
	s_mov_b32 m0, s74
	s_nop 0
	global_load_lds_dwordx4 v[226:227], off
	s_waitcnt vmcnt(8)
	s_waitcnt lgkmcnt(0)
	s_barrier
	s_setprio 1
	s_waitcnt lgkmcnt(0)
	v_mfma_f32_16x16x32_bf16 v[62:65], v[142:145], v[174:177], v[62:65]
	v_mfma_f32_16x16x32_bf16 v[58:61], v[150:153], v[174:177], v[58:61]
	v_mfma_f32_16x16x32_bf16 v[54:57], v[142:145], v[182:185], v[54:57]
	v_mfma_f32_16x16x32_bf16 v[50:53], v[150:153], v[182:185], v[50:53]
	v_mfma_f32_16x16x32_bf16 v[38:41], v[142:145], v[190:193], v[38:41]
	v_mfma_f32_16x16x32_bf16 v[34:37], v[150:153], v[190:193], v[34:37]
	v_mfma_f32_16x16x32_bf16 v[22:25], v[142:145], v[210:213], v[22:25]
	v_mfma_f32_16x16x32_bf16 v[18:21], v[150:153], v[210:213], v[18:21]
	v_mfma_f32_16x16x32_bf16 v[62:65], v[146:149], v[178:181], v[62:65]
	v_mfma_f32_16x16x32_bf16 v[58:61], v[154:157], v[178:181], v[58:61]
	v_mfma_f32_16x16x32_bf16 v[54:57], v[146:149], v[186:189], v[54:57]
	v_mfma_f32_16x16x32_bf16 v[50:53], v[154:157], v[186:189], v[50:53]
	v_mfma_f32_16x16x32_bf16 v[38:41], v[146:149], v[206:209], v[38:41]
	v_mfma_f32_16x16x32_bf16 v[34:37], v[154:157], v[206:209], v[34:37]
	v_mfma_f32_16x16x32_bf16 v[22:25], v[146:149], v[214:217], v[22:25]
	v_mfma_f32_16x16x32_bf16 v[18:21], v[154:157], v[214:217], v[18:21]
	s_setprio 0
	s_setprio 1
	v_mfma_f32_16x16x32_bf16 v[46:49], v[158:161], v[174:177], v[46:49]
	v_mfma_f32_16x16x32_bf16 v[42:45], v[166:169], v[174:177], v[42:45]
	v_mfma_f32_16x16x32_bf16 v[30:33], v[158:161], v[182:185], v[30:33]
	v_mfma_f32_16x16x32_bf16 v[26:29], v[166:169], v[182:185], v[26:29]
	v_mfma_f32_16x16x32_bf16 v[14:17], v[158:161], v[190:193], v[14:17]
	v_mfma_f32_16x16x32_bf16 v[10:13], v[166:169], v[190:193], v[10:13]
	v_mfma_f32_16x16x32_bf16 v[6:9], v[158:161], v[210:213], v[6:9]
	v_mfma_f32_16x16x32_bf16 v[2:5], v[166:169], v[210:213], v[2:5]
	v_mfma_f32_16x16x32_bf16 v[46:49], v[162:165], v[178:181], v[46:49]
	v_mfma_f32_16x16x32_bf16 v[42:45], v[170:173], v[178:181], v[42:45]
	v_mfma_f32_16x16x32_bf16 v[30:33], v[162:165], v[186:189], v[30:33]
	v_mfma_f32_16x16x32_bf16 v[26:29], v[170:173], v[186:189], v[26:29]
	v_mfma_f32_16x16x32_bf16 v[14:17], v[162:165], v[206:209], v[14:17]
	v_mfma_f32_16x16x32_bf16 v[10:13], v[170:173], v[206:209], v[10:13]
	v_mfma_f32_16x16x32_bf16 v[6:9], v[162:165], v[214:217], v[6:9]
	v_mfma_f32_16x16x32_bf16 v[2:5], v[170:173], v[214:217], v[2:5]
	s_setprio 0
	s_barrier
	s_andn2_b64 vcc, exec, s[40:41]
	s_mov_b64 s[42:43], -1
	s_mov_b64 s[40:41], 0
	s_mov_b64 s[44:45], 0x100
	s_cbranch_vccz .LBB0_799

;     __host__ __device__ bool next(int i, Unit& u) const { const bool ok = StaticOrder::next(i, u); u.lm = 0; u.ln = 0; return ok; }
; #define PG8_STAGE(bufoff, gbase, voff) do { _Pragma("unroll") for (int _i = 0; _i < 2; ++_i) \
;         __builtin_amdgcn_global_load_lds((const unsigned*)((const char*)(gbase) + (voff)[_i]), (PG8_LAS unsigned*)(lds + (bufoff) + ldsw + _i * 8192), 16, 0, 0); } while (0)
; #define PG8_LDA(dst, b, h) do { _Pragma("unroll") for (int m = 0; m < 4; ++m) _Pragma("unroll") for (int k = 0; k < 2; ++k) dst[m][k] = *(const PG8_LAS bf16x8*)(lds + PG8_SA(b, h) + aoff + m * 2048 + k * 1024); } while (0)
; #define PG8_LDB(dst, b, h) do { _Pragma("unroll") for (int n = 0; n < 2; ++n) _Pragma("unroll") for (int k = 0; k < 2; ++k) dst[n][k] = *(const PG8_LAS bf16x8*)(lds + PG8_SB(b, h) + boff + n * 2048 + k * 1024); } while (0)
; #define PG8_WAIT_V(n) asm volatile("s_waitcnt vmcnt(" #n ")" ::: "memory")
; #define PG8_BAR __builtin_amdgcn_s_barrier()
; template <class Epi, class Sched, bool ALIGN_EPI = false, bool SP2 = false>
; __device__ __forceinline__ void gemm_phase(PG8_LAS unsigned char* lds, const Gemm g, const Sched& S, const Epi& E, const int wave_id) {
;     ...
;         const bool has_next = S.next(ui + 1, nxt);
;         const char* nA = has_next ? (const char*)g.A + (size_t)nxt.lm * tstep : cA; const char* nB = has_next ? (const char*)g.Bt + (size_t)nxt.ln * tstep : cB;
; #pragma unroll 1
;         for (int t = 0; t < nt; t += 2) {
;             const bool last = (t == nt - 2);
;             const char* a1 = cA + (size_t)(t + 1) * kstep;
;             const char* a2 = last ? nA : cA + (size_t)(t + 2) * kstep; const char* b2 = last ? nB : cB + (size_t)(t + 2) * kstep;
;             const char* a3 = a2 + kstep; const char* b3 = b2 + kstep;
;             if (last && has_next) S.a_ready(nxt);
;             if constexpr (SP2) {
;             PG8_LDB(B0, 0, 0); PG8_LDB(B1, 0, 1); PG8_SCHED; PG8_LDA(At, 0, 0); PG8_STAGE(PG8_SA(1, 1), a1 + hstep, voffA);
;             PG8_WAIT_V(8); PG8_WAIT_L(0); PG8_BAR; PG8_MMA(0, 0, At, B0); PG8_MMA(0, 1, At, B1); PG8_BAR; PG8_SCHED;
;             PG8_LDA(At, 0, 1); PG8_STAGE(PG8_SB(0, 0), b2, voffB); PG8_STAGE(PG8_SB(0, 1), b2 + hstep, voffB); PG8_STAGE(PG8_SA(0, 0), a2, voffA);
;             PG8_WAIT_V(8); PG8_WAIT_L(0); PG8_BAR; PG8_MMA(1, 0, At, B0); PG8_MMA(1, 1, At, B1); PG8_BAR; PG8_SCHED;
.LBB0_903:
	s_ashr_i32 s21, s20, 31
	s_lshl_b64 s[42:43], s[20:21], 20
	s_add_u32 s42, s8, s42
	s_addc_u32 s43, s9, s43
	s_and_b64 s[44:45], s[40:41], exec
	s_cselect_b32 s21, s43, s47
	s_cselect_b32 s49, s42, s46
	s_ashr_i32 s19, s18, 31
	s_lshl_b64 s[44:45], s[18:19], 20
	s_add_u32 s44, s65, s44
	s_addc_u32 s45, s68, s45
	s_and_b64 s[80:81], s[40:41], exec
	s_cselect_b32 s19, s45, s53
	s_cselect_b32 s79, s44, s52
	s_add_u32 s46, s46, 0x80080
	s_addc_u32 s47, s47, 0
	s_add_u32 s80, s52, 0x100
	s_addc_u32 s81, s53, 0
	s_mov_b32 s84, -2
	v_add_u32_e32 v226, 0x10000, v237
	s_add_u32 s52, s46, 0xfff80080
	s_addc_u32 s53, s47, -1
	s_add_i32 s85, 0, 0x10000
	s_cmp_eq_u32 s84, 28
	s_cselect_b32 s83, s21, s53
	s_cselect_b32 s82, s49, s52
	s_cselect_b32 s53, s19, s81
	s_cselect_b32 s52, s79, s80
	s_add_i32 s92, 0, 0x14000
	s_add_i32 m0, s70, 0xc000
	s_nop 0
	global_load_lds_dwordx4 v214, s[46:47]
	ds_read_b128 v[114:117], v226
	ds_read_b128 v[118:121], v226 offset:1024
	ds_read_b128 v[130:133], v226 offset:2048
	ds_read_b128 v[134:137], v226 offset:3072
	ds_read_b128 v[138:141], v226 offset:16384
	ds_read_b128 v[142:145], v226 offset:17408
	ds_read_b128 v[146:149], v226 offset:18432
	ds_read_b128 v[150:153], v226 offset:19456
	s_add_i32 m0, s70, 0xe000
	s_nop 0
	global_load_lds_dwordx4 v216, s[46:47]
	ds_read_b128 v[162:165], v244
	ds_read_b128 v[166:169], v244 offset:1024
	ds_read_b128 v[170:173], v244 offset:2048
	ds_read_b128 v[174:177], v244 offset:3072
	ds_read_b128 v[178:181], v244 offset:4096
	ds_read_b128 v[182:185], v244 offset:5120
	ds_read_b128 v[186:189], v244 offset:6144
	ds_read_b128 v[190:193], v244 offset:7168
	s_waitcnt vmcnt(8)
	s_waitcnt lgkmcnt(0)
	s_nop 0
	s_barrier
	s_setprio 1
	s_waitcnt lgkmcnt(0)
	v_mfma_f32_16x16x32_bf16 v[158:161], v[114:117], v[162:165], 0
	v_mfma_f32_16x16x32_bf16 v[154:157], v[130:133], v[162:165], 0
	v_mfma_f32_16x16x32_bf16 v[110:113], v[114:117], v[170:173], 0
	v_mfma_f32_16x16x32_bf16 v[106:109], v[130:133], v[170:173], 0
	v_mfma_f32_16x16x32_bf16 v[94:97], v[114:117], v[178:181], 0
	v_mfma_f32_16x16x32_bf16 v[90:93], v[130:133], v[178:181], 0
	v_mfma_f32_16x16x32_bf16 v[78:81], v[114:117], v[186:189], 0
	v_mfma_f32_16x16x32_bf16 v[74:77], v[130:133], v[186:189], 0
	v_mfma_f32_16x16x32_bf16 v[158:161], v[118:121], v[166:169], v[158:161]
	v_mfma_f32_16x16x32_bf16 v[154:157], v[134:137], v[166:169], v[154:157]
	v_mfma_f32_16x16x32_bf16 v[110:113], v[118:121], v[174:177], v[110:113]
	v_mfma_f32_16x16x32_bf16 v[106:109], v[134:137], v[174:177], v[106:109]
	v_mfma_f32_16x16x32_bf16 v[94:97], v[118:121], v[182:185], v[94:97]
	v_mfma_f32_16x16x32_bf16 v[90:93], v[134:137], v[182:185], v[90:93]
	v_mfma_f32_16x16x32_bf16 v[78:81], v[118:121], v[190:193], v[78:81]
	v_mfma_f32_16x16x32_bf16 v[74:77], v[134:137], v[190:193], v[74:77]
	s_setprio 0
	s_setprio 1
	v_mfma_f32_16x16x32_bf16 v[126:129], v[138:141], v[162:165], 0
	v_mfma_f32_16x16x32_bf16 v[122:125], v[146:149], v[162:165], 0
	v_mfma_f32_16x16x32_bf16 v[102:105], v[138:141], v[170:173], 0
	v_mfma_f32_16x16x32_bf16 v[98:101], v[146:149], v[170:173], 0
	v_mfma_f32_16x16x32_bf16 v[86:89], v[138:141], v[178:181], 0
	v_mfma_f32_16x16x32_bf16 v[82:85], v[146:149], v[178:181], 0
	v_mfma_f32_16x16x32_bf16 v[70:73], v[138:141], v[186:189], 0
	v_mfma_f32_16x16x32_bf16 v[66:69], v[146:149], v[186:189], 0
	v_mfma_f32_16x16x32_bf16 v[126:129], v[142:145], v[166:169], v[126:129]
	v_mfma_f32_16x16x32_bf16 v[122:125], v[150:153], v[166:169], v[122:125]
	v_mfma_f32_16x16x32_bf16 v[102:105], v[142:145], v[174:177], v[102:105]
	v_mfma_f32_16x16x32_bf16 v[98:101], v[150:153], v[174:177], v[98:101]
	v_mfma_f32_16x16x32_bf16 v[86:89], v[142:145], v[182:185], v[86:89]
	v_mfma_f32_16x16x32_bf16 v[82:85], v[150:153], v[182:185], v[82:85]
	v_mfma_f32_16x16x32_bf16 v[70:73], v[142:145], v[190:193], v[70:73]
	v_mfma_f32_16x16x32_bf16 v[66:69], v[150:153], v[190:193], v[66:69]
	s_setprio 0
	s_barrier
	s_add_i32 s85, s85, s69
	s_mov_b32 m0, s85
	s_nop 0
	global_load_lds_dwordx4 v208, s[52:53]
	ds_read_b128 v[162:165], v244 offset:16384
	ds_read_b128 v[166:169], v244 offset:17408
	s_add_i32 m0, s85, 0x2000
	s_add_u32 s88, s52, 0x80000
	s_addc_u32 s89, s53, 0
	s_add_i32 s85, s92, s69
	global_load_lds_dwordx4 v212, s[52:53]
	ds_read_b128 v[170:173], v244 offset:18432
	ds_read_b128 v[174:177], v244 offset:19456
	s_mov_b32 m0, s85
	s_nop 0
	global_load_lds_dwordx4 v208, s[88:89]
	ds_read_b128 v[178:181], v244 offset:20480
	ds_read_b128 v[182:185], v244 offset:21504
	s_add_i32 m0, s85, 0x2000
	s_nop 0
	global_load_lds_dwordx4 v212, s[88:89]
	ds_read_b128 v[186:189], v244 offset:22528
	ds_read_b128 v[190:193], v244 offset:23552
	s_mov_b32 m0, s70
	s_nop 0
	global_load_lds_dwordx4 v206, s[82:83]
	s_mov_b32 m0, s71
	s_nop 0
	global_load_lds_dwordx4 v210, s[82:83]
	s_waitcnt vmcnt(8)
	s_waitcnt lgkmcnt(0)
	s_nop 0
	s_barrier
; #define PG8_STAGE(bufoff, gbase, voff) do { _Pragma("unroll") for (int _i = 0; _i < 2; ++_i) \
;         __builtin_amdgcn_global_load_lds((const unsigned*)((const char*)(gbase) + (voff)[_i]), (PG8_LAS unsigned*)(lds + (bufoff) + ldsw + _i * 8192), 16, 0, 0); } while (0)
; #define PG8_LDA(dst, b, h) do { _Pragma("unroll") for (int m = 0; m < 4; ++m) _Pragma("unroll") for (int k = 0; k < 2; ++k) dst[m][k] = *(const PG8_LAS bf16x8*)(lds + PG8_SA(b, h) + aoff + m * 2048 + k * 1024); } while (0)
; #define PG8_LDB(dst, b, h) do { _Pragma("unroll") for (int n = 0; n < 2; ++n) _Pragma("unroll") for (int k = 0; k < 2; ++k) dst[n][k] = *(const PG8_LAS bf16x8*)(lds + PG8_SB(b, h) + boff + n * 2048 + k * 1024); } while (0)
; #define PG8_MMA(ai, bj, At, Bt) do { __builtin_amdgcn_s_setprio(1); _Pragma("unroll") for (int m = 0; m < 4; ++m) _Pragma("unroll") for (int n = 0; n < 2; ++n) _Pragma("unroll") for (int k = 0; k < 2; ++k) \
;         acc[ai][bj][m][n] = __builtin_amdgcn_mfma_f32_16x16x32_bf16(Bt[n][k], At[m][k], acc[ai][bj][m][n], 0, 0, 0); __builtin_amdgcn_s_setprio(0); } while (0)
; #define PG8_WAIT_V(n) asm volatile("s_waitcnt vmcnt(" #n ")" ::: "memory")
; #define PG8_WAIT_L(n) asm volatile("s_waitcnt lgkmcnt(" #n ")" ::: "memory")
; #define PG8_BAR __builtin_amdgcn_s_barrier()
; #define PG8_SCHED __builtin_amdgcn_sched_barrier(0)
; template <class Epi, class Sched, bool ALIGN_EPI = false, bool SP2 = false>
; __device__ __forceinline__ void gemm_phase(PG8_LAS unsigned char* lds, const Gemm g, const Sched& S, const Epi& E, const int wave_id) {
;     ...
;             PG8_WAIT_V(8); PG8_WAIT_L(0); PG8_BAR; PG8_MMA(1, 0, At, B0); PG8_MMA(1, 1, At, B1); PG8_BAR; PG8_SCHED;
;             PG8_LDB(B0, 1, 0); PG8_LDB(B1, 1, 1); PG8_SCHED; PG8_LDA(At, 1, 0); PG8_STAGE(PG8_SA(0, 1), a2 + hstep, voffA);
;             PG8_WAIT_V(8); PG8_WAIT_L(0); PG8_BAR; PG8_MMA(0, 0, At, B0); PG8_MMA(0, 1, At, B1); PG8_BAR; PG8_SCHED;
	s_setprio 1
	s_waitcnt lgkmcnt(0)
	v_mfma_f32_16x16x32_bf16 v[62:65], v[114:117], v[162:165], 0
	v_mfma_f32_16x16x32_bf16 v[58:61], v[130:133], v[162:165], 0
	v_mfma_f32_16x16x32_bf16 v[46:49], v[114:117], v[170:173], 0
	v_mfma_f32_16x16x32_bf16 v[42:45], v[130:133], v[170:173], 0
	v_mfma_f32_16x16x32_bf16 v[30:33], v[114:117], v[178:181], 0
	v_mfma_f32_16x16x32_bf16 v[26:29], v[130:133], v[178:181], 0
	v_mfma_f32_16x16x32_bf16 v[14:17], v[114:117], v[186:189], 0
	v_mfma_f32_16x16x32_bf16 v[10:13], v[130:133], v[186:189], 0
	v_mfma_f32_16x16x32_bf16 v[62:65], v[118:121], v[166:169], v[62:65]
	v_mfma_f32_16x16x32_bf16 v[58:61], v[134:137], v[166:169], v[58:61]
	v_mfma_f32_16x16x32_bf16 v[46:49], v[118:121], v[174:177], v[46:49]
	v_mfma_f32_16x16x32_bf16 v[42:45], v[134:137], v[174:177], v[42:45]
	v_mfma_f32_16x16x32_bf16 v[30:33], v[118:121], v[182:185], v[30:33]
	v_mfma_f32_16x16x32_bf16 v[26:29], v[134:137], v[182:185], v[26:29]
	v_mfma_f32_16x16x32_bf16 v[14:17], v[118:121], v[190:193], v[14:17]
	v_mfma_f32_16x16x32_bf16 v[10:13], v[134:137], v[190:193], v[10:13]
	s_setprio 0
	s_setprio 1
	v_mfma_f32_16x16x32_bf16 v[54:57], v[138:141], v[162:165], 0
	v_mfma_f32_16x16x32_bf16 v[50:53], v[146:149], v[162:165], 0
	v_mfma_f32_16x16x32_bf16 v[38:41], v[138:141], v[170:173], 0
	v_mfma_f32_16x16x32_bf16 v[34:37], v[146:149], v[170:173], 0
	v_mfma_f32_16x16x32_bf16 v[22:25], v[138:141], v[178:181], 0
	v_mfma_f32_16x16x32_bf16 v[18:21], v[146:149], v[178:181], 0
	v_mfma_f32_16x16x32_bf16 v[6:9], v[138:141], v[186:189], 0
	v_mfma_f32_16x16x32_bf16 v[2:5], v[146:149], v[186:189], 0
	v_mfma_f32_16x16x32_bf16 v[54:57], v[142:145], v[166:169], v[54:57]
	v_mfma_f32_16x16x32_bf16 v[50:53], v[150:153], v[166:169], v[50:53]
	v_mfma_f32_16x16x32_bf16 v[38:41], v[142:145], v[174:177], v[38:41]
	v_mfma_f32_16x16x32_bf16 v[34:37], v[150:153], v[174:177], v[34:37]
	v_mfma_f32_16x16x32_bf16 v[22:25], v[142:145], v[182:185], v[22:25]
	v_mfma_f32_16x16x32_bf16 v[18:21], v[150:153], v[182:185], v[18:21]
	v_mfma_f32_16x16x32_bf16 v[6:9], v[142:145], v[190:193], v[6:9]
	v_mfma_f32_16x16x32_bf16 v[2:5], v[150:153], v[190:193], v[2:5]
	s_setprio 0
	s_barrier
	s_add_i32 s85, 0, 0x18000
	s_add_i32 s88, 0, 0x1c000
	s_add_u32 s82, s82, 0x80000
	s_addc_u32 s83, s83, 0
	s_mov_b32 m0, s72
	s_nop 0
	global_load_lds_dwordx4 v206, s[82:83]
	ds_read_b128 v[114:117], v226 offset:32768
	ds_read_b128 v[118:121], v226 offset:33792
	ds_read_b128 v[130:133], v226 offset:34816
	ds_read_b128 v[134:137], v226 offset:35840
	ds_read_b128 v[138:141], v226 offset:49152
	ds_read_b128 v[142:145], v226 offset:50176
	ds_read_b128 v[146:149], v226 offset:51200
	ds_read_b128 v[150:153], v226 offset:52224
	s_mov_b32 m0, s73
	s_nop 0
	global_load_lds_dwordx4 v210, s[82:83]
	ds_read_b128 v[162:165], v244 offset:32768
	ds_read_b128 v[166:169], v244 offset:33792
	ds_read_b128 v[170:173], v244 offset:34816
	ds_read_b128 v[174:177], v244 offset:35840
	ds_read_b128 v[178:181], v244 offset:36864
	ds_read_b128 v[182:185], v244 offset:37888
	ds_read_b128 v[186:189], v244 offset:38912
	ds_read_b128 v[190:193], v244 offset:39936
	s_waitcnt vmcnt(8)
	s_waitcnt lgkmcnt(0)
	s_barrier
	s_setprio 1
	s_waitcnt lgkmcnt(0)
	v_mfma_f32_16x16x32_bf16 v[158:161], v[114:117], v[162:165], v[158:161]
	v_mfma_f32_16x16x32_bf16 v[154:157], v[130:133], v[162:165], v[154:157]
	v_mfma_f32_16x16x32_bf16 v[110:113], v[114:117], v[170:173], v[110:113]
	v_mfma_f32_16x16x32_bf16 v[106:109], v[130:133], v[170:173], v[106:109]
	v_mfma_f32_16x16x32_bf16 v[94:97], v[114:117], v[178:181], v[94:97]
	v_mfma_f32_16x16x32_bf16 v[90:93], v[130:133], v[178:181], v[90:93]
	v_mfma_f32_16x16x32_bf16 v[78:81], v[114:117], v[186:189], v[78:81]
	v_mfma_f32_16x16x32_bf16 v[74:77], v[130:133], v[186:189], v[74:77]
	v_mfma_f32_16x16x32_bf16 v[158:161], v[118:121], v[166:169], v[158:161]
	v_mfma_f32_16x16x32_bf16 v[154:157], v[134:137], v[166:169], v[154:157]
	v_mfma_f32_16x16x32_bf16 v[110:113], v[118:121], v[174:177], v[110:113]
	v_mfma_f32_16x16x32_bf16 v[106:109], v[134:137], v[174:177], v[106:109]
	v_mfma_f32_16x16x32_bf16 v[94:97], v[118:121], v[182:185], v[94:97]
	v_mfma_f32_16x16x32_bf16 v[90:93], v[134:137], v[182:185], v[90:93]
	v_mfma_f32_16x16x32_bf16 v[78:81], v[118:121], v[190:193], v[78:81]
	v_mfma_f32_16x16x32_bf16 v[74:77], v[134:137], v[190:193], v[74:77]
	s_setprio 0
	s_setprio 1
	v_mfma_f32_16x16x32_bf16 v[126:129], v[138:141], v[162:165], v[126:129]
	v_mfma_f32_16x16x32_bf16 v[122:125], v[146:149], v[162:165], v[122:125]
	v_mfma_f32_16x16x32_bf16 v[102:105], v[138:141], v[170:173], v[102:105]
	v_mfma_f32_16x16x32_bf16 v[98:101], v[146:149], v[170:173], v[98:101]
	v_mfma_f32_16x16x32_bf16 v[86:89], v[138:141], v[178:181], v[86:89]
	v_mfma_f32_16x16x32_bf16 v[82:85], v[146:149], v[178:181], v[82:85]
	v_mfma_f32_16x16x32_bf16 v[70:73], v[138:141], v[186:189], v[70:73]
	v_mfma_f32_16x16x32_bf16 v[66:69], v[146:149], v[186:189], v[66:69]
	v_mfma_f32_16x16x32_bf16 v[126:129], v[142:145], v[166:169], v[126:129]
	v_mfma_f32_16x16x32_bf16 v[122:125], v[150:153], v[166:169], v[122:125]
	v_mfma_f32_16x16x32_bf16 v[102:105], v[142:145], v[174:177], v[102:105]
	v_mfma_f32_16x16x32_bf16 v[98:101], v[150:153], v[174:177], v[98:101]
	v_mfma_f32_16x16x32_bf16 v[86:89], v[142:145], v[182:185], v[86:89]
	v_mfma_f32_16x16x32_bf16 v[82:85], v[150:153], v[182:185], v[82:85]
	v_mfma_f32_16x16x32_bf16 v[70:73], v[142:145], v[190:193], v[70:73]
	v_mfma_f32_16x16x32_bf16 v[66:69], v[150:153], v[190:193], v[66:69]
	s_setprio 0
	s_barrier
; #define PG8_STAGE(bufoff, gbase, voff) do { _Pragma("unroll") for (int _i = 0; _i < 2; ++_i) \
;         __builtin_amdgcn_global_load_lds((const unsigned*)((const char*)(gbase) + (voff)[_i]), (PG8_LAS unsigned*)(lds + (bufoff) + ldsw + _i * 8192), 16, 0, 0); } while (0)
; #define PG8_LDA(dst, b, h) do { _Pragma("unroll") for (int m = 0; m < 4; ++m) _Pragma("unroll") for (int k = 0; k < 2; ++k) dst[m][k] = *(const PG8_LAS bf16x8*)(lds + PG8_SA(b, h) + aoff + m * 2048 + k * 1024); } while (0)
; #define PG8_LDB(dst, b, h) do { _Pragma("unroll") for (int n = 0; n < 2; ++n) _Pragma("unroll") for (int k = 0; k < 2; ++k) dst[n][k] = *(const PG8_LAS bf16x8*)(lds + PG8_SB(b, h) + boff + n * 2048 + k * 1024); } while (0)
; #define PG8_MMA(ai, bj, At, Bt) do { __builtin_amdgcn_s_setprio(1); _Pragma("unroll") for (int m = 0; m < 4; ++m) _Pragma("unroll") for (int n = 0; n < 2; ++n) _Pragma("unroll") for (int k = 0; k < 2; ++k) \
;         acc[ai][bj][m][n] = __builtin_amdgcn_mfma_f32_16x16x32_bf16(Bt[n][k], At[m][k], acc[ai][bj][m][n], 0, 0, 0); __builtin_amdgcn_s_setprio(0); } while (0)
; #define PG8_WAIT_V(n) asm volatile("s_waitcnt vmcnt(" #n ")" ::: "memory")
; #define PG8_WAIT_L(n) asm volatile("s_waitcnt lgkmcnt(" #n ")" ::: "memory")
; template <class Epi, class Sched, bool ALIGN_EPI = false, bool SP2 = false>
; __device__ __forceinline__ void gemm_phase(PG8_LAS unsigned char* lds, const Gemm g, const Sched& S, const Epi& E, const int wave_id) {
;     ...
;             const bool last = (t == nt - 2);
;             const char* a1 = cA + (size_t)(t + 1) * kstep;
;             const char* a2 = last ? nA : cA + (size_t)(t + 2) * kstep; const char* b2 = last ? nB : cB + (size_t)(t + 2) * kstep;
;             const char* a3 = a2 + kstep; const char* b3 = b2 + kstep;
;             if (last && has_next) S.a_ready(nxt);
;             if constexpr (SP2) {
;             PG8_LDB(B0, 0, 0); PG8_LDB(B1, 0, 1); PG8_SCHED; PG8_LDA(At, 0, 0); PG8_STAGE(PG8_SA(1, 1), a1 + hstep, voffA);
;             PG8_WAIT_V(8); PG8_WAIT_L(0); PG8_BAR; PG8_MMA(0, 0, At, B0); PG8_MMA(0, 1, At, B1); PG8_BAR; PG8_SCHED;
;     ...
;             PG8_LDA(At, 1, 1); PG8_STAGE(PG8_SB(1, 0), b3, voffB); PG8_STAGE(PG8_SB(1, 1), b3 + hstep, voffB); PG8_STAGE(PG8_SA(1, 0), a3, voffA);
;             PG8_WAIT_V(8); PG8_WAIT_L(0); PG8_BAR; PG8_MMA(1, 0, At, B0); PG8_MMA(1, 1, At, B1); PG8_BAR; PG8_SCHED;
	s_add_u32 vcc_lo, s82, 0xfff80080
	s_addc_u32 vcc_hi, s83, -1
	s_mov_b32 m0, s76
	s_nop 0
	global_load_lds_dwordx4 v206, vcc
	ds_read_b128 v[162:165], v244 offset:49152
	ds_read_b128 v[166:169], v244 offset:50176
	s_mov_b32 m0, s77
	s_add_i32 s82, s85, s69
	global_load_lds_dwordx4 v210, vcc
	ds_read_b128 v[170:173], v244 offset:51200
	ds_read_b128 v[174:177], v244 offset:52224
	s_add_u32 vcc_lo, s52, 0x80
	s_addc_u32 vcc_hi, s53, 0
	s_mov_b32 m0, s82
	s_nop 0
	global_load_lds_dwordx4 v208, vcc
	ds_read_b128 v[178:181], v244 offset:53248
	ds_read_b128 v[182:185], v244 offset:54272
	s_add_i32 m0, s82, 0x2000
	s_add_u32 s52, s52, 0x80080
	s_addc_u32 s53, s53, 0
	global_load_lds_dwordx4 v212, vcc
	ds_read_b128 v[186:189], v244 offset:55296
	ds_read_b128 v[190:193], v244 offset:56320
	s_add_i32 s82, s88, s69
	s_mov_b32 m0, s82
	s_nop 0
	global_load_lds_dwordx4 v208, s[52:53]
	s_add_i32 m0, s82, 0x2000
	s_nop 0
	global_load_lds_dwordx4 v212, s[52:53]
	s_waitcnt vmcnt(8)
	s_waitcnt lgkmcnt(0)
	s_barrier
	s_setprio 1
	s_waitcnt lgkmcnt(0)
	v_mfma_f32_16x16x32_bf16 v[62:65], v[114:117], v[162:165], v[62:65]
	v_mfma_f32_16x16x32_bf16 v[58:61], v[130:133], v[162:165], v[58:61]
	v_mfma_f32_16x16x32_bf16 v[46:49], v[114:117], v[170:173], v[46:49]
	v_mfma_f32_16x16x32_bf16 v[42:45], v[130:133], v[170:173], v[42:45]
	v_mfma_f32_16x16x32_bf16 v[30:33], v[114:117], v[178:181], v[30:33]
	v_mfma_f32_16x16x32_bf16 v[26:29], v[130:133], v[178:181], v[26:29]
	v_mfma_f32_16x16x32_bf16 v[14:17], v[114:117], v[186:189], v[14:17]
	v_mfma_f32_16x16x32_bf16 v[10:13], v[130:133], v[186:189], v[10:13]
	v_mfma_f32_16x16x32_bf16 v[62:65], v[118:121], v[166:169], v[62:65]
	v_mfma_f32_16x16x32_bf16 v[58:61], v[134:137], v[166:169], v[58:61]
	v_mfma_f32_16x16x32_bf16 v[46:49], v[118:121], v[174:177], v[46:49]
	v_mfma_f32_16x16x32_bf16 v[42:45], v[134:137], v[174:177], v[42:45]
	v_mfma_f32_16x16x32_bf16 v[30:33], v[118:121], v[182:185], v[30:33]
	v_mfma_f32_16x16x32_bf16 v[26:29], v[134:137], v[182:185], v[26:29]
	v_mfma_f32_16x16x32_bf16 v[14:17], v[118:121], v[190:193], v[14:17]
	v_mfma_f32_16x16x32_bf16 v[10:13], v[134:137], v[190:193], v[10:13]
	s_setprio 0
	s_setprio 1
	v_mfma_f32_16x16x32_bf16 v[54:57], v[138:141], v[162:165], v[54:57]
	v_mfma_f32_16x16x32_bf16 v[50:53], v[146:149], v[162:165], v[50:53]
	v_mfma_f32_16x16x32_bf16 v[38:41], v[138:141], v[170:173], v[38:41]
	v_mfma_f32_16x16x32_bf16 v[34:37], v[146:149], v[170:173], v[34:37]
	v_mfma_f32_16x16x32_bf16 v[22:25], v[138:141], v[178:181], v[22:25]
	v_mfma_f32_16x16x32_bf16 v[18:21], v[146:149], v[178:181], v[18:21]
	v_mfma_f32_16x16x32_bf16 v[6:9], v[138:141], v[186:189], v[6:9]
	v_mfma_f32_16x16x32_bf16 v[2:5], v[146:149], v[186:189], v[2:5]
	v_mfma_f32_16x16x32_bf16 v[54:57], v[142:145], v[166:169], v[54:57]
	v_mfma_f32_16x16x32_bf16 v[50:53], v[150:153], v[166:169], v[50:53]
	v_mfma_f32_16x16x32_bf16 v[38:41], v[142:145], v[174:177], v[38:41]
	v_mfma_f32_16x16x32_bf16 v[34:37], v[150:153], v[174:177], v[34:37]
	v_mfma_f32_16x16x32_bf16 v[22:25], v[142:145], v[182:185], v[22:25]
	v_mfma_f32_16x16x32_bf16 v[18:21], v[150:153], v[182:185], v[18:21]
	v_mfma_f32_16x16x32_bf16 v[6:9], v[142:145], v[190:193], v[6:9]
	v_mfma_f32_16x16x32_bf16 v[2:5], v[150:153], v[190:193], v[2:5]
	s_setprio 0
	s_barrier
	s_add_i32 s84, s84, 2
	s_add_u32 s46, s46, 0x100
	s_addc_u32 s47, s47, 0
	s_add_u32 s80, s80, 0x100
	s_addc_u32 s81, s81, 0
	s_cmp_gt_u32 s84, 29
	s_cbranch_scc1 .Lpeel_exit_g5
.LBB0_904:
	s_add_u32 s52, s46, 0xfff80080
	s_addc_u32 s53, s47, -1
	s_add_i32 s85, 0, 0x10000
	s_cmp_eq_u32 s84, 28
	s_cselect_b32 s83, s21, s53
	s_cselect_b32 s82, s49, s52
	s_cselect_b32 s53, s19, s81
	s_cselect_b32 s52, s79, s80
	s_add_i32 s92, 0, 0x14000
	s_add_i32 m0, s70, 0xc000
	s_nop 0
	global_load_lds_dwordx4 v214, s[46:47]
	ds_read_b128 v[114:117], v226
	ds_read_b128 v[118:121], v226 offset:1024
	ds_read_b128 v[130:133], v226 offset:2048
	ds_read_b128 v[134:137], v226 offset:3072
	ds_read_b128 v[138:141], v226 offset:16384
	ds_read_b128 v[142:145], v226 offset:17408
	ds_read_b128 v[146:149], v226 offset:18432
	ds_read_b128 v[150:153], v226 offset:19456
	s_add_i32 m0, s70, 0xe000
	s_nop 0
	global_load_lds_dwordx4 v216, s[46:47]
	ds_read_b128 v[162:165], v244
	ds_read_b128 v[166:169], v244 offset:1024
	ds_read_b128 v[170:173], v244 offset:2048
	ds_read_b128 v[174:177], v244 offset:3072
	ds_read_b128 v[178:181], v244 offset:4096
	ds_read_b128 v[182:185], v244 offset:5120
	ds_read_b128 v[186:189], v244 offset:6144
	ds_read_b128 v[190:193], v244 offset:7168
	s_waitcnt vmcnt(8)
	s_waitcnt lgkmcnt(0)
	s_barrier
; #define PG8_STAGE(bufoff, gbase, voff) do { _Pragma("unroll") for (int _i = 0; _i < 2; ++_i) \
;         __builtin_amdgcn_global_load_lds((const unsigned*)((const char*)(gbase) + (voff)[_i]), (PG8_LAS unsigned*)(lds + (bufoff) + ldsw + _i * 8192), 16, 0, 0); } while (0)
; #define PG8_LDA(dst, b, h) do { _Pragma("unroll") for (int m = 0; m < 4; ++m) _Pragma("unroll") for (int k = 0; k < 2; ++k) dst[m][k] = *(const PG8_LAS bf16x8*)(lds + PG8_SA(b, h) + aoff + m * 2048 + k * 1024); } while (0)
; #define PG8_MMA(ai, bj, At, Bt) do { __builtin_amdgcn_s_setprio(1); _Pragma("unroll") for (int m = 0; m < 4; ++m) _Pragma("unroll") for (int n = 0; n < 2; ++n) _Pragma("unroll") for (int k = 0; k < 2; ++k) \
;         acc[ai][bj][m][n] = __builtin_amdgcn_mfma_f32_16x16x32_bf16(Bt[n][k], At[m][k], acc[ai][bj][m][n], 0, 0, 0); __builtin_amdgcn_s_setprio(0); } while (0)
; #define PG8_WAIT_V(n) asm volatile("s_waitcnt vmcnt(" #n ")" ::: "memory")
; #define PG8_WAIT_L(n) asm volatile("s_waitcnt lgkmcnt(" #n ")" ::: "memory")
; #define PG8_BAR __builtin_amdgcn_s_barrier()
; #define PG8_SCHED __builtin_amdgcn_sched_barrier(0)
; template <class Epi, class Sched, bool ALIGN_EPI = false, bool SP2 = false>
; __device__ __forceinline__ void gemm_phase(PG8_LAS unsigned char* lds, const Gemm g, const Sched& S, const Epi& E, const int wave_id) {
;     ...
;             PG8_WAIT_V(8); PG8_WAIT_L(0); PG8_BAR; PG8_MMA(0, 0, At, B0); PG8_MMA(0, 1, At, B1); PG8_BAR; PG8_SCHED;
;             PG8_LDA(At, 0, 1); PG8_STAGE(PG8_SB(0, 0), b2, voffB); PG8_STAGE(PG8_SB(0, 1), b2 + hstep, voffB); PG8_STAGE(PG8_SA(0, 0), a2, voffA);
;             PG8_WAIT_V(8); PG8_WAIT_L(0); PG8_BAR; PG8_MMA(1, 0, At, B0); PG8_MMA(1, 1, At, B1); PG8_BAR; PG8_SCHED;
	s_setprio 1
	s_waitcnt lgkmcnt(0)
	v_mfma_f32_16x16x32_bf16 v[158:161], v[114:117], v[162:165], v[158:161]
	v_mfma_f32_16x16x32_bf16 v[154:157], v[130:133], v[162:165], v[154:157]
	v_mfma_f32_16x16x32_bf16 v[110:113], v[114:117], v[170:173], v[110:113]
	v_mfma_f32_16x16x32_bf16 v[106:109], v[130:133], v[170:173], v[106:109]
	v_mfma_f32_16x16x32_bf16 v[94:97], v[114:117], v[178:181], v[94:97]
	v_mfma_f32_16x16x32_bf16 v[90:93], v[130:133], v[178:181], v[90:93]
	v_mfma_f32_16x16x32_bf16 v[78:81], v[114:117], v[186:189], v[78:81]
	v_mfma_f32_16x16x32_bf16 v[74:77], v[130:133], v[186:189], v[74:77]
	v_mfma_f32_16x16x32_bf16 v[158:161], v[118:121], v[166:169], v[158:161]
	v_mfma_f32_16x16x32_bf16 v[154:157], v[134:137], v[166:169], v[154:157]
	v_mfma_f32_16x16x32_bf16 v[110:113], v[118:121], v[174:177], v[110:113]
	v_mfma_f32_16x16x32_bf16 v[106:109], v[134:137], v[174:177], v[106:109]
	v_mfma_f32_16x16x32_bf16 v[94:97], v[118:121], v[182:185], v[94:97]
	v_mfma_f32_16x16x32_bf16 v[90:93], v[134:137], v[182:185], v[90:93]
	v_mfma_f32_16x16x32_bf16 v[78:81], v[118:121], v[190:193], v[78:81]
	v_mfma_f32_16x16x32_bf16 v[74:77], v[134:137], v[190:193], v[74:77]
	s_setprio 0
	s_setprio 1
	v_mfma_f32_16x16x32_bf16 v[126:129], v[138:141], v[162:165], v[126:129]
	v_mfma_f32_16x16x32_bf16 v[122:125], v[146:149], v[162:165], v[122:125]
	v_mfma_f32_16x16x32_bf16 v[102:105], v[138:141], v[170:173], v[102:105]
	v_mfma_f32_16x16x32_bf16 v[98:101], v[146:149], v[170:173], v[98:101]
	v_mfma_f32_16x16x32_bf16 v[86:89], v[138:141], v[178:181], v[86:89]
	v_mfma_f32_16x16x32_bf16 v[82:85], v[146:149], v[178:181], v[82:85]
	v_mfma_f32_16x16x32_bf16 v[70:73], v[138:141], v[186:189], v[70:73]
	v_mfma_f32_16x16x32_bf16 v[66:69], v[146:149], v[186:189], v[66:69]
	v_mfma_f32_16x16x32_bf16 v[126:129], v[142:145], v[166:169], v[126:129]
	v_mfma_f32_16x16x32_bf16 v[122:125], v[150:153], v[166:169], v[122:125]
	v_mfma_f32_16x16x32_bf16 v[102:105], v[142:145], v[174:177], v[102:105]
	v_mfma_f32_16x16x32_bf16 v[98:101], v[150:153], v[174:177], v[98:101]
	v_mfma_f32_16x16x32_bf16 v[86:89], v[142:145], v[182:185], v[86:89]
	v_mfma_f32_16x16x32_bf16 v[82:85], v[150:153], v[182:185], v[82:85]
	v_mfma_f32_16x16x32_bf16 v[70:73], v[142:145], v[190:193], v[70:73]
	v_mfma_f32_16x16x32_bf16 v[66:69], v[150:153], v[190:193], v[66:69]
	s_setprio 0
	s_barrier
	s_add_i32 s85, s85, s69
	s_mov_b32 m0, s85
	s_nop 0
	global_load_lds_dwordx4 v208, s[52:53]
	ds_read_b128 v[162:165], v244 offset:16384
	ds_read_b128 v[166:169], v244 offset:17408
	s_add_i32 m0, s85, 0x2000
	s_add_u32 s88, s52, 0x80000
	s_addc_u32 s89, s53, 0
	s_add_i32 s85, s92, s69
	global_load_lds_dwordx4 v212, s[52:53]
	ds_read_b128 v[170:173], v244 offset:18432
	ds_read_b128 v[174:177], v244 offset:19456
	s_mov_b32 m0, s85
	s_nop 0
	global_load_lds_dwordx4 v208, s[88:89]
	ds_read_b128 v[178:181], v244 offset:20480
	ds_read_b128 v[182:185], v244 offset:21504
	s_add_i32 m0, s85, 0x2000
	s_nop 0
	global_load_lds_dwordx4 v212, s[88:89]
	ds_read_b128 v[186:189], v244 offset:22528
	ds_read_b128 v[190:193], v244 offset:23552
	s_mov_b32 m0, s70
	s_nop 0
	global_load_lds_dwordx4 v206, s[82:83]
	s_mov_b32 m0, s71
	s_nop 0
	global_load_lds_dwordx4 v210, s[82:83]
	s_waitcnt vmcnt(8)
	s_waitcnt lgkmcnt(0)
	s_nop 0
	s_barrier
	s_setprio 1
	s_waitcnt lgkmcnt(0)
	v_mfma_f32_16x16x32_bf16 v[62:65], v[114:117], v[162:165], v[62:65]
	v_mfma_f32_16x16x32_bf16 v[58:61], v[130:133], v[162:165], v[58:61]
	v_mfma_f32_16x16x32_bf16 v[46:49], v[114:117], v[170:173], v[46:49]
	v_mfma_f32_16x16x32_bf16 v[42:45], v[130:133], v[170:173], v[42:45]
	v_mfma_f32_16x16x32_bf16 v[30:33], v[114:117], v[178:181], v[30:33]
	v_mfma_f32_16x16x32_bf16 v[26:29], v[130:133], v[178:181], v[26:29]
	v_mfma_f32_16x16x32_bf16 v[14:17], v[114:117], v[186:189], v[14:17]
	v_mfma_f32_16x16x32_bf16 v[10:13], v[130:133], v[186:189], v[10:13]
	v_mfma_f32_16x16x32_bf16 v[62:65], v[118:121], v[166:169], v[62:65]
	v_mfma_f32_16x16x32_bf16 v[58:61], v[134:137], v[166:169], v[58:61]
	v_mfma_f32_16x16x32_bf16 v[46:49], v[118:121], v[174:177], v[46:49]
	v_mfma_f32_16x16x32_bf16 v[42:45], v[134:137], v[174:177], v[42:45]
	v_mfma_f32_16x16x32_bf16 v[30:33], v[118:121], v[182:185], v[30:33]
	v_mfma_f32_16x16x32_bf16 v[26:29], v[134:137], v[182:185], v[26:29]
	v_mfma_f32_16x16x32_bf16 v[14:17], v[118:121], v[190:193], v[14:17]
	v_mfma_f32_16x16x32_bf16 v[10:13], v[134:137], v[190:193], v[10:13]
	s_setprio 0
	s_setprio 1
	v_mfma_f32_16x16x32_bf16 v[54:57], v[138:141], v[162:165], v[54:57]
	v_mfma_f32_16x16x32_bf16 v[50:53], v[146:149], v[162:165], v[50:53]
	v_mfma_f32_16x16x32_bf16 v[38:41], v[138:141], v[170:173], v[38:41]
	v_mfma_f32_16x16x32_bf16 v[34:37], v[146:149], v[170:173], v[34:37]
	v_mfma_f32_16x16x32_bf16 v[22:25], v[138:141], v[178:181], v[22:25]
	v_mfma_f32_16x16x32_bf16 v[18:21], v[146:149], v[178:181], v[18:21]
	v_mfma_f32_16x16x32_bf16 v[6:9], v[138:141], v[186:189], v[6:9]
	v_mfma_f32_16x16x32_bf16 v[2:5], v[146:149], v[186:189], v[2:5]
	v_mfma_f32_16x16x32_bf16 v[54:57], v[142:145], v[166:169], v[54:57]
	v_mfma_f32_16x16x32_bf16 v[50:53], v[150:153], v[166:169], v[50:53]
	v_mfma_f32_16x16x32_bf16 v[38:41], v[142:145], v[174:177], v[38:41]
	v_mfma_f32_16x16x32_bf16 v[34:37], v[150:153], v[174:177], v[34:37]
	v_mfma_f32_16x16x32_bf16 v[22:25], v[142:145], v[182:185], v[22:25]
	v_mfma_f32_16x16x32_bf16 v[18:21], v[150:153], v[182:185], v[18:21]
	v_mfma_f32_16x16x32_bf16 v[6:9], v[142:145], v[190:193], v[6:9]
	v_mfma_f32_16x16x32_bf16 v[2:5], v[150:153], v[190:193], v[2:5]
	s_setprio 0
	s_barrier
; #define PG8_STAGE(bufoff, gbase, voff) do { _Pragma("unroll") for (int _i = 0; _i < 2; ++_i) \
;         __builtin_amdgcn_global_load_lds((const unsigned*)((const char*)(gbase) + (voff)[_i]), (PG8_LAS unsigned*)(lds + (bufoff) + ldsw + _i * 8192), 16, 0, 0); } while (0)
; #define PG8_LDA(dst, b, h) do { _Pragma("unroll") for (int m = 0; m < 4; ++m) _Pragma("unroll") for (int k = 0; k < 2; ++k) dst[m][k] = *(const PG8_LAS bf16x8*)(lds + PG8_SA(b, h) + aoff + m * 2048 + k * 1024); } while (0)
; #define PG8_LDB(dst, b, h) do { _Pragma("unroll") for (int n = 0; n < 2; ++n) _Pragma("unroll") for (int k = 0; k < 2; ++k) dst[n][k] = *(const PG8_LAS bf16x8*)(lds + PG8_SB(b, h) + boff + n * 2048 + k * 1024); } while (0)
; #define PG8_MMA(ai, bj, At, Bt) do { __builtin_amdgcn_s_setprio(1); _Pragma("unroll") for (int m = 0; m < 4; ++m) _Pragma("unroll") for (int n = 0; n < 2; ++n) _Pragma("unroll") for (int k = 0; k < 2; ++k) \
;         acc[ai][bj][m][n] = __builtin_amdgcn_mfma_f32_16x16x32_bf16(Bt[n][k], At[m][k], acc[ai][bj][m][n], 0, 0, 0); __builtin_amdgcn_s_setprio(0); } while (0)
; #define PG8_WAIT_V(n) asm volatile("s_waitcnt vmcnt(" #n ")" ::: "memory")
; #define PG8_WAIT_L(n) asm volatile("s_waitcnt lgkmcnt(" #n ")" ::: "memory")
; #define PG8_BAR __builtin_amdgcn_s_barrier()
; #define PG8_SCHED __builtin_amdgcn_sched_barrier(0)
; template <class Epi, class Sched, bool ALIGN_EPI = false, bool SP2 = false>
; __device__ __forceinline__ void gemm_phase(PG8_LAS unsigned char* lds, const Gemm g, const Sched& S, const Epi& E, const int wave_id) {
;     ...
;             PG8_LDB(B0, 1, 0); PG8_LDB(B1, 1, 1); PG8_SCHED; PG8_LDA(At, 1, 0); PG8_STAGE(PG8_SA(0, 1), a2 + hstep, voffA);
;             PG8_WAIT_V(8); PG8_WAIT_L(0); PG8_BAR; PG8_MMA(0, 0, At, B0); PG8_MMA(0, 1, At, B1); PG8_BAR; PG8_SCHED;
;             PG8_LDA(At, 1, 1); PG8_STAGE(PG8_SB(1, 0), b3, voffB); PG8_STAGE(PG8_SB(1, 1), b3 + hstep, voffB); PG8_STAGE(PG8_SA(1, 0), a3, voffA);
;             PG8_WAIT_V(8); PG8_WAIT_L(0); PG8_BAR; PG8_MMA(1, 0, At, B0); PG8_MMA(1, 1, At, B1); PG8_BAR; PG8_SCHED;
	s_add_i32 s85, 0, 0x18000
	s_add_i32 s88, 0, 0x1c000
	s_add_u32 s82, s82, 0x80000
	s_addc_u32 s83, s83, 0
	s_mov_b32 m0, s72
	s_nop 0
	global_load_lds_dwordx4 v206, s[82:83]
	ds_read_b128 v[114:117], v226 offset:32768
	ds_read_b128 v[118:121], v226 offset:33792
	ds_read_b128 v[130:133], v226 offset:34816
	ds_read_b128 v[134:137], v226 offset:35840
	ds_read_b128 v[138:141], v226 offset:49152
	ds_read_b128 v[142:145], v226 offset:50176
	ds_read_b128 v[146:149], v226 offset:51200
	ds_read_b128 v[150:153], v226 offset:52224
	s_mov_b32 m0, s73
	s_nop 0
	global_load_lds_dwordx4 v210, s[82:83]
	ds_read_b128 v[162:165], v244 offset:32768
	ds_read_b128 v[166:169], v244 offset:33792
	ds_read_b128 v[170:173], v244 offset:34816
	ds_read_b128 v[174:177], v244 offset:35840
	ds_read_b128 v[178:181], v244 offset:36864
	ds_read_b128 v[182:185], v244 offset:37888
	ds_read_b128 v[186:189], v244 offset:38912
	ds_read_b128 v[190:193], v244 offset:39936
	s_waitcnt vmcnt(8)
	s_waitcnt lgkmcnt(0)
	s_barrier
	s_setprio 1
	s_waitcnt lgkmcnt(0)
	v_mfma_f32_16x16x32_bf16 v[158:161], v[114:117], v[162:165], v[158:161]
	v_mfma_f32_16x16x32_bf16 v[154:157], v[130:133], v[162:165], v[154:157]
	v_mfma_f32_16x16x32_bf16 v[110:113], v[114:117], v[170:173], v[110:113]
	v_mfma_f32_16x16x32_bf16 v[106:109], v[130:133], v[170:173], v[106:109]
	v_mfma_f32_16x16x32_bf16 v[94:97], v[114:117], v[178:181], v[94:97]
	v_mfma_f32_16x16x32_bf16 v[90:93], v[130:133], v[178:181], v[90:93]
	v_mfma_f32_16x16x32_bf16 v[78:81], v[114:117], v[186:189], v[78:81]
	v_mfma_f32_16x16x32_bf16 v[74:77], v[130:133], v[186:189], v[74:77]
	v_mfma_f32_16x16x32_bf16 v[158:161], v[118:121], v[166:169], v[158:161]
	v_mfma_f32_16x16x32_bf16 v[154:157], v[134:137], v[166:169], v[154:157]
	v_mfma_f32_16x16x32_bf16 v[110:113], v[118:121], v[174:177], v[110:113]
	v_mfma_f32_16x16x32_bf16 v[106:109], v[134:137], v[174:177], v[106:109]
	v_mfma_f32_16x16x32_bf16 v[94:97], v[118:121], v[182:185], v[94:97]
	v_mfma_f32_16x16x32_bf16 v[90:93], v[134:137], v[182:185], v[90:93]
	v_mfma_f32_16x16x32_bf16 v[78:81], v[118:121], v[190:193], v[78:81]
	v_mfma_f32_16x16x32_bf16 v[74:77], v[134:137], v[190:193], v[74:77]
	s_setprio 0
	s_setprio 1
	v_mfma_f32_16x16x32_bf16 v[126:129], v[138:141], v[162:165], v[126:129]
	v_mfma_f32_16x16x32_bf16 v[122:125], v[146:149], v[162:165], v[122:125]
	v_mfma_f32_16x16x32_bf16 v[102:105], v[138:141], v[170:173], v[102:105]
	v_mfma_f32_16x16x32_bf16 v[98:101], v[146:149], v[170:173], v[98:101]
	v_mfma_f32_16x16x32_bf16 v[86:89], v[138:141], v[178:181], v[86:89]
	v_mfma_f32_16x16x32_bf16 v[82:85], v[146:149], v[178:181], v[82:85]
	v_mfma_f32_16x16x32_bf16 v[70:73], v[138:141], v[186:189], v[70:73]
	v_mfma_f32_16x16x32_bf16 v[66:69], v[146:149], v[186:189], v[66:69]
	v_mfma_f32_16x16x32_bf16 v[126:129], v[142:145], v[166:169], v[126:129]
	v_mfma_f32_16x16x32_bf16 v[122:125], v[150:153], v[166:169], v[122:125]
	v_mfma_f32_16x16x32_bf16 v[102:105], v[142:145], v[174:177], v[102:105]
	v_mfma_f32_16x16x32_bf16 v[98:101], v[150:153], v[174:177], v[98:101]
	v_mfma_f32_16x16x32_bf16 v[86:89], v[142:145], v[182:185], v[86:89]
	v_mfma_f32_16x16x32_bf16 v[82:85], v[150:153], v[182:185], v[82:85]
	v_mfma_f32_16x16x32_bf16 v[70:73], v[142:145], v[190:193], v[70:73]
	v_mfma_f32_16x16x32_bf16 v[66:69], v[150:153], v[190:193], v[66:69]
	s_setprio 0
	s_barrier
	s_add_u32 vcc_lo, s82, 0xfff80080
	s_addc_u32 vcc_hi, s83, -1
	s_mov_b32 m0, s76
	s_nop 0
	global_load_lds_dwordx4 v206, vcc
	ds_read_b128 v[162:165], v244 offset:49152
	ds_read_b128 v[166:169], v244 offset:50176
	s_mov_b32 m0, s77
	s_add_i32 s82, s85, s69
	global_load_lds_dwordx4 v210, vcc
	ds_read_b128 v[170:173], v244 offset:51200
	ds_read_b128 v[174:177], v244 offset:52224
	s_add_u32 vcc_lo, s52, 0x80
	s_addc_u32 vcc_hi, s53, 0
	s_mov_b32 m0, s82
	s_nop 0
	global_load_lds_dwordx4 v208, vcc
	ds_read_b128 v[178:181], v244 offset:53248
	ds_read_b128 v[182:185], v244 offset:54272
	s_add_i32 m0, s82, 0x2000
	s_add_u32 s52, s52, 0x80080
	s_addc_u32 s53, s53, 0
	global_load_lds_dwordx4 v212, vcc
	ds_read_b128 v[186:189], v244 offset:55296
	ds_read_b128 v[190:193], v244 offset:56320
	s_add_i32 s82, s88, s69
	s_mov_b32 m0, s82
	s_nop 0
	global_load_lds_dwordx4 v208, s[52:53]
	s_add_i32 m0, s82, 0x2000
	s_nop 0
	global_load_lds_dwordx4 v212, s[52:53]
	s_waitcnt vmcnt(8)
	s_waitcnt lgkmcnt(0)
	s_barrier
	s_setprio 1
	s_waitcnt lgkmcnt(0)
	v_mfma_f32_16x16x32_bf16 v[62:65], v[114:117], v[162:165], v[62:65]
	v_mfma_f32_16x16x32_bf16 v[58:61], v[130:133], v[162:165], v[58:61]
	v_mfma_f32_16x16x32_bf16 v[46:49], v[114:117], v[170:173], v[46:49]
	v_mfma_f32_16x16x32_bf16 v[42:45], v[130:133], v[170:173], v[42:45]
	v_mfma_f32_16x16x32_bf16 v[30:33], v[114:117], v[178:181], v[30:33]
	v_mfma_f32_16x16x32_bf16 v[26:29], v[130:133], v[178:181], v[26:29]
	v_mfma_f32_16x16x32_bf16 v[14:17], v[114:117], v[186:189], v[14:17]
	v_mfma_f32_16x16x32_bf16 v[10:13], v[130:133], v[186:189], v[10:13]
	v_mfma_f32_16x16x32_bf16 v[62:65], v[118:121], v[166:169], v[62:65]
	v_mfma_f32_16x16x32_bf16 v[58:61], v[134:137], v[166:169], v[58:61]
	v_mfma_f32_16x16x32_bf16 v[46:49], v[118:121], v[174:177], v[46:49]
	v_mfma_f32_16x16x32_bf16 v[42:45], v[134:137], v[174:177], v[42:45]
	v_mfma_f32_16x16x32_bf16 v[30:33], v[118:121], v[182:185], v[30:33]
	v_mfma_f32_16x16x32_bf16 v[26:29], v[134:137], v[182:185], v[26:29]
	v_mfma_f32_16x16x32_bf16 v[14:17], v[118:121], v[190:193], v[14:17]
	v_mfma_f32_16x16x32_bf16 v[10:13], v[134:137], v[190:193], v[10:13]
	s_setprio 0
	s_setprio 1
	v_mfma_f32_16x16x32_bf16 v[54:57], v[138:141], v[162:165], v[54:57]
	v_mfma_f32_16x16x32_bf16 v[50:53], v[146:149], v[162:165], v[50:53]
	v_mfma_f32_16x16x32_bf16 v[38:41], v[138:141], v[170:173], v[38:41]
	v_mfma_f32_16x16x32_bf16 v[34:37], v[146:149], v[170:173], v[34:37]
	v_mfma_f32_16x16x32_bf16 v[22:25], v[138:141], v[178:181], v[22:25]
	v_mfma_f32_16x16x32_bf16 v[18:21], v[146:149], v[178:181], v[18:21]
	v_mfma_f32_16x16x32_bf16 v[6:9], v[138:141], v[186:189], v[6:9]
	v_mfma_f32_16x16x32_bf16 v[2:5], v[146:149], v[186:189], v[2:5]
	v_mfma_f32_16x16x32_bf16 v[54:57], v[142:145], v[166:169], v[54:57]
	v_mfma_f32_16x16x32_bf16 v[50:53], v[150:153], v[166:169], v[50:53]
	v_mfma_f32_16x16x32_bf16 v[38:41], v[142:145], v[174:177], v[38:41]
	v_mfma_f32_16x16x32_bf16 v[34:37], v[150:153], v[174:177], v[34:37]
	v_mfma_f32_16x16x32_bf16 v[22:25], v[142:145], v[182:185], v[22:25]
	v_mfma_f32_16x16x32_bf16 v[18:21], v[150:153], v[182:185], v[18:21]
	v_mfma_f32_16x16x32_bf16 v[6:9], v[142:145], v[190:193], v[6:9]
	v_mfma_f32_16x16x32_bf16 v[2:5], v[150:153], v[190:193], v[2:5]
	s_setprio 0
	s_barrier
	s_add_i32 s84, s84, 2
	s_add_u32 s46, s46, 0x100
	s_addc_u32 s47, s47, 0
	s_add_u32 s80, s80, 0x100
	s_addc_u32 s81, s81, 0
	s_cmp_gt_u32 s84, 29
	s_cbranch_scc0 .LBB0_904
